# nt loads in P2 (XRLA read once) and nt stores for P0's transposed weights (on top of P0 nt loads)
# speedup vs baseline: 1.0247x; 1.0086x over previous
.LBB0_21:
	s_cmpk_gt_i32 s38, 0x1ff
	s_mov_b64 s[4:5], -1
	s_cbranch_scc0 .LBB0_123
	s_cmpk_gt_u32 s38, 0x57f
	s_cbranch_scc0 .LBB0_96
	s_cmpk_gt_u32 s38, 0x5df
	s_cbranch_scc0 .LBB0_89
	s_cmpk_gt_u32 s38, 0x6df
	s_cbranch_scc0 .LBB0_62
	s_cmpk_gt_u32 s38, 0x8df
	s_cbranch_scc0 .LBB0_59
	s_cmpk_gt_u32 s38, 0xcdf
	s_cbranch_scc0 .LBB0_56
	s_cmpk_gt_u32 s38, 0x22df
	s_cbranch_scc0 .LBB0_29
	s_add_i32 s4, s38, 0xffffdd20
	s_add_i32 s5, s38, 0xffffd7a0
	s_cmpk_lt_u32 s4, 0x580
	v_mov_b32_e32 v7, s0
	v_mov_b32_e32 v8, s1
	s_cselect_b32 s20, s4, s5
	s_cmpk_gt_u32 s4, 0x57f
	v_mov_b32_e32 v4, s0
	v_readfirstlane_b32 s4, v7
	v_readfirstlane_b32 s5, v8
	s_load_dwordx2 s[4:5], s[4:5], 0xb0
	v_mov_b32_e32 v6, s1
	s_cselect_b32 s8, 0xb00000, 0
	v_readfirstlane_b32 s18, v4
	v_readfirstlane_b32 s19, v6
	s_load_dwordx2 s[18:19], s[18:19], 0xc0
	s_cselect_b32 s21, 0x580000, 0
	s_waitcnt lgkmcnt(0)
	s_add_u32 s22, s4, s8
	s_addc_u32 s23, s5, 0
	s_lshl_b32 s4, s20, 1
	s_and_b32 s8, s4, 0xfc0
	s_lshl_b32 s4, s20, 5
	s_and_b32 s4, s4, 0x3e0
	s_add_u32 s18, s18, s21
	s_addc_u32 s5, s19, 0
	s_lshl_b32 s19, s4, 2
	s_add_u32 s20, s22, s19
	v_or_b32_e32 v8, s8, v3
	s_addc_u32 s21, s23, 0
	v_lshlrev_b32_e32 v4, 2, v0
	v_lshl_add_u64 v[6:7], s[20:21], 0, v[4:5]
	v_lshlrev_b32_e32 v4, 12, v8
	v_lshl_add_u64 v[6:7], v[6:7], 0, v[4:5]
	v_add_co_u32_e32 v8, vcc, s35, v6
	s_lshl_b32 s8, s8, 1
	s_nop 0
	v_addc_co_u32_e32 v9, vcc, 0, v7, vcc
	v_add_co_u32_e32 v10, vcc, s36, v6
	s_add_u32 s18, s18, s8
	s_nop 0
	v_addc_co_u32_e32 v11, vcc, 0, v7, vcc
	v_add_co_u32_e32 v12, vcc, s37, v6
	s_addc_u32 s19, s5, 0
	s_nop 0
	v_addc_co_u32_e32 v13, vcc, 0, v7, vcc
	v_add_co_u32_e32 v14, vcc, s74, v6
	s_nop 1
	v_addc_co_u32_e32 v15, vcc, 0, v7, vcc
	v_add_co_u32_e32 v16, vcc, s39, v6
	s_nop 1
	v_addc_co_u32_e32 v17, vcc, 0, v7, vcc
	v_add_co_u32_e32 v18, vcc, s40, v6
	s_nop 1
	v_addc_co_u32_e32 v19, vcc, 0, v7, vcc
	v_add_co_u32_e32 v20, vcc, s41, v6
	s_nop 1
	v_addc_co_u32_e32 v21, vcc, 0, v7, vcc
	global_load_dword v4, v[6:7], off nt
	global_load_dword v24, v[8:9], off nt
	global_load_dword v25, v[10:11], off nt
	global_load_dword v81, v[12:13], off nt
	global_load_dword v82, v[14:15], off nt
	global_load_dword v83, v[16:17], off nt
	global_load_dword v84, v[18:19], off nt
	global_load_dword v85, v[20:21], off nt
	v_add_co_u32_e32 v8, vcc, s42, v6
	s_nop 1
	v_addc_co_u32_e32 v9, vcc, 0, v7, vcc
	v_add_co_u32_e32 v10, vcc, s43, v6
	s_nop 1
	v_addc_co_u32_e32 v11, vcc, 0, v7, vcc
	v_add_co_u32_e32 v12, vcc, s44, v6
	s_nop 1
	v_addc_co_u32_e32 v13, vcc, 0, v7, vcc
	v_add_co_u32_e32 v14, vcc, s45, v6
	s_nop 1
	v_addc_co_u32_e32 v15, vcc, 0, v7, vcc
	v_add_co_u32_e32 v16, vcc, s46, v6
	s_nop 1
	v_addc_co_u32_e32 v17, vcc, 0, v7, vcc
	v_add_co_u32_e32 v18, vcc, s47, v6
	s_nop 1
	v_addc_co_u32_e32 v19, vcc, 0, v7, vcc
	v_add_co_u32_e32 v20, vcc, s48, v6
	s_nop 1
	v_addc_co_u32_e32 v21, vcc, 0, v7, vcc
	v_add_co_u32_e32 v22, vcc, s49, v6
	s_nop 1
	v_addc_co_u32_e32 v23, vcc, 0, v7, vcc
	global_load_dword v87, v[8:9], off nt
	global_load_dword v88, v[10:11], off nt
	global_load_dword v89, v[12:13], off nt
	global_load_dword v90, v[14:15], off nt
	global_load_dword v91, v[16:17], off nt
	global_load_dword v92, v[18:19], off nt
	global_load_dword v93, v[20:21], off nt
	global_load_dword v94, v[22:23], off nt
	v_add_co_u32_e32 v8, vcc, s50, v6
	s_nop 1
	v_addc_co_u32_e32 v9, vcc, 0, v7, vcc
	v_add_co_u32_e32 v10, vcc, s51, v6
	s_nop 1
	v_addc_co_u32_e32 v11, vcc, 0, v7, vcc
	v_add_co_u32_e32 v12, vcc, s52, v6
	s_nop 1
	v_addc_co_u32_e32 v13, vcc, 0, v7, vcc
	v_add_co_u32_e32 v14, vcc, s53, v6
	s_nop 1
	v_addc_co_u32_e32 v15, vcc, 0, v7, vcc
	v_add_co_u32_e32 v16, vcc, s54, v6
	s_nop 1
	v_addc_co_u32_e32 v17, vcc, 0, v7, vcc
	v_add_co_u32_e32 v18, vcc, s55, v6
	s_nop 1
	v_addc_co_u32_e32 v19, vcc, 0, v7, vcc
	v_add_co_u32_e32 v20, vcc, s56, v6
	s_nop 1
	v_addc_co_u32_e32 v21, vcc, 0, v7, vcc
	v_add_co_u32_e32 v22, vcc, s57, v6
	s_nop 1
	v_addc_co_u32_e32 v23, vcc, 0, v7, vcc
	global_load_dword v95, v[8:9], off nt
	global_load_dword v96, v[10:11], off nt
	global_load_dword v97, v[12:13], off nt
	global_load_dword v98, v[14:15], off nt
	global_load_dword v99, v[16:17], off nt
	global_load_dword v100, v[18:19], off nt
	global_load_dword v101, v[20:21], off nt
	s_nop 0
	global_load_dword v22, v[22:23], off nt
	v_add_co_u32_e32 v8, vcc, s58, v6
	s_nop 1
	v_addc_co_u32_e32 v9, vcc, 0, v7, vcc
	v_add_co_u32_e32 v10, vcc, s59, v6
	s_nop 1
	v_addc_co_u32_e32 v11, vcc, 0, v7, vcc
	v_add_co_u32_e32 v12, vcc, s60, v6
	s_nop 1
	v_addc_co_u32_e32 v13, vcc, 0, v7, vcc
	v_add_co_u32_e32 v14, vcc, s61, v6
	s_nop 1
	v_addc_co_u32_e32 v15, vcc, 0, v7, vcc
	v_add_co_u32_e32 v16, vcc, s62, v6
	s_nop 1
	v_addc_co_u32_e32 v17, vcc, 0, v7, vcc
	v_add_co_u32_e32 v18, vcc, s63, v6
	s_nop 1
	v_addc_co_u32_e32 v19, vcc, 0, v7, vcc
	v_add_co_u32_e32 v20, vcc, s64, v6
	s_nop 1
	v_addc_co_u32_e32 v21, vcc, 0, v7, vcc
	v_add_co_u32_e32 v6, vcc, s65, v6
	s_nop 1
	v_addc_co_u32_e32 v7, vcc, 0, v7, vcc
	global_load_dword v8, v[8:9], off nt
	s_nop 0
	global_load_dword v9, v[10:11], off nt
	s_nop 0
	global_load_dword v10, v[12:13], off nt
	global_load_dword v11, v[14:15], off nt
	s_nop 0
	global_load_dword v12, v[16:17], off nt
	global_load_dword v13, v[18:19], off nt
	global_load_dword v14, v[20:21], off nt
	s_nop 0
	global_load_dword v6, v[6:7], off nt
	s_waitcnt vmcnt(30)
	ds_write2_b32 v27, v4, v24 offset1:66
	s_waitcnt vmcnt(28)
	ds_write2_b32 v27, v25, v81 offset0:132 offset1:198
	v_add_u32_e32 v4, 0x400, v27
	s_waitcnt vmcnt(26)
	ds_write2_b32 v4, v82, v83 offset0:8 offset1:74
	s_waitcnt vmcnt(24)
	ds_write2_b32 v4, v84, v85 offset0:140 offset1:206
	v_add_u32_e32 v4, 0x800, v27
	s_waitcnt vmcnt(22)
	ds_write2_b32 v4, v87, v88 offset0:16 offset1:82
	s_waitcnt vmcnt(20)
	ds_write2_b32 v4, v89, v90 offset0:148 offset1:214
	v_add_u32_e32 v4, 0xc00, v27
	s_waitcnt vmcnt(18)
	ds_write2_b32 v4, v91, v92 offset0:24 offset1:90
	s_waitcnt vmcnt(16)
	ds_write2_b32 v4, v93, v94 offset0:156 offset1:222
	v_add_u32_e32 v4, 0x1000, v27
	s_waitcnt vmcnt(14)
	ds_write2_b32 v4, v95, v96 offset0:32 offset1:98
	s_waitcnt vmcnt(12)
	ds_write2_b32 v4, v97, v98 offset0:164 offset1:230
	v_add_u32_e32 v4, 0x1400, v27
	s_waitcnt vmcnt(10)
	ds_write2_b32 v4, v99, v100 offset0:40 offset1:106
	s_waitcnt vmcnt(8)
	ds_write2_b32 v4, v101, v22 offset0:172 offset1:238
	v_add_u32_e32 v4, 0x1800, v27
	s_waitcnt vmcnt(6)
	ds_write2_b32 v4, v8, v9 offset0:48 offset1:114
	s_waitcnt vmcnt(4)
	ds_write2_b32 v4, v10, v11 offset0:180 offset1:246
	v_add_u32_e32 v4, 0x1c00, v27
	s_waitcnt vmcnt(2)
	ds_write2_b32 v4, v12, v13 offset0:56 offset1:122
	s_waitcnt vmcnt(0)
	ds_write2_b32 v4, v14, v6 offset0:188 offset1:254
	s_waitcnt lgkmcnt(0)
	v_lshlrev_b32_e32 v4, 1, v2
	ds_read2_b32 v[6:7], v29 offset1:33
	v_lshl_add_u64 v[12:13], s[18:19], 0, v[4:5]
	v_or_b32_e32 v4, s4, v28
	s_waitcnt lgkmcnt(0)
	v_cvt_pk_bf16_f32 v6, v6, v7
	ds_read2_b32 v[8:9], v29 offset0:66 offset1:99
	s_mov_b64 s[18:19], 0x23e0000
	v_mul_u32_u24_e32 v4, 0xb00, v4
	s_waitcnt lgkmcnt(0)
	v_cvt_pk_bf16_f32 v7, v8, v9
	ds_read2_b32 v[8:9], v29 offset0:132 offset1:165
	v_lshl_add_u64 v[12:13], v[12:13], 0, s[18:19]
	v_lshlrev_b32_e32 v4, 1, v4
	s_waitcnt lgkmcnt(0)
	v_cvt_pk_bf16_f32 v8, v8, v9
	ds_read2_b32 v[10:11], v29 offset0:198 offset1:231
	s_waitcnt lgkmcnt(0)
	v_cvt_pk_bf16_f32 v9, v10, v11
	v_lshl_add_u64 v[14:15], v[12:13], 0, v[4:5]
	v_or_b32_e32 v4, s4, v30
	ds_read2_b32 v[10:11], v29 offset0:8 offset1:41
	global_store_dwordx4 v[14:15], v[6:9], off nt
	v_mul_u32_u24_e32 v4, 0xb00, v4
	v_lshlrev_b32_e32 v4, 1, v4
	s_waitcnt lgkmcnt(0)
	v_cvt_pk_bf16_f32 v6, v10, v11
	ds_read2_b32 v[8:9], v29 offset0:74 offset1:107
	s_waitcnt lgkmcnt(0)
	v_cvt_pk_bf16_f32 v7, v8, v9
	ds_read2_b32 v[8:9], v29 offset0:140 offset1:173
	s_waitcnt lgkmcnt(0)
	v_cvt_pk_bf16_f32 v8, v8, v9
	ds_read2_b32 v[10:11], v29 offset0:206 offset1:239
	s_waitcnt lgkmcnt(0)
	v_cvt_pk_bf16_f32 v9, v10, v11
	v_lshl_add_u64 v[14:15], v[12:13], 0, v[4:5]
	v_or_b32_e32 v4, s4, v31
	ds_read2_b32 v[10:11], v29 offset0:16 offset1:49
	global_store_dwordx4 v[14:15], v[6:9], off nt
	v_mul_u32_u24_e32 v4, 0xb00, v4
	v_lshlrev_b32_e32 v4, 1, v4
	s_waitcnt lgkmcnt(0)
	v_cvt_pk_bf16_f32 v6, v10, v11
	ds_read2_b32 v[8:9], v29 offset0:82 offset1:115
	s_waitcnt lgkmcnt(0)
	v_cvt_pk_bf16_f32 v7, v8, v9
	ds_read2_b32 v[8:9], v29 offset0:148 offset1:181
	s_waitcnt lgkmcnt(0)
	v_cvt_pk_bf16_f32 v8, v8, v9
	ds_read2_b32 v[10:11], v29 offset0:214 offset1:247
	s_waitcnt lgkmcnt(0)
	v_cvt_pk_bf16_f32 v9, v10, v11
	v_lshl_add_u64 v[14:15], v[12:13], 0, v[4:5]
	ds_read2_b32 v[10:11], v29 offset0:24 offset1:57
	global_store_dwordx4 v[14:15], v[6:9], off nt
	v_or_b32_e32 v4, s4, v32
	v_mul_u32_u24_e32 v4, 0xb00, v4
	s_waitcnt lgkmcnt(0)
	v_cvt_pk_bf16_f32 v6, v10, v11
	ds_read2_b32 v[8:9], v29 offset0:90 offset1:123
	s_waitcnt lgkmcnt(0)
	v_cvt_pk_bf16_f32 v7, v8, v9
	ds_read2_b32 v[8:9], v29 offset0:156 offset1:189
	s_waitcnt lgkmcnt(0)
	v_cvt_pk_bf16_f32 v8, v8, v9
	ds_read2_b32 v[10:11], v29 offset0:222 offset1:255
	v_lshlrev_b32_e32 v4, 1, v4
	s_waitcnt lgkmcnt(0)
	v_cvt_pk_bf16_f32 v9, v10, v11
	v_lshl_add_u64 v[10:11], v[12:13], 0, v[4:5]
	global_store_dwordx4 v[10:11], v[6:9], off nt
	s_waitcnt lgkmcnt(0)
	s_mov_b64 s[4:5], 0

.LBB0_54:
	s_cmpk_gt_u32 s73, 0x57
	s_cselect_b32 s4, 0xf500, 0
	s_cselect_b32 s20, 0x80, 0
	s_add_i32 s8, s4, s8
	s_and_b64 s[4:5], s[18:19], exec
	s_cselect_b32 s4, 0xb00000, 0
	s_sext_i32_i16 s5, s8
	s_waitcnt lgkmcnt(0)
	s_add_u32 s4, s22, s4
	s_addc_u32 s18, s23, 0
	s_bfe_u32 s5, s5, 0x70018
	s_add_i32 s5, s8, s5
	s_waitcnt vmcnt(4)
	ds_write2_b32 v10, v8, v9 offset0:140 offset1:206
	s_sext_i32_i16 s19, s5
	s_and_b32 s5, s5, 0xff80
	s_waitcnt lgkmcnt(0)
	s_sub_i32 s5, s8, s5
	s_waitcnt vmcnt(0)
	ds_read2_b32 v[6:7], v29 offset1:33
	s_lshl_b32 s19, s19, 1
	s_sext_i32_i16 s5, s5
	s_waitcnt lgkmcnt(0)
	v_cvt_pk_bf16_f32 v6, v6, v7
	ds_read2_b32 v[8:9], v29 offset0:66 offset1:99
	s_and_b32 s19, s19, 0xffffff00
	s_add_i32 s5, s20, s5
	s_waitcnt lgkmcnt(0)
	v_cvt_pk_bf16_f32 v7, v8, v9
	ds_read2_b32 v[8:9], v29 offset0:132 offset1:165
	s_add_i32 s8, s5, s19
	s_lshl_b32 s5, s72, 1
	s_add_u32 s4, s4, s5
	s_waitcnt lgkmcnt(0)
	v_cvt_pk_bf16_f32 v8, v8, v9
	ds_read2_b32 v[10:11], v29 offset0:198 offset1:231
	s_addc_u32 s5, s18, 0
	v_lshlrev_b32_e32 v4, 1, v2
	s_waitcnt lgkmcnt(0)
	v_cvt_pk_bf16_f32 v9, v10, v11
	v_or_b32_e32 v10, s8, v28
	v_lshl_add_u64 v[12:13], s[4:5], 0, v[4:5]
	s_mov_b64 s[4:5], 0xde0000
	v_ashrrev_i32_e32 v11, 31, v10
	v_lshl_add_u64 v[12:13], v[12:13], 0, s[4:5]
	v_lshlrev_b64 v[10:11], 11, v[10:11]
	v_lshl_add_u64 v[10:11], v[12:13], 0, v[10:11]
	ds_read2_b32 v[14:15], v29 offset0:8 offset1:41
	global_store_dwordx4 v[10:11], v[6:9], off nt
	s_waitcnt lgkmcnt(0)
	s_nop 0
	v_cvt_pk_bf16_f32 v6, v14, v15
	ds_read2_b32 v[8:9], v29 offset0:74 offset1:107
	s_waitcnt lgkmcnt(0)
	v_cvt_pk_bf16_f32 v7, v8, v9
	ds_read2_b32 v[8:9], v29 offset0:140 offset1:173
	s_waitcnt lgkmcnt(0)
	v_cvt_pk_bf16_f32 v8, v8, v9
	ds_read2_b32 v[10:11], v29 offset0:206 offset1:239
	s_waitcnt lgkmcnt(0)
	v_cvt_pk_bf16_f32 v9, v10, v11
	v_or_b32_e32 v10, s8, v30
	v_ashrrev_i32_e32 v11, 31, v10
	v_lshlrev_b64 v[10:11], 11, v[10:11]
	ds_read2_b32 v[14:15], v29 offset0:16 offset1:49
	v_lshl_add_u64 v[10:11], v[12:13], 0, v[10:11]
	global_store_dwordx4 v[10:11], v[6:9], off nt
	s_waitcnt lgkmcnt(0)
	s_nop 0
	v_cvt_pk_bf16_f32 v6, v14, v15
	v_or_b32_e32 v14, s8, v31
	ds_read2_b32 v[8:9], v29 offset0:82 offset1:115
	v_ashrrev_i32_e32 v15, 31, v14
	s_waitcnt lgkmcnt(0)
	v_cvt_pk_bf16_f32 v7, v8, v9
	ds_read2_b32 v[8:9], v29 offset0:148 offset1:181
	v_lshlrev_b64 v[14:15], 11, v[14:15]
	s_waitcnt lgkmcnt(0)
	v_cvt_pk_bf16_f32 v8, v8, v9
	ds_read2_b32 v[10:11], v29 offset0:214 offset1:247
	s_waitcnt lgkmcnt(0)
	v_cvt_pk_bf16_f32 v9, v10, v11
	v_lshl_add_u64 v[14:15], v[12:13], 0, v[14:15]
	ds_read2_b32 v[10:11], v29 offset0:24 offset1:57
	global_store_dwordx4 v[14:15], v[6:9], off nt
	v_or_b32_e32 v14, s8, v32
	v_ashrrev_i32_e32 v15, 31, v14
	s_waitcnt lgkmcnt(0)
	v_cvt_pk_bf16_f32 v6, v10, v11
	ds_read2_b32 v[8:9], v29 offset0:90 offset1:123
	s_waitcnt lgkmcnt(0)
	v_cvt_pk_bf16_f32 v7, v8, v9
	ds_read2_b32 v[8:9], v29 offset0:156 offset1:189
	s_waitcnt lgkmcnt(0)
	v_cvt_pk_bf16_f32 v8, v8, v9
	ds_read2_b32 v[10:11], v29 offset0:222 offset1:255
	v_lshlrev_b64 v[14:15], 11, v[14:15]
	s_waitcnt lgkmcnt(0)
	v_cvt_pk_bf16_f32 v9, v10, v11
	v_lshl_add_u64 v[10:11], v[12:13], 0, v[14:15]
	global_store_dwordx4 v[10:11], v[6:9], off nt
	s_waitcnt lgkmcnt(0)

.LBB0_56:
	s_andn2_b64 vcc, exec, s[4:5]
	s_cbranch_vccnz .LBB0_58
	v_mov_b32_e32 v7, s1
	v_mov_b32_e32 v8, s0
	s_add_i32 s8, s38, 0xfffff720
	v_readfirstlane_b32 s4, v8
	v_readfirstlane_b32 s5, v7
	s_load_dwordx2 s[4:5], s[4:5], 0xa0
	s_lshr_b32 s8, s8, 9
	s_lshl_b64 s[18:19], s[8:9], 22
	v_mov_b32_e32 v4, s0
	v_mov_b32_e32 v6, s1
	s_waitcnt lgkmcnt(0)
	s_add_u32 s24, s4, s18
	s_addc_u32 s19, s5, s19
	s_lshl_b64 s[22:23], s[8:9], 21
	v_readfirstlane_b32 s4, v4
	v_readfirstlane_b32 s5, v6
	s_load_dwordx2 s[20:21], s[4:5], 0xc0
	s_add_i32 s4, s7, 0xffffee40
	s_and_b32 s18, s4, 0x3c0
	s_and_b32 s4, s27, 0x3e0
	v_or_b32_e32 v8, s18, v3
	s_waitcnt lgkmcnt(0)
	s_add_u32 s8, s20, s22
	s_addc_u32 s5, s21, s23
	s_lshl_b32 s20, s4, 2
	s_add_u32 s20, s24, s20
	s_addc_u32 s21, s19, 0
	v_lshlrev_b32_e32 v4, 2, v0
	v_lshl_add_u64 v[6:7], s[20:21], 0, v[4:5]
	v_lshlrev_b32_e32 v4, 12, v8
	v_lshl_add_u64 v[6:7], v[6:7], 0, v[4:5]
	v_add_co_u32_e32 v8, vcc, s35, v6
	s_lshl_b32 s18, s18, 1
	s_nop 0
	v_addc_co_u32_e32 v9, vcc, 0, v7, vcc
	v_add_co_u32_e32 v10, vcc, s36, v6
	s_add_u32 s18, s8, s18
	s_nop 0
	v_addc_co_u32_e32 v11, vcc, 0, v7, vcc
	v_add_co_u32_e32 v12, vcc, s37, v6
	s_addc_u32 s19, s5, 0
	s_nop 0
	v_addc_co_u32_e32 v13, vcc, 0, v7, vcc
	v_add_co_u32_e32 v14, vcc, s74, v6
	s_nop 1
	v_addc_co_u32_e32 v15, vcc, 0, v7, vcc
	v_add_co_u32_e32 v16, vcc, s39, v6
	s_nop 1
	v_addc_co_u32_e32 v17, vcc, 0, v7, vcc
	v_add_co_u32_e32 v18, vcc, s40, v6
	s_nop 1
	v_addc_co_u32_e32 v19, vcc, 0, v7, vcc
	v_add_co_u32_e32 v20, vcc, s41, v6
	s_nop 1
	v_addc_co_u32_e32 v21, vcc, 0, v7, vcc
	global_load_dword v4, v[6:7], off nt
	global_load_dword v24, v[8:9], off nt
	global_load_dword v25, v[10:11], off nt
	global_load_dword v81, v[12:13], off nt
	global_load_dword v82, v[14:15], off nt
	global_load_dword v83, v[16:17], off nt
	global_load_dword v84, v[18:19], off nt
	global_load_dword v85, v[20:21], off nt
	v_add_co_u32_e32 v8, vcc, s42, v6
	s_nop 1
	v_addc_co_u32_e32 v9, vcc, 0, v7, vcc
	v_add_co_u32_e32 v10, vcc, s43, v6
	s_nop 1
	v_addc_co_u32_e32 v11, vcc, 0, v7, vcc
	v_add_co_u32_e32 v12, vcc, s44, v6
	s_nop 1
	v_addc_co_u32_e32 v13, vcc, 0, v7, vcc
	v_add_co_u32_e32 v14, vcc, s45, v6
	s_nop 1
	v_addc_co_u32_e32 v15, vcc, 0, v7, vcc
	v_add_co_u32_e32 v16, vcc, s46, v6
	s_nop 1
	v_addc_co_u32_e32 v17, vcc, 0, v7, vcc
	v_add_co_u32_e32 v18, vcc, s47, v6
	s_nop 1
	v_addc_co_u32_e32 v19, vcc, 0, v7, vcc
	v_add_co_u32_e32 v20, vcc, s48, v6
	s_nop 1
	v_addc_co_u32_e32 v21, vcc, 0, v7, vcc
	v_add_co_u32_e32 v22, vcc, s49, v6
	s_nop 1
	v_addc_co_u32_e32 v23, vcc, 0, v7, vcc
	global_load_dword v87, v[8:9], off nt
	global_load_dword v88, v[10:11], off nt
	global_load_dword v89, v[12:13], off nt
	global_load_dword v90, v[14:15], off nt
	global_load_dword v91, v[16:17], off nt
	global_load_dword v92, v[18:19], off nt
	global_load_dword v93, v[20:21], off nt
	global_load_dword v94, v[22:23], off nt
	v_add_co_u32_e32 v8, vcc, s50, v6
	s_nop 1
	v_addc_co_u32_e32 v9, vcc, 0, v7, vcc
	v_add_co_u32_e32 v10, vcc, s51, v6
	s_nop 1
	v_addc_co_u32_e32 v11, vcc, 0, v7, vcc
	v_add_co_u32_e32 v12, vcc, s52, v6
	s_nop 1
	v_addc_co_u32_e32 v13, vcc, 0, v7, vcc
	v_add_co_u32_e32 v14, vcc, s53, v6
	s_nop 1
	v_addc_co_u32_e32 v15, vcc, 0, v7, vcc
	v_add_co_u32_e32 v16, vcc, s54, v6
	s_nop 1
	v_addc_co_u32_e32 v17, vcc, 0, v7, vcc
	v_add_co_u32_e32 v18, vcc, s55, v6
	s_nop 1
	v_addc_co_u32_e32 v19, vcc, 0, v7, vcc
	v_add_co_u32_e32 v20, vcc, s56, v6
	s_nop 1
	v_addc_co_u32_e32 v21, vcc, 0, v7, vcc
	v_add_co_u32_e32 v22, vcc, s57, v6
	s_nop 1
	v_addc_co_u32_e32 v23, vcc, 0, v7, vcc
	global_load_dword v95, v[8:9], off nt
	global_load_dword v96, v[10:11], off nt
	global_load_dword v97, v[12:13], off nt
	global_load_dword v98, v[14:15], off nt
	global_load_dword v99, v[16:17], off nt
	global_load_dword v100, v[18:19], off nt
	global_load_dword v101, v[20:21], off nt
	s_nop 0
	global_load_dword v22, v[22:23], off nt
	v_add_co_u32_e32 v8, vcc, s58, v6
	s_nop 1
	v_addc_co_u32_e32 v9, vcc, 0, v7, vcc
	v_add_co_u32_e32 v10, vcc, s59, v6
	s_nop 1
	v_addc_co_u32_e32 v11, vcc, 0, v7, vcc
	v_add_co_u32_e32 v12, vcc, s60, v6
	s_nop 1
	v_addc_co_u32_e32 v13, vcc, 0, v7, vcc
	v_add_co_u32_e32 v14, vcc, s61, v6
	s_nop 1
	v_addc_co_u32_e32 v15, vcc, 0, v7, vcc
	v_add_co_u32_e32 v16, vcc, s62, v6
	s_nop 1
	v_addc_co_u32_e32 v17, vcc, 0, v7, vcc
	v_add_co_u32_e32 v18, vcc, s63, v6
	s_nop 1
	v_addc_co_u32_e32 v19, vcc, 0, v7, vcc
	v_add_co_u32_e32 v20, vcc, s64, v6
	s_nop 1
	v_addc_co_u32_e32 v21, vcc, 0, v7, vcc
	v_add_co_u32_e32 v6, vcc, s65, v6
	s_nop 1
	v_addc_co_u32_e32 v7, vcc, 0, v7, vcc
	global_load_dword v8, v[8:9], off nt
	s_nop 0
	global_load_dword v9, v[10:11], off nt
	s_nop 0
	global_load_dword v10, v[12:13], off nt
	global_load_dword v11, v[14:15], off nt
	s_nop 0
	global_load_dword v12, v[16:17], off nt
	global_load_dword v13, v[18:19], off nt
	global_load_dword v14, v[20:21], off nt
	s_nop 0
	global_load_dword v6, v[6:7], off nt
	s_waitcnt vmcnt(30)
	ds_write2_b32 v27, v4, v24 offset1:66
	s_waitcnt vmcnt(28)
	ds_write2_b32 v27, v25, v81 offset0:132 offset1:198
	v_add_u32_e32 v4, 0x400, v27
	s_waitcnt vmcnt(26)
	ds_write2_b32 v4, v82, v83 offset0:8 offset1:74
	s_waitcnt vmcnt(24)
	ds_write2_b32 v4, v84, v85 offset0:140 offset1:206
	v_add_u32_e32 v4, 0x800, v27
	s_waitcnt vmcnt(22)
	ds_write2_b32 v4, v87, v88 offset0:16 offset1:82
	s_waitcnt vmcnt(20)
	ds_write2_b32 v4, v89, v90 offset0:148 offset1:214
	v_add_u32_e32 v4, 0xc00, v27
	s_waitcnt vmcnt(18)
	ds_write2_b32 v4, v91, v92 offset0:24 offset1:90
	s_waitcnt vmcnt(16)
	ds_write2_b32 v4, v93, v94 offset0:156 offset1:222
	v_add_u32_e32 v4, 0x1000, v27
	s_waitcnt vmcnt(14)
	ds_write2_b32 v4, v95, v96 offset0:32 offset1:98
	s_waitcnt vmcnt(12)
	ds_write2_b32 v4, v97, v98 offset0:164 offset1:230
	v_add_u32_e32 v4, 0x1400, v27
	s_waitcnt vmcnt(10)
	ds_write2_b32 v4, v99, v100 offset0:40 offset1:106
	s_waitcnt vmcnt(8)
	ds_write2_b32 v4, v101, v22 offset0:172 offset1:238
	v_add_u32_e32 v4, 0x1800, v27
	s_waitcnt vmcnt(6)
	ds_write2_b32 v4, v8, v9 offset0:48 offset1:114
	s_waitcnt vmcnt(4)
	ds_write2_b32 v4, v10, v11 offset0:180 offset1:246
	v_add_u32_e32 v4, 0x1c00, v27
	s_waitcnt vmcnt(2)
	ds_write2_b32 v4, v12, v13 offset0:56 offset1:122
	s_waitcnt vmcnt(0)
	ds_write2_b32 v4, v14, v6 offset0:188 offset1:254
	s_waitcnt lgkmcnt(0)
	ds_read2_b32 v[6:7], v29 offset1:33
	v_lshlrev_b32_e32 v4, 1, v2
	s_waitcnt lgkmcnt(0)
	v_cvt_pk_bf16_f32 v6, v6, v7
	ds_read2_b32 v[8:9], v29 offset0:66 offset1:99
	v_lshl_add_u64 v[12:13], s[18:19], 0, v[4:5]
	s_mov_b64 s[18:19], 0x9e0000
	v_or_b32_e32 v4, s4, v28
	s_waitcnt lgkmcnt(0)
	v_cvt_pk_bf16_f32 v7, v8, v9
	ds_read2_b32 v[8:9], v29 offset0:132 offset1:165
	v_lshl_add_u64 v[12:13], v[12:13], 0, s[18:19]
	v_lshlrev_b32_e32 v4, 11, v4
	s_waitcnt lgkmcnt(0)
	v_cvt_pk_bf16_f32 v8, v8, v9
	ds_read2_b32 v[10:11], v29 offset0:198 offset1:231
	s_waitcnt lgkmcnt(0)
	v_cvt_pk_bf16_f32 v9, v10, v11
	v_lshl_add_u64 v[14:15], v[12:13], 0, v[4:5]
	ds_read2_b32 v[10:11], v29 offset0:8 offset1:41
	global_store_dwordx4 v[14:15], v[6:9], off nt
	v_or_b32_e32 v4, s4, v30
	v_lshlrev_b32_e32 v4, 11, v4
	s_waitcnt lgkmcnt(0)
	v_cvt_pk_bf16_f32 v6, v10, v11
	ds_read2_b32 v[8:9], v29 offset0:74 offset1:107
	s_waitcnt lgkmcnt(0)
	v_cvt_pk_bf16_f32 v7, v8, v9
	ds_read2_b32 v[8:9], v29 offset0:140 offset1:173
	s_waitcnt lgkmcnt(0)
	v_cvt_pk_bf16_f32 v8, v8, v9
	ds_read2_b32 v[10:11], v29 offset0:206 offset1:239
	s_waitcnt lgkmcnt(0)
	v_cvt_pk_bf16_f32 v9, v10, v11
	v_lshl_add_u64 v[14:15], v[12:13], 0, v[4:5]
	ds_read2_b32 v[10:11], v29 offset0:16 offset1:49
	global_store_dwordx4 v[14:15], v[6:9], off nt
	v_or_b32_e32 v4, s4, v31
	v_lshlrev_b32_e32 v4, 11, v4
	s_waitcnt lgkmcnt(0)
	v_cvt_pk_bf16_f32 v6, v10, v11
	ds_read2_b32 v[8:9], v29 offset0:82 offset1:115
	s_waitcnt lgkmcnt(0)
	v_cvt_pk_bf16_f32 v7, v8, v9
	ds_read2_b32 v[8:9], v29 offset0:148 offset1:181
	s_waitcnt lgkmcnt(0)
	v_cvt_pk_bf16_f32 v8, v8, v9
	ds_read2_b32 v[10:11], v29 offset0:214 offset1:247
	s_waitcnt lgkmcnt(0)
	v_cvt_pk_bf16_f32 v9, v10, v11
	v_lshl_add_u64 v[14:15], v[12:13], 0, v[4:5]
	ds_read2_b32 v[10:11], v29 offset0:24 offset1:57
	global_store_dwordx4 v[14:15], v[6:9], off nt
	v_or_b32_e32 v4, s4, v32
	v_lshlrev_b32_e32 v4, 11, v4
	s_waitcnt lgkmcnt(0)
	v_cvt_pk_bf16_f32 v6, v10, v11
	ds_read2_b32 v[8:9], v29 offset0:90 offset1:123
	s_waitcnt lgkmcnt(0)
	v_cvt_pk_bf16_f32 v7, v8, v9
	ds_read2_b32 v[8:9], v29 offset0:156 offset1:189
	s_waitcnt lgkmcnt(0)
	v_cvt_pk_bf16_f32 v8, v8, v9
	ds_read2_b32 v[10:11], v29 offset0:222 offset1:255
	s_waitcnt lgkmcnt(0)
	v_cvt_pk_bf16_f32 v9, v10, v11
	v_lshl_add_u64 v[10:11], v[12:13], 0, v[4:5]
	global_store_dwordx4 v[10:11], v[6:9], off nt
	s_waitcnt lgkmcnt(0)

.LBB0_59:
	s_andn2_b64 vcc, exec, s[4:5]
	s_cbranch_vccnz .LBB0_61
	v_mov_b32_e32 v7, s0
	v_mov_b32_e32 v8, s1
	v_mov_b32_e32 v4, s0
	v_readfirstlane_b32 s4, v7
	v_readfirstlane_b32 s5, v8
	v_mov_b32_e32 v7, s0
	v_mov_b32_e32 v8, s1
	v_mov_b32_e32 v6, s1
	s_load_dwordx2 s[22:23], s[4:5], 0x90
	s_and_b32 s8, s7, 0x1fc0
	v_readfirstlane_b32 s4, v7
	v_readfirstlane_b32 s5, v8
	s_load_dwordx2 s[4:5], s[4:5], 0xc0
	s_and_b32 s21, s27, 0x3e0
	v_readfirstlane_b32 s18, v4
	v_readfirstlane_b32 s19, v6
	s_load_dwordx2 s[18:19], s[18:19], 0x10
	s_addk_i32 s8, 0xf240
	s_add_i32 s20, s21, 0x200
	v_or_b32_e32 v6, s8, v3
	v_lshlrev_b32_e32 v4, 2, v0
	s_waitcnt lgkmcnt(0)
	s_add_u32 s18, s18, 0x1000
	s_addc_u32 s19, s19, 0
	s_lshl_b32 s21, s21, 2
	s_add_u32 s22, s22, s21
	s_addc_u32 s23, s23, 0
	v_lshl_add_u64 v[8:9], s[22:23], 0, v[4:5]
	v_or_b32_e32 v4, 2, v6
	v_lshlrev_b64 v[12:13], 12, v[4:5]
	v_or_b32_e32 v4, 4, v6
	v_lshlrev_b64 v[14:15], 12, v[4:5]
	v_or_b32_e32 v4, 6, v6
	v_lshlrev_b64 v[16:17], 12, v[4:5]
	v_or_b32_e32 v4, 8, v6
	v_lshlrev_b64 v[18:19], 12, v[4:5]
	v_or_b32_e32 v4, 10, v6
	v_mov_b32_e32 v7, v5
	v_lshlrev_b64 v[20:21], 12, v[4:5]
	v_or_b32_e32 v4, 12, v6
	v_lshlrev_b64 v[10:11], 12, v[6:7]
	v_lshlrev_b64 v[22:23], 12, v[4:5]
	v_or_b32_e32 v4, 14, v6
	v_lshl_add_u64 v[10:11], v[8:9], 0, v[10:11]
	v_lshlrev_b64 v[24:25], 12, v[4:5]
	v_or_b32_e32 v4, 16, v6
	v_lshl_add_u64 v[12:13], v[8:9], 0, v[12:13]
	v_lshl_add_u64 v[14:15], v[8:9], 0, v[14:15]
	v_lshl_add_u64 v[16:17], v[8:9], 0, v[16:17]
	v_lshl_add_u64 v[18:19], v[8:9], 0, v[18:19]
	v_lshl_add_u64 v[20:21], v[8:9], 0, v[20:21]
	v_lshl_add_u64 v[22:23], v[8:9], 0, v[22:23]
	v_lshl_add_u64 v[24:25], v[8:9], 0, v[24:25]
	global_load_dword v81, v[10:11], off nt
	global_load_dword v82, v[12:13], off nt
	global_load_dword v83, v[14:15], off nt
	global_load_dword v84, v[16:17], off nt
	global_load_dword v85, v[18:19], off nt
	global_load_dword v87, v[20:21], off nt
	global_load_dword v88, v[22:23], off nt
	global_load_dword v89, v[24:25], off nt
	v_lshlrev_b64 v[10:11], 12, v[4:5]
	v_or_b32_e32 v4, 18, v6
	v_lshlrev_b64 v[12:13], 12, v[4:5]
	v_or_b32_e32 v4, 20, v6
	v_lshlrev_b64 v[14:15], 12, v[4:5]
	v_or_b32_e32 v4, 22, v6
	v_lshlrev_b64 v[16:17], 12, v[4:5]
	v_or_b32_e32 v4, 24, v6
	v_lshlrev_b64 v[18:19], 12, v[4:5]
	v_or_b32_e32 v4, 26, v6
	v_lshlrev_b64 v[20:21], 12, v[4:5]
	v_or_b32_e32 v4, 28, v6
	v_lshlrev_b64 v[22:23], 12, v[4:5]
	v_or_b32_e32 v4, 30, v6
	v_lshl_add_u64 v[10:11], v[8:9], 0, v[10:11]
	v_lshlrev_b64 v[24:25], 12, v[4:5]
	v_or_b32_e32 v4, 32, v6
	v_lshl_add_u64 v[12:13], v[8:9], 0, v[12:13]
	v_lshl_add_u64 v[14:15], v[8:9], 0, v[14:15]
	v_lshl_add_u64 v[16:17], v[8:9], 0, v[16:17]
	v_lshl_add_u64 v[18:19], v[8:9], 0, v[18:19]
	v_lshl_add_u64 v[20:21], v[8:9], 0, v[20:21]
	v_lshl_add_u64 v[22:23], v[8:9], 0, v[22:23]
	v_lshl_add_u64 v[24:25], v[8:9], 0, v[24:25]
	global_load_dword v90, v[10:11], off nt
	global_load_dword v91, v[12:13], off nt
	global_load_dword v92, v[14:15], off nt
	global_load_dword v93, v[16:17], off nt
	global_load_dword v94, v[18:19], off nt
	global_load_dword v95, v[20:21], off nt
	global_load_dword v96, v[22:23], off nt
	global_load_dword v97, v[24:25], off nt
	v_lshlrev_b64 v[10:11], 12, v[4:5]
	v_or_b32_e32 v4, 34, v6
	v_lshlrev_b64 v[12:13], 12, v[4:5]
	v_or_b32_e32 v4, 36, v6
	v_lshlrev_b64 v[14:15], 12, v[4:5]
	v_or_b32_e32 v4, 38, v6
	v_lshlrev_b64 v[16:17], 12, v[4:5]
	v_or_b32_e32 v4, 40, v6
	v_lshlrev_b64 v[18:19], 12, v[4:5]
	v_or_b32_e32 v4, 42, v6
	v_lshlrev_b64 v[20:21], 12, v[4:5]
	v_or_b32_e32 v4, 44, v6
	v_lshlrev_b64 v[22:23], 12, v[4:5]
	v_or_b32_e32 v4, 46, v6
	v_lshl_add_u64 v[10:11], v[8:9], 0, v[10:11]
	v_lshlrev_b64 v[24:25], 12, v[4:5]
	v_or_b32_e32 v4, 48, v6
	v_lshl_add_u64 v[12:13], v[8:9], 0, v[12:13]
	v_lshl_add_u64 v[14:15], v[8:9], 0, v[14:15]
	v_lshl_add_u64 v[16:17], v[8:9], 0, v[16:17]
	v_lshl_add_u64 v[18:19], v[8:9], 0, v[18:19]
	v_lshl_add_u64 v[20:21], v[8:9], 0, v[20:21]
	v_lshl_add_u64 v[22:23], v[8:9], 0, v[22:23]
	v_lshl_add_u64 v[24:25], v[8:9], 0, v[24:25]
	global_load_dword v98, v[10:11], off nt
	global_load_dword v99, v[12:13], off nt
	global_load_dword v100, v[14:15], off nt
	global_load_dword v101, v[16:17], off nt
	global_load_dword v102, v[18:19], off nt
	global_load_dword v103, v[20:21], off nt
	global_load_dword v104, v[22:23], off nt
	global_load_dword v105, v[24:25], off nt
	v_lshlrev_b64 v[10:11], 12, v[4:5]
	v_or_b32_e32 v4, 50, v6
	v_lshlrev_b64 v[12:13], 12, v[4:5]
	v_or_b32_e32 v4, 52, v6
	v_lshlrev_b64 v[14:15], 12, v[4:5]
	v_or_b32_e32 v4, 54, v6
	v_lshlrev_b64 v[16:17], 12, v[4:5]
	v_or_b32_e32 v4, 56, v6
	v_lshlrev_b64 v[18:19], 12, v[4:5]
	v_or_b32_e32 v4, 58, v6
	v_lshlrev_b64 v[20:21], 12, v[4:5]
	v_or_b32_e32 v4, 60, v6
	v_lshlrev_b64 v[22:23], 12, v[4:5]
	v_or_b32_e32 v4, 62, v6
	v_lshlrev_b64 v[24:25], 12, v[4:5]
	v_lshl_add_u64 v[10:11], v[8:9], 0, v[10:11]
	v_lshl_add_u64 v[12:13], v[8:9], 0, v[12:13]
	v_lshl_add_u64 v[14:15], v[8:9], 0, v[14:15]
	v_lshl_add_u64 v[16:17], v[8:9], 0, v[16:17]
	v_lshl_add_u64 v[18:19], v[8:9], 0, v[18:19]
	v_lshl_add_u64 v[20:21], v[8:9], 0, v[20:21]
	v_lshl_add_u64 v[22:23], v[8:9], 0, v[22:23]
	v_lshl_add_u64 v[8:9], v[8:9], 0, v[24:25]
	v_or_b32_e32 v4, s8, v33
	global_load_dword v24, v[10:11], off nt
	global_load_dword v25, v[12:13], off nt
	global_load_dword v106, v[14:15], off nt
	global_load_dword v107, v[16:17], off nt
	global_load_dword v108, v[18:19], off nt
	global_load_dword v109, v[20:21], off nt
	s_nop 0
	global_load_dword v22, v[22:23], off nt
	s_nop 0
	global_load_dword v23, v[8:9], off nt
	v_lshl_add_u64 v[8:9], v[4:5], 2, s[18:19]
	v_or_b32_e32 v4, s8, v35
	v_lshl_add_u64 v[10:11], v[4:5], 2, s[18:19]
	v_or_b32_e32 v4, s8, v37
	v_lshl_add_u64 v[12:13], v[4:5], 2, s[18:19]
	v_or_b32_e32 v4, s8, v38
	v_lshl_add_u64 v[14:15], v[4:5], 2, s[18:19]
	v_or_b32_e32 v4, s8, v40
	v_lshl_add_u64 v[16:17], v[4:5], 2, s[18:19]
	v_or_b32_e32 v4, s8, v41
	v_lshl_add_u64 v[18:19], v[4:5], 2, s[18:19]
	v_or_b32_e32 v4, s8, v43
	v_lshl_add_u64 v[6:7], v[6:7], 2, s[18:19]
	v_lshl_add_u64 v[20:21], v[4:5], 2, s[18:19]
	v_or_b32_e32 v4, s8, v44
	global_load_dword v110, v[6:7], off nt
	global_load_dword v111, v[8:9], off nt
	global_load_dword v112, v[10:11], off nt
	global_load_dword v113, v[12:13], off nt
	global_load_dword v114, v[14:15], off nt
	global_load_dword v115, v[16:17], off nt
	global_load_dword v116, v[18:19], off nt
	global_load_dword v117, v[20:21], off nt
	v_lshl_add_u64 v[6:7], v[4:5], 2, s[18:19]
	v_or_b32_e32 v4, s8, v46
	v_lshl_add_u64 v[8:9], v[4:5], 2, s[18:19]
	v_or_b32_e32 v4, s8, v47
	v_lshl_add_u64 v[10:11], v[4:5], 2, s[18:19]
	v_or_b32_e32 v4, s8, v49
	v_lshl_add_u64 v[12:13], v[4:5], 2, s[18:19]
	v_or_b32_e32 v4, s8, v50
	v_lshl_add_u64 v[14:15], v[4:5], 2, s[18:19]
	v_or_b32_e32 v4, s8, v52
	v_lshl_add_u64 v[16:17], v[4:5], 2, s[18:19]
	v_or_b32_e32 v4, s8, v53
	v_lshl_add_u64 v[18:19], v[4:5], 2, s[18:19]
	v_or_b32_e32 v4, s8, v55
	v_lshl_add_u64 v[20:21], v[4:5], 2, s[18:19]
	v_or_b32_e32 v4, s8, v56
	global_load_dword v118, v[6:7], off nt
	global_load_dword v119, v[8:9], off nt
	global_load_dword v120, v[10:11], off nt
	global_load_dword v121, v[12:13], off nt
	global_load_dword v122, v[14:15], off nt
	global_load_dword v123, v[16:17], off nt
	global_load_dword v124, v[18:19], off nt
	global_load_dword v125, v[20:21], off nt
	v_lshl_add_u64 v[6:7], v[4:5], 2, s[18:19]
	v_or_b32_e32 v4, s8, v58
	v_lshl_add_u64 v[8:9], v[4:5], 2, s[18:19]
	v_or_b32_e32 v4, s8, v59
	v_lshl_add_u64 v[10:11], v[4:5], 2, s[18:19]
	v_or_b32_e32 v4, s8, v61
	v_lshl_add_u64 v[12:13], v[4:5], 2, s[18:19]
	v_or_b32_e32 v4, s8, v62
	v_lshl_add_u64 v[14:15], v[4:5], 2, s[18:19]
	v_or_b32_e32 v4, s8, v64
	v_lshl_add_u64 v[16:17], v[4:5], 2, s[18:19]
	v_or_b32_e32 v4, s8, v65
	v_lshl_add_u64 v[18:19], v[4:5], 2, s[18:19]
	v_or_b32_e32 v4, s8, v67
	v_lshl_add_u64 v[20:21], v[4:5], 2, s[18:19]
	v_or_b32_e32 v4, s8, v68
	global_load_dword v126, v[6:7], off nt
	global_load_dword v127, v[8:9], off nt
	global_load_dword v128, v[10:11], off nt
	global_load_dword v129, v[12:13], off nt
	s_nop 0
	global_load_dword v14, v[14:15], off nt
	s_nop 0
	global_load_dword v15, v[16:17], off nt
	s_nop 0
	global_load_dword v16, v[18:19], off nt
	global_load_dword v17, v[20:21], off nt
	v_lshl_add_u64 v[6:7], v[4:5], 2, s[18:19]
	v_or_b32_e32 v4, s8, v71
	global_load_dword v18, v[6:7], off nt
	v_lshl_add_u64 v[6:7], v[4:5], 2, s[18:19]
	v_or_b32_e32 v4, s8, v72
	v_lshl_add_u64 v[8:9], v[4:5], 2, s[18:19]
	v_or_b32_e32 v4, s8, v73
	v_lshl_add_u64 v[10:11], v[4:5], 2, s[18:19]
	v_or_b32_e32 v4, s8, v74
	v_lshl_add_u64 v[12:13], v[4:5], 2, s[18:19]
	v_or_b32_e32 v4, s8, v78
	global_load_dword v19, v[6:7], off nt
	global_load_dword v20, v[8:9], off nt
	s_nop 0
	global_load_dword v10, v[10:11], off nt
	s_nop 0
	global_load_dword v11, v[12:13], off nt
	v_lshl_add_u64 v[6:7], v[4:5], 2, s[18:19]
	v_or_b32_e32 v4, s8, v79
	v_lshl_add_u64 v[8:9], v[4:5], 2, s[18:19]
	v_or_b32_e32 v4, s8, v80
	global_load_dword v12, v[6:7], off nt
	s_nop 0
	global_load_dword v8, v[8:9], off nt
	v_lshl_add_u64 v[6:7], v[4:5], 2, s[18:19]
	global_load_dword v4, v[6:7], off nt
	v_add_u32_e32 v7, v26, v34
	s_lshl_b64 s[18:19], s[8:9], 1
	s_add_u32 s4, s4, s18
	s_addc_u32 s5, s5, s19
	s_waitcnt vmcnt(31)
	v_mul_f32_e32 v6, v81, v110
	ds_write_b32 v27, v6
	s_waitcnt vmcnt(30)
	v_mul_f32_e32 v6, v82, v111
	s_waitcnt vmcnt(29)
	v_mul_f32_e32 v9, v83, v112
	ds_write2_b32 v7, v6, v9 offset1:66
	s_waitcnt vmcnt(28)
	v_mul_f32_e32 v6, v84, v113
	s_waitcnt vmcnt(27)
	v_mul_f32_e32 v9, v85, v114
	ds_write2_b32 v7, v6, v9 offset0:132 offset1:198
	s_waitcnt vmcnt(26)
	v_mul_f32_e32 v6, v87, v115
	s_waitcnt vmcnt(25)
	v_mul_f32_e32 v9, v88, v116
	v_add_u32_e32 v7, 0x400, v7
	ds_write2_b32 v7, v6, v9 offset0:8 offset1:74
	s_waitcnt vmcnt(24)
	v_mul_f32_e32 v6, v89, v117
	v_add_u32_e32 v9, 0x400, v75
	s_waitcnt vmcnt(23)
	v_mul_f32_e32 v7, v90, v118
	ds_write2_b32 v75, v6, v7 offset1:66
	s_waitcnt vmcnt(22)
	v_mul_f32_e32 v6, v91, v119
	s_waitcnt vmcnt(21)
	v_mul_f32_e32 v7, v92, v120
	ds_write2_b32 v75, v6, v7 offset0:132 offset1:198
	s_waitcnt vmcnt(20)
	v_mul_f32_e32 v6, v93, v121
	s_waitcnt vmcnt(19)
	v_mul_f32_e32 v7, v94, v122
	ds_write2_b32 v9, v6, v7 offset0:8 offset1:74
	s_waitcnt vmcnt(18)
	v_mul_f32_e32 v6, v95, v123
	s_waitcnt vmcnt(17)
	v_mul_f32_e32 v7, v96, v124
	ds_write2_b32 v76, v6, v7 offset1:66
	s_waitcnt vmcnt(16)
	v_mul_f32_e32 v6, v97, v125
	v_add_u32_e32 v9, 0x400, v76
	s_waitcnt vmcnt(15)
	v_mul_f32_e32 v7, v98, v126
	ds_write2_b32 v76, v6, v7 offset0:132 offset1:198
	s_waitcnt vmcnt(14)
	v_mul_f32_e32 v6, v99, v127
	s_waitcnt vmcnt(13)
	v_mul_f32_e32 v7, v100, v128
	ds_write2_b32 v9, v6, v7 offset0:8 offset1:74
	s_waitcnt vmcnt(12)
	v_mul_f32_e32 v6, v101, v129
	s_waitcnt vmcnt(11)
	v_mul_f32_e32 v7, v102, v14
	ds_write2_b32 v77, v6, v7 offset1:66
	s_waitcnt vmcnt(10)
	v_mul_f32_e32 v6, v103, v15
	s_waitcnt vmcnt(9)
	v_mul_f32_e32 v7, v104, v16
	ds_write2_b32 v77, v6, v7 offset0:132 offset1:198
	s_waitcnt vmcnt(8)
	v_mul_f32_e32 v6, v105, v17
	s_waitcnt vmcnt(7)
	v_mul_f32_e32 v7, v24, v18
	v_add_u32_e32 v9, 0x400, v77
	ds_write2_b32 v9, v6, v7 offset0:8 offset1:74
	v_add_u32_e32 v7, v26, v69
	s_waitcnt vmcnt(6)
	v_mul_f32_e32 v6, v25, v19
	s_waitcnt vmcnt(5)
	v_mul_f32_e32 v9, v106, v20
	ds_write2_b32 v7, v6, v9 offset0:66 offset1:132
	s_waitcnt vmcnt(4)
	v_mul_f32_e32 v6, v107, v10
	s_waitcnt vmcnt(3)
	v_mul_f32_e32 v9, v108, v11
	v_add_u32_e32 v10, 0x200, v7
	ds_write2_b32 v10, v6, v9 offset0:70 offset1:136
	s_waitcnt vmcnt(2)
	v_mul_f32_e32 v6, v109, v12
	s_waitcnt vmcnt(1)
	v_mul_f32_e32 v8, v22, v8
	v_add_u32_e32 v9, 0x400, v7
	s_waitcnt vmcnt(0)
	v_mul_f32_e32 v4, v23, v4
	ds_write2_b32 v9, v6, v8 offset0:74 offset1:140
	ds_write_b32 v7, v4 offset:1848
	s_waitcnt lgkmcnt(0)
	ds_read2_b32 v[6:7], v29 offset1:33
	v_lshlrev_b32_e32 v4, 1, v2
	s_waitcnt lgkmcnt(0)
	v_cvt_pk_bf16_f32 v6, v6, v7
	ds_read2_b32 v[8:9], v29 offset0:66 offset1:99
	v_lshl_add_u64 v[12:13], s[4:5], 0, v[4:5]
	v_or_b32_e32 v4, s20, v28
	s_waitcnt lgkmcnt(0)
	v_cvt_pk_bf16_f32 v7, v8, v9
	ds_read2_b32 v[8:9], v29 offset0:132 offset1:165
	v_lshl_add_u64 v[12:13], v[12:13], 0, s[10:11]
	v_lshlrev_b32_e32 v4, 11, v4
	s_waitcnt lgkmcnt(0)
	v_cvt_pk_bf16_f32 v8, v8, v9
	ds_read2_b32 v[10:11], v29 offset0:198 offset1:231
	s_waitcnt lgkmcnt(0)
	v_cvt_pk_bf16_f32 v9, v10, v11
	v_lshl_add_u64 v[14:15], v[12:13], 0, v[4:5]
	ds_read2_b32 v[10:11], v29 offset0:8 offset1:41
	global_store_dwordx4 v[14:15], v[6:9], off nt
	v_or_b32_e32 v4, s20, v30
	v_lshlrev_b32_e32 v4, 11, v4
	s_waitcnt lgkmcnt(0)
	v_cvt_pk_bf16_f32 v6, v10, v11
	ds_read2_b32 v[8:9], v29 offset0:74 offset1:107
	s_waitcnt lgkmcnt(0)
	v_cvt_pk_bf16_f32 v7, v8, v9
	ds_read2_b32 v[8:9], v29 offset0:140 offset1:173
	s_waitcnt lgkmcnt(0)
	v_cvt_pk_bf16_f32 v8, v8, v9
	ds_read2_b32 v[10:11], v29 offset0:206 offset1:239
	s_waitcnt lgkmcnt(0)
	v_cvt_pk_bf16_f32 v9, v10, v11
	v_lshl_add_u64 v[14:15], v[12:13], 0, v[4:5]
	ds_read2_b32 v[10:11], v29 offset0:16 offset1:49
	global_store_dwordx4 v[14:15], v[6:9], off nt
	v_or_b32_e32 v4, s20, v31
	v_lshlrev_b32_e32 v4, 11, v4
	s_waitcnt lgkmcnt(0)
	v_cvt_pk_bf16_f32 v6, v10, v11
	ds_read2_b32 v[8:9], v29 offset0:82 offset1:115
	s_waitcnt lgkmcnt(0)
	v_cvt_pk_bf16_f32 v7, v8, v9
	ds_read2_b32 v[8:9], v29 offset0:148 offset1:181
	s_waitcnt lgkmcnt(0)
	v_cvt_pk_bf16_f32 v8, v8, v9
	ds_read2_b32 v[10:11], v29 offset0:214 offset1:247
	s_waitcnt lgkmcnt(0)
	v_cvt_pk_bf16_f32 v9, v10, v11
	v_lshl_add_u64 v[14:15], v[12:13], 0, v[4:5]
	ds_read2_b32 v[10:11], v29 offset0:24 offset1:57
	global_store_dwordx4 v[14:15], v[6:9], off nt
	v_or_b32_e32 v4, s20, v32
	v_lshlrev_b32_e32 v4, 11, v4
	s_waitcnt lgkmcnt(0)
	v_cvt_pk_bf16_f32 v6, v10, v11
	ds_read2_b32 v[8:9], v29 offset0:90 offset1:123
	s_waitcnt lgkmcnt(0)
	v_cvt_pk_bf16_f32 v7, v8, v9
	ds_read2_b32 v[8:9], v29 offset0:156 offset1:189
	s_waitcnt lgkmcnt(0)
	v_cvt_pk_bf16_f32 v8, v8, v9
	ds_read2_b32 v[10:11], v29 offset0:222 offset1:255
	s_waitcnt lgkmcnt(0)
	v_cvt_pk_bf16_f32 v9, v10, v11
	v_lshl_add_u64 v[10:11], v[12:13], 0, v[4:5]
	global_store_dwordx4 v[10:11], v[6:9], off nt
	s_waitcnt lgkmcnt(0)

.LBB0_87:
	ds_write2_b32 v4, v8, v9 offset0:140 offset1:206
	s_lshl_b64 s[4:5], s[8:9], 1
	s_waitcnt lgkmcnt(0)
	s_waitcnt lgkmcnt(0)
	s_add_u32 s4, s18, s4
	s_waitcnt vmcnt(0)
	ds_read2_b32 v[6:7], v29 offset1:33
	v_lshlrev_b32_e32 v4, 1, v2
	s_addc_u32 s5, s19, s5
	s_waitcnt lgkmcnt(0)
	v_cvt_pk_bf16_f32 v6, v6, v7
	ds_read2_b32 v[8:9], v29 offset0:66 offset1:99
	v_or_b32_e32 v14, s72, v28
	v_lshl_add_u64 v[12:13], s[4:5], 0, v[4:5]
	s_waitcnt lgkmcnt(0)
	v_cvt_pk_bf16_f32 v7, v8, v9
	ds_read2_b32 v[8:9], v29 offset0:132 offset1:165
	v_lshlrev_b32_e32 v4, 11, v14
	v_lshl_add_u64 v[12:13], v[12:13], 0, s[10:11]
	s_waitcnt lgkmcnt(0)
	v_cvt_pk_bf16_f32 v8, v8, v9
	ds_read2_b32 v[10:11], v29 offset0:198 offset1:231
	s_waitcnt lgkmcnt(0)
	v_cvt_pk_bf16_f32 v9, v10, v11
	v_lshl_add_u64 v[14:15], v[12:13], 0, v[4:5]
	ds_read2_b32 v[10:11], v29 offset0:8 offset1:41
	global_store_dwordx4 v[14:15], v[6:9], off nt
	v_or_b32_e32 v4, s72, v30
	v_lshlrev_b32_e32 v4, 11, v4
	s_waitcnt lgkmcnt(0)
	v_cvt_pk_bf16_f32 v6, v10, v11
	ds_read2_b32 v[8:9], v29 offset0:74 offset1:107
	s_waitcnt lgkmcnt(0)
	v_cvt_pk_bf16_f32 v7, v8, v9
	ds_read2_b32 v[8:9], v29 offset0:140 offset1:173
	s_waitcnt lgkmcnt(0)
	v_cvt_pk_bf16_f32 v8, v8, v9
	ds_read2_b32 v[10:11], v29 offset0:206 offset1:239
	s_waitcnt lgkmcnt(0)
	v_cvt_pk_bf16_f32 v9, v10, v11
	v_lshl_add_u64 v[14:15], v[12:13], 0, v[4:5]
	ds_read2_b32 v[10:11], v29 offset0:16 offset1:49
	global_store_dwordx4 v[14:15], v[6:9], off nt
	v_or_b32_e32 v4, s72, v31
	v_lshlrev_b32_e32 v4, 11, v4
	s_waitcnt lgkmcnt(0)
	v_cvt_pk_bf16_f32 v6, v10, v11
	ds_read2_b32 v[8:9], v29 offset0:82 offset1:115
	s_waitcnt lgkmcnt(0)
	v_cvt_pk_bf16_f32 v7, v8, v9
	ds_read2_b32 v[8:9], v29 offset0:148 offset1:181
	s_waitcnt lgkmcnt(0)
	v_cvt_pk_bf16_f32 v8, v8, v9
	ds_read2_b32 v[10:11], v29 offset0:214 offset1:247
	s_waitcnt lgkmcnt(0)
	v_cvt_pk_bf16_f32 v9, v10, v11
	v_lshl_add_u64 v[14:15], v[12:13], 0, v[4:5]
	ds_read2_b32 v[10:11], v29 offset0:24 offset1:57
	global_store_dwordx4 v[14:15], v[6:9], off nt
	v_or_b32_e32 v4, s72, v32
	v_lshlrev_b32_e32 v4, 11, v4
	s_waitcnt lgkmcnt(0)
	v_cvt_pk_bf16_f32 v6, v10, v11
	ds_read2_b32 v[8:9], v29 offset0:90 offset1:123
	s_waitcnt lgkmcnt(0)
	v_cvt_pk_bf16_f32 v7, v8, v9
	ds_read2_b32 v[8:9], v29 offset0:156 offset1:189
	s_waitcnt lgkmcnt(0)
	v_cvt_pk_bf16_f32 v8, v8, v9
	ds_read2_b32 v[10:11], v29 offset0:222 offset1:255
	s_waitcnt lgkmcnt(0)
	v_cvt_pk_bf16_f32 v9, v10, v11
	v_lshl_add_u64 v[10:11], v[12:13], 0, v[4:5]
	global_store_dwordx4 v[10:11], v[6:9], off nt
	s_waitcnt lgkmcnt(0)

.LBB0_94:
	s_lshr_b32 s8, s20, 3
	s_add_i32 s23, s8, -6
	s_and_b64 s[4:5], exec, s[4:5]
	s_cselect_b32 s8, s8, s23
	s_add_u32 s4, s21, s18
	s_addc_u32 s5, s22, s19
	s_load_dwordx2 s[4:5], s[4:5], 0x0
	v_mov_b32_e32 v4, s0
	v_mov_b32_e32 v6, s1
	s_lshl_b64 s[18:19], s[8:9], 16
	v_readfirstlane_b32 s22, v4
	v_readfirstlane_b32 s23, v6
	s_load_dwordx2 s[22:23], s[22:23], 0xc0
	s_waitcnt lgkmcnt(0)
	s_add_u32 s8, s4, s18
	s_addc_u32 s5, s5, s19
	s_and_b32 s21, s31, 64
	s_and_b32 s24, s27, 0x60
	s_add_u32 s22, s22, s18
	s_addc_u32 s23, s23, s19
	s_cmp_gt_u32 s20, 47
	s_cselect_b32 s4, 0x80, 0
	s_or_b32 s4, s4, s24
	s_lshl_b32 s18, s24, 2
	s_add_u32 s18, s8, s18
	v_or_b32_e32 v8, s21, v3
	s_addc_u32 s19, s5, 0
	v_lshlrev_b32_e32 v4, 2, v0
	v_lshl_add_u64 v[6:7], s[18:19], 0, v[4:5]
	v_lshlrev_b32_e32 v4, 9, v8
	v_lshl_add_u64 v[6:7], v[6:7], 0, v[4:5]
	s_movk_i32 s5, 0x1000
	v_add_co_u32_e32 v8, vcc, s5, v6
	v_add_u32_e32 v94, 0x800, v27
	s_nop 0
	v_addc_co_u32_e32 v9, vcc, 0, v7, vcc
	v_add_co_u32_e32 v10, vcc, s35, v6
	v_add_u32_e32 v95, 0xc00, v27
	s_nop 0
	v_addc_co_u32_e32 v11, vcc, 0, v7, vcc
	v_add_co_u32_e32 v12, vcc, s67, v6
	v_add_u32_e32 v96, 0x1000, v27
	s_nop 0
	v_addc_co_u32_e32 v13, vcc, 0, v7, vcc
	v_add_co_u32_e32 v14, vcc, s36, v6
	s_lshl_b32 s5, s21, 1
	s_nop 0
	v_addc_co_u32_e32 v15, vcc, 0, v7, vcc
	global_load_dword v4, v[6:7], off nt
	global_load_dword v16, v[6:7], off offset:1024 nt
	global_load_dword v17, v[6:7], off offset:2048 nt
	global_load_dword v18, v[6:7], off offset:3072 nt
	global_load_dword v19, v[8:9], off offset:1024 nt
	global_load_dword v20, v[8:9], off offset:2048 nt
	global_load_dword v21, v[8:9], off offset:3072 nt
	global_load_dword v22, v[12:13], off offset:1024 nt
	global_load_dword v23, v[10:11], off offset:-4096 nt
	global_load_dword v24, v[10:11], off nt
	global_load_dword v25, v[10:11], off offset:1024 nt
	global_load_dword v81, v[10:11], off offset:2048 nt
	global_load_dword v82, v[10:11], off offset:3072 nt
	global_load_dword v83, v[14:15], off offset:-4096 nt
	global_load_dword v84, v[14:15], off nt
	v_add_co_u32_e32 v8, vcc, s68, v6
	s_add_u32 s18, s22, s5
	s_nop 0
	v_addc_co_u32_e32 v9, vcc, 0, v7, vcc
	v_add_co_u32_e32 v10, vcc, s37, v6
	s_addc_u32 s19, s23, 0
	s_nop 0
	v_addc_co_u32_e32 v11, vcc, 0, v7, vcc
	v_add_co_u32_e32 v6, vcc, s69, v6
	global_load_dword v85, v[12:13], off offset:2048 nt
	s_nop 0
	global_load_dword v12, v[12:13], off offset:3072 nt
	s_nop 0
	global_load_dword v13, v[8:9], off offset:1024 nt
	global_load_dword v87, v[8:9], off offset:2048 nt
	s_nop 0
	global_load_dword v8, v[8:9], off offset:3072 nt
	s_nop 0
	global_load_dword v9, v[14:15], off offset:1024 nt
	global_load_dword v88, v[14:15], off offset:2048 nt
	s_nop 0
	global_load_dword v14, v[14:15], off offset:3072 nt
	s_nop 0
	global_load_dword v15, v[10:11], off offset:-4096 nt
	global_load_dword v89, v[10:11], off nt
	global_load_dword v90, v[10:11], off offset:1024 nt
	global_load_dword v91, v[10:11], off offset:2048 nt
	s_nop 0
	global_load_dword v10, v[10:11], off offset:3072 nt
	v_addc_co_u32_e32 v7, vcc, 0, v7, vcc
	global_load_dword v11, v[6:7], off nt
	global_load_dword v92, v[6:7], off offset:1024 nt
	global_load_dword v93, v[6:7], off offset:2048 nt
	s_nop 0
	global_load_dword v6, v[6:7], off offset:3072 nt
	v_add_u32_e32 v7, 0x400, v27
	s_waitcnt vmcnt(30)
	ds_write2_b32 v27, v4, v16 offset1:66
	s_waitcnt vmcnt(28)
	ds_write2_b32 v27, v17, v18 offset0:132 offset1:198
	s_waitcnt vmcnt(23)
	ds_write2_b32 v7, v23, v19 offset0:8 offset1:74
	ds_write2_b32 v7, v20, v21 offset0:140 offset1:206
	s_waitcnt vmcnt(21)
	ds_write2_b32 v94, v24, v25 offset0:16 offset1:82
	s_waitcnt vmcnt(19)
	ds_write2_b32 v94, v81, v82 offset0:148 offset1:214
	s_waitcnt vmcnt(18)
	ds_write2_b32 v95, v83, v22 offset0:24 offset1:90
	s_waitcnt vmcnt(15)
	ds_write2_b32 v95, v85, v12 offset0:156 offset1:222
	s_waitcnt vmcnt(11)
	ds_write2_b32 v96, v84, v9 offset0:32 offset1:98
	s_waitcnt vmcnt(9)
	ds_write2_b32 v96, v88, v14 offset0:164 offset1:230
	v_add_u32_e32 v4, 0x1400, v27
	s_waitcnt vmcnt(8)
	ds_write2_b32 v4, v15, v13 offset0:40 offset1:106
	ds_write2_b32 v4, v87, v8 offset0:172 offset1:238
	v_add_u32_e32 v4, 0x1800, v27
	s_waitcnt vmcnt(6)
	ds_write2_b32 v4, v89, v90 offset0:48 offset1:114
	s_waitcnt vmcnt(4)
	ds_write2_b32 v4, v91, v10 offset0:180 offset1:246
	v_add_u32_e32 v4, 0x1c00, v27
	s_waitcnt vmcnt(2)
	ds_write2_b32 v4, v11, v92 offset0:56 offset1:122
	s_waitcnt vmcnt(0)
	ds_write2_b32 v4, v93, v6 offset0:188 offset1:254
	s_waitcnt lgkmcnt(0)
	ds_read2_b32 v[6:7], v29 offset1:33
	v_lshlrev_b32_e32 v4, 1, v2
	s_waitcnt lgkmcnt(0)
	v_cvt_pk_bf16_f32 v6, v6, v7
	ds_read2_b32 v[8:9], v29 offset0:66 offset1:99
	v_lshl_add_u64 v[12:13], s[18:19], 0, v[4:5]
	v_or_b32_e32 v4, s4, v28
	s_waitcnt lgkmcnt(0)
	v_cvt_pk_bf16_f32 v7, v8, v9
	ds_read2_b32 v[8:9], v29 offset0:132 offset1:165
	v_lshl_add_u64 v[12:13], v[12:13], 0, s[12:13]
	v_lshlrev_b32_e32 v4, 8, v4
	s_waitcnt lgkmcnt(0)
	v_cvt_pk_bf16_f32 v8, v8, v9
	ds_read2_b32 v[10:11], v29 offset0:198 offset1:231
	s_waitcnt lgkmcnt(0)
	v_cvt_pk_bf16_f32 v9, v10, v11
	v_lshl_add_u64 v[14:15], v[12:13], 0, v[4:5]
	ds_read2_b32 v[10:11], v29 offset0:8 offset1:41
	global_store_dwordx4 v[14:15], v[6:9], off nt
	v_or_b32_e32 v4, s4, v30
	v_lshlrev_b32_e32 v4, 8, v4
	s_waitcnt lgkmcnt(0)
	v_cvt_pk_bf16_f32 v6, v10, v11
	ds_read2_b32 v[8:9], v29 offset0:74 offset1:107
	s_waitcnt lgkmcnt(0)
	v_cvt_pk_bf16_f32 v7, v8, v9
	ds_read2_b32 v[8:9], v29 offset0:140 offset1:173
	s_waitcnt lgkmcnt(0)
	v_cvt_pk_bf16_f32 v8, v8, v9
	ds_read2_b32 v[10:11], v29 offset0:206 offset1:239
	s_waitcnt lgkmcnt(0)
	v_cvt_pk_bf16_f32 v9, v10, v11
	v_lshl_add_u64 v[14:15], v[12:13], 0, v[4:5]
	ds_read2_b32 v[10:11], v29 offset0:16 offset1:49
	global_store_dwordx4 v[14:15], v[6:9], off nt
	v_or_b32_e32 v4, s4, v31
	v_lshlrev_b32_e32 v4, 8, v4
	s_waitcnt lgkmcnt(0)
	v_cvt_pk_bf16_f32 v6, v10, v11
	ds_read2_b32 v[8:9], v29 offset0:82 offset1:115
	s_waitcnt lgkmcnt(0)
	v_cvt_pk_bf16_f32 v7, v8, v9
	ds_read2_b32 v[8:9], v29 offset0:148 offset1:181
	s_waitcnt lgkmcnt(0)
	v_cvt_pk_bf16_f32 v8, v8, v9
	ds_read2_b32 v[10:11], v29 offset0:214 offset1:247
	s_waitcnt lgkmcnt(0)
	v_cvt_pk_bf16_f32 v9, v10, v11
	v_lshl_add_u64 v[14:15], v[12:13], 0, v[4:5]
	ds_read2_b32 v[10:11], v29 offset0:24 offset1:57
	global_store_dwordx4 v[14:15], v[6:9], off nt
	v_or_b32_e32 v4, s4, v32
	v_lshlrev_b32_e32 v4, 8, v4
	s_waitcnt lgkmcnt(0)
	v_cvt_pk_bf16_f32 v6, v10, v11
	ds_read2_b32 v[8:9], v29 offset0:90 offset1:123
	s_waitcnt lgkmcnt(0)
	v_cvt_pk_bf16_f32 v7, v8, v9
	ds_read2_b32 v[8:9], v29 offset0:156 offset1:189
	s_waitcnt lgkmcnt(0)
	v_cvt_pk_bf16_f32 v8, v8, v9
	ds_read2_b32 v[10:11], v29 offset0:222 offset1:255
	s_waitcnt lgkmcnt(0)
	v_cvt_pk_bf16_f32 v9, v10, v11
	v_lshl_add_u64 v[10:11], v[12:13], 0, v[4:5]
	global_store_dwordx4 v[10:11], v[6:9], off nt
	s_waitcnt lgkmcnt(0)

.LBB0_121:
	s_lshl_b32 s4, s8, 5
	s_waitcnt vmcnt(4)
	ds_write2_b32 v10, v8, v9 offset0:140 offset1:206
	s_lshl_b32 s5, s72, 1
	s_and_b32 s8, 0xffff, s4
	s_waitcnt lgkmcnt(0)
	s_waitcnt lgkmcnt(0)
	s_add_u32 s4, s18, s5
	s_waitcnt vmcnt(0)
	ds_read2_b32 v[6:7], v29 offset1:33
	v_lshlrev_b32_e32 v4, 1, v2
	s_addc_u32 s5, s19, 0
	s_waitcnt lgkmcnt(0)
	v_cvt_pk_bf16_f32 v6, v6, v7
	ds_read2_b32 v[8:9], v29 offset0:66 offset1:99
	v_or_b32_e32 v14, s8, v28
	v_lshl_add_u64 v[12:13], s[4:5], 0, v[4:5]
	s_waitcnt lgkmcnt(0)
	v_cvt_pk_bf16_f32 v7, v8, v9
	ds_read2_b32 v[8:9], v29 offset0:132 offset1:165
	v_lshlrev_b32_e32 v4, 11, v14
	v_lshl_add_u64 v[12:13], v[12:13], 0, s[14:15]
	s_waitcnt lgkmcnt(0)
	v_cvt_pk_bf16_f32 v8, v8, v9
	ds_read2_b32 v[10:11], v29 offset0:198 offset1:231
	s_waitcnt lgkmcnt(0)
	v_cvt_pk_bf16_f32 v9, v10, v11
	v_lshl_add_u64 v[14:15], v[12:13], 0, v[4:5]
	ds_read2_b32 v[10:11], v29 offset0:8 offset1:41
	global_store_dwordx4 v[14:15], v[6:9], off nt
	v_or_b32_e32 v4, s8, v30
	v_lshlrev_b32_e32 v4, 11, v4
	s_waitcnt lgkmcnt(0)
	v_cvt_pk_bf16_f32 v6, v10, v11
	ds_read2_b32 v[8:9], v29 offset0:74 offset1:107
	s_waitcnt lgkmcnt(0)
	v_cvt_pk_bf16_f32 v7, v8, v9
	ds_read2_b32 v[8:9], v29 offset0:140 offset1:173
	s_waitcnt lgkmcnt(0)
	v_cvt_pk_bf16_f32 v8, v8, v9
	ds_read2_b32 v[10:11], v29 offset0:206 offset1:239
	s_waitcnt lgkmcnt(0)
	v_cvt_pk_bf16_f32 v9, v10, v11
	v_lshl_add_u64 v[14:15], v[12:13], 0, v[4:5]
	ds_read2_b32 v[10:11], v29 offset0:16 offset1:49
	global_store_dwordx4 v[14:15], v[6:9], off nt
	v_or_b32_e32 v4, s8, v31
	v_lshlrev_b32_e32 v4, 11, v4
	s_waitcnt lgkmcnt(0)
	v_cvt_pk_bf16_f32 v6, v10, v11
	ds_read2_b32 v[8:9], v29 offset0:82 offset1:115
	s_waitcnt lgkmcnt(0)
	v_cvt_pk_bf16_f32 v7, v8, v9
	ds_read2_b32 v[8:9], v29 offset0:148 offset1:181
	s_waitcnt lgkmcnt(0)
	v_cvt_pk_bf16_f32 v8, v8, v9
	ds_read2_b32 v[10:11], v29 offset0:214 offset1:247
	s_waitcnt lgkmcnt(0)
	v_cvt_pk_bf16_f32 v9, v10, v11
	v_lshl_add_u64 v[14:15], v[12:13], 0, v[4:5]
	ds_read2_b32 v[10:11], v29 offset0:24 offset1:57
	global_store_dwordx4 v[14:15], v[6:9], off nt
	v_or_b32_e32 v4, s8, v32
	v_lshlrev_b32_e32 v4, 11, v4
	s_waitcnt lgkmcnt(0)
	v_cvt_pk_bf16_f32 v6, v10, v11
	ds_read2_b32 v[8:9], v29 offset0:90 offset1:123
	s_waitcnt lgkmcnt(0)
	v_cvt_pk_bf16_f32 v7, v8, v9
	ds_read2_b32 v[8:9], v29 offset0:156 offset1:189
	s_waitcnt lgkmcnt(0)
	v_cvt_pk_bf16_f32 v8, v8, v9
	ds_read2_b32 v[10:11], v29 offset0:222 offset1:255
	s_waitcnt lgkmcnt(0)
	v_cvt_pk_bf16_f32 v9, v10, v11
	v_lshl_add_u64 v[10:11], v[12:13], 0, v[4:5]
	global_store_dwordx4 v[10:11], v[6:9], off nt
	s_waitcnt lgkmcnt(0)

.LBB0_123:
	s_andn2_b64 vcc, exec, s[4:5]
	s_cbranch_vccnz .LBB0_20
	s_ashr_i32 s4, s38, 31
	s_lshr_b32 s4, s4, 24
	s_add_i32 s4, s38, s4
	s_ashr_i32 s18, s4, 8
	s_and_b32 s4, s4, 0xff00
	s_sub_i32 s8, s38, s4
	s_sext_i32_i16 s4, s8
	s_bfe_u32 s4, s4, 0x4001b
	s_add_i32 s4, s8, s4
	v_mov_b32_e32 v4, s0
	v_mov_b32_e32 v6, s1
	s_sext_i32_i16 s22, s4
	s_and_b32 s19, s4, 0xfff0
	s_sub_i32 s8, s8, s19
	v_readfirstlane_b32 s4, v4
	v_readfirstlane_b32 s5, v6
	s_load_dwordx2 s[4:5], s[4:5], 0x38
	s_ashr_i32 s19, s18, 31
	s_lshl_b64 s[20:21], s[18:19], 21
	s_sext_i32_i16 s8, s8
	v_lshlrev_b32_e32 v4, 2, v0
	s_waitcnt lgkmcnt(0)
	s_add_u32 s23, s4, s20
	s_addc_u32 s5, s5, s21
	s_lshl_b32 s4, s22, 2
	s_lshl_b32 s20, s8, 5
	s_andn2_b32 s4, s4, 63
	s_lshl_b32 s8, s18, 9
	s_ashr_i32 s21, s20, 31
	s_add_i32 s8, s20, s8
	v_or_b32_e32 v6, s4, v3
	s_lshl_b64 s[18:19], s[20:21], 2
	s_add_u32 s18, s23, s18
	v_or_b32_e32 v12, 2, v6
	v_or_b32_e32 v14, 4, v6
	v_or_b32_e32 v16, 6, v6
	v_or_b32_e32 v18, 8, v6
	v_or_b32_e32 v20, 10, v6
	v_or_b32_e32 v22, 12, v6
	v_or_b32_e32 v24, 14, v6
	s_addc_u32 s19, s5, s19
	v_ashrrev_i32_e32 v7, 31, v6
	v_ashrrev_i32_e32 v13, 31, v12
	v_ashrrev_i32_e32 v15, 31, v14
	v_ashrrev_i32_e32 v17, 31, v16
	v_ashrrev_i32_e32 v19, 31, v18
	v_ashrrev_i32_e32 v21, 31, v20
	v_ashrrev_i32_e32 v23, 31, v22
	v_ashrrev_i32_e32 v25, 31, v24
	v_lshl_add_u64 v[8:9], s[18:19], 0, v[4:5]
	v_lshlrev_b64 v[10:11], 11, v[6:7]
	v_lshlrev_b64 v[12:13], 11, v[12:13]
	v_lshlrev_b64 v[14:15], 11, v[14:15]
	v_lshlrev_b64 v[16:17], 11, v[16:17]
	v_lshlrev_b64 v[18:19], 11, v[18:19]
	v_lshlrev_b64 v[20:21], 11, v[20:21]
	v_lshlrev_b64 v[22:23], 11, v[22:23]
	v_lshlrev_b64 v[24:25], 11, v[24:25]
	v_mov_b32_e32 v81, s0
	v_mov_b32_e32 v82, s1
	v_lshl_add_u64 v[10:11], v[8:9], 0, v[10:11]
	v_lshl_add_u64 v[12:13], v[8:9], 0, v[12:13]
	v_lshl_add_u64 v[14:15], v[8:9], 0, v[14:15]
	v_lshl_add_u64 v[16:17], v[8:9], 0, v[16:17]
	v_lshl_add_u64 v[18:19], v[8:9], 0, v[18:19]
	v_lshl_add_u64 v[20:21], v[8:9], 0, v[20:21]
	v_lshl_add_u64 v[22:23], v[8:9], 0, v[22:23]
	v_lshl_add_u64 v[24:25], v[8:9], 0, v[24:25]
	global_load_dword v4, v[10:11], off nt
	global_load_dword v83, v[12:13], off nt
	global_load_dword v84, v[14:15], off nt
	global_load_dword v85, v[16:17], off nt
	global_load_dword v87, v[18:19], off nt
	global_load_dword v88, v[20:21], off nt
	global_load_dword v89, v[22:23], off nt
	global_load_dword v90, v[24:25], off nt
	v_or_b32_e32 v10, 16, v6
	v_or_b32_e32 v12, 18, v6
	v_or_b32_e32 v14, 20, v6
	v_or_b32_e32 v16, 22, v6
	v_or_b32_e32 v18, 24, v6
	v_or_b32_e32 v20, 26, v6
	v_or_b32_e32 v22, 28, v6
	v_or_b32_e32 v24, 30, v6
	v_ashrrev_i32_e32 v11, 31, v10
	v_ashrrev_i32_e32 v13, 31, v12
	v_ashrrev_i32_e32 v15, 31, v14
	v_ashrrev_i32_e32 v17, 31, v16
	v_ashrrev_i32_e32 v19, 31, v18
	v_ashrrev_i32_e32 v21, 31, v20
	v_ashrrev_i32_e32 v23, 31, v22
	v_ashrrev_i32_e32 v25, 31, v24
	v_lshlrev_b64 v[10:11], 11, v[10:11]
	v_lshlrev_b64 v[12:13], 11, v[12:13]
	v_lshlrev_b64 v[14:15], 11, v[14:15]
	v_lshlrev_b64 v[16:17], 11, v[16:17]
	v_lshlrev_b64 v[18:19], 11, v[18:19]
	v_lshlrev_b64 v[20:21], 11, v[20:21]
	v_lshlrev_b64 v[22:23], 11, v[22:23]
	v_lshlrev_b64 v[24:25], 11, v[24:25]
	v_lshl_add_u64 v[10:11], v[8:9], 0, v[10:11]
	v_lshl_add_u64 v[12:13], v[8:9], 0, v[12:13]
	v_lshl_add_u64 v[14:15], v[8:9], 0, v[14:15]
	v_lshl_add_u64 v[16:17], v[8:9], 0, v[16:17]
	v_lshl_add_u64 v[18:19], v[8:9], 0, v[18:19]
	v_lshl_add_u64 v[20:21], v[8:9], 0, v[20:21]
	v_lshl_add_u64 v[22:23], v[8:9], 0, v[22:23]
	v_lshl_add_u64 v[24:25], v[8:9], 0, v[24:25]
	global_load_dword v91, v[10:11], off nt
	global_load_dword v92, v[12:13], off nt
	global_load_dword v93, v[14:15], off nt
	global_load_dword v94, v[16:17], off nt
	global_load_dword v95, v[18:19], off nt
	global_load_dword v96, v[20:21], off nt
	global_load_dword v97, v[22:23], off nt
	global_load_dword v98, v[24:25], off nt
	v_or_b32_e32 v10, 32, v6
	v_or_b32_e32 v12, 34, v6
	v_or_b32_e32 v14, 36, v6
	v_or_b32_e32 v16, 38, v6
	v_or_b32_e32 v18, 40, v6
	v_or_b32_e32 v20, 42, v6
	v_or_b32_e32 v22, 44, v6
	v_or_b32_e32 v24, 46, v6
	v_ashrrev_i32_e32 v11, 31, v10
	v_ashrrev_i32_e32 v13, 31, v12
	v_ashrrev_i32_e32 v15, 31, v14
	v_ashrrev_i32_e32 v17, 31, v16
	v_ashrrev_i32_e32 v19, 31, v18
	v_ashrrev_i32_e32 v21, 31, v20
	v_ashrrev_i32_e32 v23, 31, v22
	v_ashrrev_i32_e32 v25, 31, v24
	v_lshlrev_b64 v[10:11], 11, v[10:11]
	v_lshlrev_b64 v[12:13], 11, v[12:13]
	v_lshlrev_b64 v[14:15], 11, v[14:15]
	v_lshlrev_b64 v[16:17], 11, v[16:17]
	v_lshlrev_b64 v[18:19], 11, v[18:19]
	v_lshlrev_b64 v[20:21], 11, v[20:21]
	v_lshlrev_b64 v[22:23], 11, v[22:23]
	v_lshlrev_b64 v[24:25], 11, v[24:25]
	v_lshl_add_u64 v[10:11], v[8:9], 0, v[10:11]
	v_lshl_add_u64 v[12:13], v[8:9], 0, v[12:13]
	v_lshl_add_u64 v[14:15], v[8:9], 0, v[14:15]
	v_lshl_add_u64 v[16:17], v[8:9], 0, v[16:17]
	v_lshl_add_u64 v[18:19], v[8:9], 0, v[18:19]
	v_lshl_add_u64 v[20:21], v[8:9], 0, v[20:21]
	v_lshl_add_u64 v[22:23], v[8:9], 0, v[22:23]
	v_lshl_add_u64 v[24:25], v[8:9], 0, v[24:25]
	global_load_dword v99, v[10:11], off nt
	global_load_dword v100, v[12:13], off nt
	global_load_dword v101, v[14:15], off nt
	global_load_dword v102, v[16:17], off nt
	global_load_dword v103, v[18:19], off nt
	global_load_dword v104, v[20:21], off nt
	global_load_dword v105, v[22:23], off nt
	s_nop 0
	global_load_dword v24, v[24:25], off nt
	v_or_b32_e32 v10, 48, v6
	v_or_b32_e32 v12, 50, v6
	v_or_b32_e32 v14, 52, v6
	v_or_b32_e32 v16, 54, v6
	v_or_b32_e32 v18, 56, v6
	v_or_b32_e32 v20, 58, v6
	v_or_b32_e32 v22, 60, v6
	v_or_b32_e32 v6, 62, v6
	v_ashrrev_i32_e32 v11, 31, v10
	v_ashrrev_i32_e32 v13, 31, v12
	v_ashrrev_i32_e32 v15, 31, v14
	v_ashrrev_i32_e32 v7, 31, v6
	v_lshlrev_b64 v[10:11], 11, v[10:11]
	v_lshlrev_b64 v[12:13], 11, v[12:13]
	v_lshlrev_b64 v[14:15], 11, v[14:15]
	v_ashrrev_i32_e32 v17, 31, v16
	v_ashrrev_i32_e32 v19, 31, v18
	v_ashrrev_i32_e32 v21, 31, v20
	v_ashrrev_i32_e32 v23, 31, v22
	v_lshlrev_b64 v[6:7], 11, v[6:7]
	v_lshl_add_u64 v[10:11], v[8:9], 0, v[10:11]
	v_lshl_add_u64 v[12:13], v[8:9], 0, v[12:13]
	v_lshl_add_u64 v[14:15], v[8:9], 0, v[14:15]
	v_lshlrev_b64 v[16:17], 11, v[16:17]
	v_lshlrev_b64 v[18:19], 11, v[18:19]
	v_lshlrev_b64 v[20:21], 11, v[20:21]
	v_lshlrev_b64 v[22:23], 11, v[22:23]
	v_lshl_add_u64 v[6:7], v[8:9], 0, v[6:7]
	v_lshl_add_u64 v[16:17], v[8:9], 0, v[16:17]
	v_lshl_add_u64 v[18:19], v[8:9], 0, v[18:19]
	v_lshl_add_u64 v[20:21], v[8:9], 0, v[20:21]
	v_lshl_add_u64 v[22:23], v[8:9], 0, v[22:23]
	global_load_dword v8, v[10:11], off nt
	global_load_dword v9, v[12:13], off nt
	s_nop 0
	global_load_dword v10, v[14:15], off nt
	global_load_dword v11, v[16:17], off nt
	global_load_dword v12, v[18:19], off nt
	global_load_dword v13, v[20:21], off nt
	s_nop 0
	global_load_dword v14, v[22:23], off nt
	s_nop 0
	global_load_dword v6, v[6:7], off nt
	v_readfirstlane_b32 s18, v81
	v_readfirstlane_b32 s19, v82
	s_load_dwordx2 s[18:19], s[18:19], 0xc0
	s_waitcnt vmcnt(30)
	ds_write2_b32 v27, v4, v83 offset1:66
	s_waitcnt vmcnt(28)
	ds_write2_b32 v27, v84, v85 offset0:132 offset1:198
	v_add_u32_e32 v4, 0x400, v27
	s_waitcnt vmcnt(26)
	ds_write2_b32 v4, v87, v88 offset0:8 offset1:74
	s_waitcnt vmcnt(24)
	ds_write2_b32 v4, v89, v90 offset0:140 offset1:206
	v_add_u32_e32 v4, 0x800, v27
	s_waitcnt vmcnt(22)
	ds_write2_b32 v4, v91, v92 offset0:16 offset1:82
	s_waitcnt vmcnt(20)
	ds_write2_b32 v4, v93, v94 offset0:148 offset1:214
	v_add_u32_e32 v4, 0xc00, v27
	s_waitcnt vmcnt(18)
	ds_write2_b32 v4, v95, v96 offset0:24 offset1:90
	s_waitcnt vmcnt(16)
	ds_write2_b32 v4, v97, v98 offset0:156 offset1:222
	v_add_u32_e32 v4, 0x1000, v27
	s_waitcnt vmcnt(14)
	ds_write2_b32 v4, v99, v100 offset0:32 offset1:98
	s_waitcnt vmcnt(12)
	ds_write2_b32 v4, v101, v102 offset0:164 offset1:230
	v_add_u32_e32 v4, 0x1400, v27
	s_waitcnt vmcnt(10)
	ds_write2_b32 v4, v103, v104 offset0:40 offset1:106
	s_waitcnt vmcnt(8)
	ds_write2_b32 v4, v105, v24 offset0:172 offset1:238
	v_add_u32_e32 v4, 0x1800, v27
	s_waitcnt vmcnt(6)
	ds_write2_b32 v4, v8, v9 offset0:48 offset1:114
	s_waitcnt vmcnt(4)
	ds_write2_b32 v4, v10, v11 offset0:180 offset1:246
	v_add_u32_e32 v4, 0x1c00, v27
	s_waitcnt vmcnt(2)
	ds_write2_b32 v4, v12, v13 offset0:56 offset1:122
	s_waitcnt vmcnt(0)
	ds_write2_b32 v4, v14, v6 offset0:188 offset1:254
	s_waitcnt lgkmcnt(0)
	ds_read2_b32 v[6:7], v29 offset1:33
	s_waitcnt lgkmcnt(0)
	v_cvt_pk_bf16_f32 v6, v6, v7
	ds_read2_b32 v[8:9], v29 offset0:66 offset1:99
	s_ashr_i32 s5, s4, 31
	s_waitcnt lgkmcnt(0)
	v_cvt_pk_bf16_f32 v7, v8, v9
	ds_read2_b32 v[8:9], v29 offset0:132 offset1:165
	s_lshl_b64 s[4:5], s[4:5], 1
	s_add_u32 s4, s18, s4
	s_waitcnt lgkmcnt(0)
	v_cvt_pk_bf16_f32 v8, v8, v9
	ds_read2_b32 v[10:11], v29 offset0:198 offset1:231
	s_addc_u32 s5, s19, s5
	v_lshlrev_b32_e32 v4, 1, v2
	s_waitcnt lgkmcnt(0)
	v_cvt_pk_bf16_f32 v9, v10, v11
	v_or_b32_e32 v10, s8, v28
	v_lshl_add_u64 v[12:13], s[4:5], 0, v[4:5]
	v_ashrrev_i32_e32 v11, 31, v10
	v_lshl_add_u64 v[12:13], v[12:13], 0, s[16:17]
	v_lshlrev_b64 v[10:11], 11, v[10:11]
	v_lshl_add_u64 v[10:11], v[12:13], 0, v[10:11]
	ds_read2_b32 v[14:15], v29 offset0:8 offset1:41
	global_store_dwordx4 v[10:11], v[6:9], off nt
	s_waitcnt lgkmcnt(0)
	s_nop 0
	v_cvt_pk_bf16_f32 v6, v14, v15
	ds_read2_b32 v[8:9], v29 offset0:74 offset1:107
	s_waitcnt lgkmcnt(0)
	v_cvt_pk_bf16_f32 v7, v8, v9
	ds_read2_b32 v[8:9], v29 offset0:140 offset1:173
	s_waitcnt lgkmcnt(0)
	v_cvt_pk_bf16_f32 v8, v8, v9
	ds_read2_b32 v[10:11], v29 offset0:206 offset1:239
	s_waitcnt lgkmcnt(0)
	v_cvt_pk_bf16_f32 v9, v10, v11
	v_or_b32_e32 v10, s8, v30
	v_ashrrev_i32_e32 v11, 31, v10
	v_lshlrev_b64 v[10:11], 11, v[10:11]
	v_lshl_add_u64 v[10:11], v[12:13], 0, v[10:11]
	ds_read2_b32 v[14:15], v29 offset0:16 offset1:49
	global_store_dwordx4 v[10:11], v[6:9], off nt
	s_waitcnt lgkmcnt(0)
	s_nop 0
	v_cvt_pk_bf16_f32 v6, v14, v15
	ds_read2_b32 v[8:9], v29 offset0:82 offset1:115
	s_waitcnt lgkmcnt(0)
	v_cvt_pk_bf16_f32 v7, v8, v9
	ds_read2_b32 v[8:9], v29 offset0:148 offset1:181
	s_waitcnt lgkmcnt(0)
	v_cvt_pk_bf16_f32 v8, v8, v9
	ds_read2_b32 v[10:11], v29 offset0:214 offset1:247
	s_waitcnt lgkmcnt(0)
	v_cvt_pk_bf16_f32 v9, v10, v11
	v_or_b32_e32 v10, s8, v31
	v_ashrrev_i32_e32 v11, 31, v10
	v_lshlrev_b64 v[10:11], 11, v[10:11]
	v_lshl_add_u64 v[10:11], v[12:13], 0, v[10:11]
	ds_read2_b32 v[14:15], v29 offset0:24 offset1:57
	global_store_dwordx4 v[10:11], v[6:9], off nt
	s_waitcnt lgkmcnt(0)
	s_nop 0
	v_cvt_pk_bf16_f32 v6, v14, v15
	ds_read2_b32 v[8:9], v29 offset0:90 offset1:123
	s_waitcnt lgkmcnt(0)
	v_cvt_pk_bf16_f32 v7, v8, v9
	ds_read2_b32 v[8:9], v29 offset0:156 offset1:189
	s_waitcnt lgkmcnt(0)
	v_cvt_pk_bf16_f32 v8, v8, v9
	ds_read2_b32 v[10:11], v29 offset0:222 offset1:255
	s_waitcnt lgkmcnt(0)
	v_cvt_pk_bf16_f32 v9, v10, v11
	v_or_b32_e32 v10, s8, v32
	v_ashrrev_i32_e32 v11, 31, v10
	v_lshlrev_b64 v[10:11], 11, v[10:11]
	v_lshl_add_u64 v[10:11], v[12:13], 0, v[10:11]
	global_store_dwordx4 v[10:11], v[6:9], off nt
	s_waitcnt lgkmcnt(0)
	s_branch .LBB0_20

.LBB0_480:
	s_or_b64 exec, exec, s[18:19]
	v_mov_b32_e32 v34, s0
	v_mov_b32_e32 v35, s1
	v_lshlrev_b64 v[110:111], 1, v[32:33]
	v_readfirstlane_b32 s16, v34
	v_readfirstlane_b32 s17, v35
	s_load_dwordx2 s[16:17], s[16:17], 0xc0
	v_or_b32_e32 v150, 1, v149
	v_or_b32_e32 v148, 2, v149
	v_or_b32_e32 v147, 3, v149
	v_or_b32_e32 v146, 4, v149
	s_waitcnt lgkmcnt(0)
	v_mov_b64_e32 v[34:35], s[16:17]
	v_mad_i64_i32 v[34:35], s[16:17], v149, s24, v[34:35]
	v_lshl_add_u64 v[32:33], v[34:35], 0, v[110:111]
	v_add_co_u32_e32 v32, vcc, s25, v32
	v_or_b32_e32 v145, 5, v149
	s_nop 0
	v_addc_co_u32_e32 v33, vcc, 0, v33, vcc
	global_load_dwordx4 v[104:107], v[32:33], off nt
	v_mov_b32_e32 v32, s0
	v_mov_b32_e32 v33, s1
	v_or_b32_e32 v144, 6, v149
	v_readfirstlane_b32 s16, v32
	v_readfirstlane_b32 s17, v33
	s_load_dwordx2 s[16:17], s[16:17], 0xc0
	v_or_b32_e32 v143, 7, v149
	v_or_b32_e32 v142, 8, v149
	v_or_b32_e32 v141, 9, v149
	v_or_b32_e32 v140, 10, v149
	s_waitcnt lgkmcnt(0)
	v_mov_b64_e32 v[32:33], s[16:17]
	v_mad_i64_i32 v[32:33], s[16:17], v150, s24, v[32:33]
	v_lshl_add_u64 v[32:33], v[32:33], 0, v[110:111]
	v_add_co_u32_e32 v32, vcc, s25, v32
	s_waitcnt vmcnt(1)
	v_lshlrev_b32_e32 v117, 16, v28
	v_addc_co_u32_e32 v33, vcc, 0, v33, vcc
	global_load_dwordx4 v[84:87], v[32:33], off nt
	v_mov_b32_e32 v32, s0
	v_mov_b32_e32 v33, s1
	v_and_b32_e32 v125, 0xffff0000, v28
	v_readfirstlane_b32 s16, v32
	v_readfirstlane_b32 s17, v33
	s_load_dwordx2 s[16:17], s[16:17], 0xc0
	v_lshlrev_b32_e32 v121, 16, v29
	v_and_b32_e32 v119, 0xffff0000, v29
	v_or_b32_e32 v139, 11, v149
	v_lshlrev_b32_e32 v116, 16, v24
	s_waitcnt lgkmcnt(0)
	v_mov_b64_e32 v[32:33], s[16:17]
	v_mad_i64_i32 v[32:33], s[16:17], v148, s24, v[32:33]
	v_lshl_add_u64 v[32:33], v[32:33], 0, v[110:111]
	v_add_co_u32_e32 v32, vcc, s25, v32
	v_mov_b32_e32 v112, v96
	s_nop 0
	v_addc_co_u32_e32 v33, vcc, 0, v33, vcc
	global_load_dwordx4 v[88:91], v[32:33], off nt
	v_mov_b32_e32 v32, s0
	v_mov_b32_e32 v33, s1
	v_mov_b32_e32 v113, v12
	v_readfirstlane_b32 s16, v32
	v_readfirstlane_b32 s17, v33
	s_load_dwordx2 s[16:17], s[16:17], 0xc0
	v_pk_mul_f32 v[114:115], v[112:113], v[116:117]
	v_lshlrev_b32_e32 v152, 16, v100
	v_add_f32_e32 v12, v20, v114
	v_add_f32_e32 v12, v12, v115
	s_waitcnt lgkmcnt(0)
	v_mov_b64_e32 v[32:33], s[16:17]
	v_mad_i64_i32 v[32:33], s[16:17], v147, s24, v[32:33]
	v_lshl_add_u64 v[32:33], v[32:33], 0, v[110:111]
	v_add_co_u32_e32 v32, vcc, s25, v32
	v_mov_b32_e32 v114, v92
	s_nop 0
	v_addc_co_u32_e32 v33, vcc, 0, v33, vcc
	global_load_dwordx4 v[68:71], v[32:33], off nt
	v_mov_b32_e32 v32, s0
	v_mov_b32_e32 v33, s1
	v_mov_b32_e32 v115, v16
	v_readfirstlane_b32 s16, v32
	v_readfirstlane_b32 s17, v33
	s_load_dwordx2 s[16:17], s[16:17], 0xc0
	v_and_b32_e32 v124, 0xffff0000, v24
	v_or_b32_e32 v138, 12, v149
	v_lshlrev_b32_e32 v120, 16, v25
	v_lshlrev_b32_e32 v156, 16, v101
	s_waitcnt lgkmcnt(0)
	v_mov_b64_e32 v[32:33], s[16:17]
	v_mad_i64_i32 v[32:33], s[16:17], v146, s24, v[32:33]
	v_lshl_add_u64 v[32:33], v[32:33], 0, v[110:111]
	v_add_co_u32_e32 v32, vcc, s25, v32
	s_waitcnt vmcnt(3)
	v_lshlrev_b32_e32 v153, 16, v104
	v_addc_co_u32_e32 v33, vcc, 0, v33, vcc
	global_load_dwordx4 v[72:75], v[32:33], off nt
	v_mov_b32_e32 v32, s0
	v_mov_b32_e32 v33, s1
	v_pk_mul_f32 v[154:155], v[114:115], v[152:153]
	v_readfirstlane_b32 s16, v32
	v_readfirstlane_b32 s17, v33
	s_load_dwordx2 s[16:17], s[16:17], 0xc0
	v_add_f32_e32 v12, v12, v154
	v_add_f32_e32 v116, v12, v155
	v_mov_b32_e32 v12, v97
	v_pk_mul_f32 v[96:97], v[12:13], v[124:125]
	s_waitcnt lgkmcnt(0)
	v_mov_b64_e32 v[32:33], s[16:17]
	v_mad_i64_i32 v[32:33], s[16:17], v145, s24, v[32:33]
	v_lshl_add_u64 v[32:33], v[32:33], 0, v[110:111]
	v_add_co_u32_e32 v32, vcc, s25, v32
	v_add_f32_e32 v16, v21, v96
	s_nop 0
	v_addc_co_u32_e32 v33, vcc, 0, v33, vcc
	global_load_dwordx4 v[60:63], v[32:33], off nt
	v_mov_b32_e32 v32, s0
	v_mov_b32_e32 v33, s1
	v_add_f32_e32 v96, v16, v97
	v_readfirstlane_b32 s16, v32
	v_readfirstlane_b32 s17, v33
	s_load_dwordx2 s[16:17], s[16:17], 0xc0
	v_and_b32_e32 v155, 0xffff0000, v104
	v_and_b32_e32 v154, 0xffff0000, v100
	v_mov_b32_e32 v16, v93
	v_pk_mul_f32 v[92:93], v[16:17], v[154:155]
	s_waitcnt lgkmcnt(0)
	v_mov_b64_e32 v[32:33], s[16:17]
	v_mad_i64_i32 v[32:33], s[16:17], v144, s24, v[32:33]
	v_lshl_add_u64 v[32:33], v[32:33], 0, v[110:111]
	v_add_co_u32_e32 v32, vcc, s25, v32
	v_add_f32_e32 v92, v96, v92
	s_nop 0
	v_addc_co_u32_e32 v33, vcc, 0, v33, vcc
	global_load_dwordx4 v[64:67], v[32:33], off nt
	v_mov_b32_e32 v32, s0
	v_mov_b32_e32 v33, s1
	v_add_f32_e32 v124, v92, v93
	v_readfirstlane_b32 s16, v32
	v_readfirstlane_b32 s17, v33
	s_load_dwordx2 s[16:17], s[16:17], 0xc0
	v_mov_b32_e32 v92, v98
	v_mov_b32_e32 v93, v14
	v_pk_mul_f32 v[96:97], v[92:93], v[120:121]
	v_lshlrev_b32_e32 v157, 16, v105
	s_waitcnt lgkmcnt(0)
	v_mov_b64_e32 v[32:33], s[16:17]
	v_mad_i64_i32 v[32:33], s[16:17], v143, s24, v[32:33]
	v_lshl_add_u64 v[32:33], v[32:33], 0, v[110:111]
	v_add_co_u32_e32 v32, vcc, s25, v32
	v_add_f32_e32 v14, v22, v96
	s_nop 0
	v_addc_co_u32_e32 v33, vcc, 0, v33, vcc
	global_load_dwordx4 v[52:55], v[32:33], off nt
	v_mov_b32_e32 v32, s0
	v_mov_b32_e32 v33, s1
	v_add_f32_e32 v14, v14, v97
	v_readfirstlane_b32 s16, v32
	v_readfirstlane_b32 s17, v33
	s_load_dwordx2 s[16:17], s[16:17], 0xc0
	v_mov_b32_e32 v96, v94
	v_mov_b32_e32 v97, v18
	v_pk_mul_f32 v[158:159], v[96:97], v[156:157]
	v_and_b32_e32 v118, 0xffff0000, v25
	s_waitcnt lgkmcnt(0)
	v_mov_b64_e32 v[32:33], s[16:17]
	v_mad_i64_i32 v[32:33], s[16:17], v142, s24, v[32:33]
	v_lshl_add_u64 v[32:33], v[32:33], 0, v[110:111]
	v_add_co_u32_e32 v32, vcc, s25, v32
	v_add_f32_e32 v14, v14, v158
	s_nop 0
	v_addc_co_u32_e32 v33, vcc, 0, v33, vcc
	global_load_dwordx4 v[56:59], v[32:33], off nt
	v_mov_b32_e32 v32, s0
	v_mov_b32_e32 v33, s1
	v_add_f32_e32 v120, v14, v159
	v_readfirstlane_b32 s16, v32
	v_readfirstlane_b32 s17, v33
	s_load_dwordx2 s[16:17], s[16:17], 0xc0
	v_mov_b32_e32 v14, v99
	v_pk_mul_f32 v[98:99], v[14:15], v[118:119]
	v_or_b32_e32 v137, 13, v149
	v_add_f32_e32 v18, v23, v98
	s_waitcnt lgkmcnt(0)
	v_mov_b64_e32 v[32:33], s[16:17]
	v_mad_i64_i32 v[32:33], s[16:17], v141, s24, v[32:33]
	v_lshl_add_u64 v[32:33], v[32:33], 0, v[110:111]
	v_add_co_u32_e32 v32, vcc, s25, v32
	v_add_f32_e32 v98, v18, v99
	s_nop 0
	v_addc_co_u32_e32 v33, vcc, 0, v33, vcc
	global_load_dwordx4 v[44:47], v[32:33], off nt
	v_mov_b32_e32 v32, s0
	v_mov_b32_e32 v33, s1
	v_and_b32_e32 v105, 0xffff0000, v105
	v_readfirstlane_b32 s16, v32
	v_readfirstlane_b32 s17, v33
	s_load_dwordx2 s[16:17], s[16:17], 0xc0
	v_and_b32_e32 v104, 0xffff0000, v101
	v_mov_b32_e32 v18, v95
	v_pk_mul_f32 v[94:95], v[18:19], v[104:105]
	v_lshlrev_b32_e32 v129, 16, v30
	s_waitcnt lgkmcnt(0)
	v_mov_b64_e32 v[32:33], s[16:17]
	v_mad_i64_i32 v[32:33], s[16:17], v140, s24, v[32:33]
	v_lshl_add_u64 v[32:33], v[32:33], 0, v[110:111]
	v_add_co_u32_e32 v32, vcc, s25, v32
	v_add_f32_e32 v94, v98, v94
	s_nop 0
	v_addc_co_u32_e32 v33, vcc, 0, v33, vcc
	global_load_dwordx4 v[48:51], v[32:33], off nt
	v_mov_b32_e32 v32, s0
	v_mov_b32_e32 v33, s1
	v_lshlrev_b32_e32 v128, 16, v26
	v_readfirstlane_b32 s16, v32
	v_readfirstlane_b32 s17, v33
	s_load_dwordx2 s[16:17], s[16:17], 0xc0
	v_add_f32_e32 v118, v94, v95
	v_mov_b32_e32 v94, v80
	v_mov_b32_e32 v95, v0
	v_mov_b32_e32 v24, s0
	s_waitcnt lgkmcnt(0)
	v_mov_b64_e32 v[28:29], s[16:17]
	v_mad_i64_i32 v[28:29], s[16:17], v139, s24, v[28:29]
	v_lshl_add_u64 v[28:29], v[28:29], 0, v[110:111]
	v_add_co_u32_e32 v28, vcc, s25, v28
	v_mov_b32_e32 v32, s1
	s_nop 0
	v_addc_co_u32_e32 v29, vcc, 0, v29, vcc
	global_load_dwordx4 v[36:39], v[28:29], off nt
	v_mov_b32_e32 v28, s0
	v_mov_b32_e32 v29, s1
	v_pk_mul_f32 v[98:99], v[94:95], v[128:129]
	v_readfirstlane_b32 s16, v28
	v_readfirstlane_b32 s17, v29
	s_load_dwordx2 s[16:17], s[16:17], 0xc0
	v_and_b32_e32 v127, 0xffff0000, v30
	v_lshlrev_b32_e32 v123, 16, v31
	v_and_b32_e32 v131, 0xffff0000, v31
	v_add_f32_e32 v0, v8, v98
	s_waitcnt lgkmcnt(0)
	v_mov_b64_e32 v[28:29], s[16:17]
	v_mad_i64_i32 v[28:29], s[16:17], v138, s24, v[28:29]
	v_lshl_add_u64 v[28:29], v[28:29], 0, v[110:111]
	v_add_co_u32_e32 v28, vcc, s25, v28
	v_add_f32_e32 v0, v0, v99
	s_nop 0
	v_addc_co_u32_e32 v29, vcc, 0, v29, vcc
	global_load_dwordx4 v[40:43], v[28:29], off nt
	v_mov_b32_e32 v28, s0
	v_mov_b32_e32 v29, s1
	v_lshlrev_b32_e32 v159, 16, v106
	v_readfirstlane_b32 s16, v28
	v_readfirstlane_b32 s17, v29
	s_load_dwordx2 s[16:17], s[16:17], 0xc0
	v_lshlrev_b32_e32 v158, 16, v102
	v_mov_b32_e32 v98, v76
	v_mov_b32_e32 v99, v4
	v_pk_mul_f32 v[100:101], v[98:99], v[158:159]
	s_waitcnt lgkmcnt(0)
	v_mov_b64_e32 v[28:29], s[16:17]
	v_mad_i64_i32 v[28:29], s[16:17], v137, s24, v[28:29]
	v_lshl_add_u64 v[28:29], v[28:29], 0, v[110:111]
	v_add_co_u32_e32 v28, vcc, s25, v28
	v_add_f32_e32 v0, v0, v100
	s_nop 0
	v_addc_co_u32_e32 v29, vcc, 0, v29, vcc
	global_load_dwordx4 v[28:31], v[28:29], off nt
	v_and_b32_e32 v126, 0xffff0000, v26
	v_readfirstlane_b32 s16, v24
	v_readfirstlane_b32 s17, v32
	s_load_dwordx2 s[16:17], s[16:17], 0xc0
	v_add_f32_e32 v128, v0, v101
	v_mov_b32_e32 v0, v81
	v_pk_mul_f32 v[80:81], v[0:1], v[126:127]
	v_or_b32_e32 v136, 14, v149
	s_waitcnt lgkmcnt(0)
	v_mov_b64_e32 v[24:25], s[16:17]
	v_add_f32_e32 v4, v9, v80
	v_mad_i64_i32 v[24:25], s[16:17], v136, s24, v[24:25]
	v_add_f32_e32 v80, v4, v81
	v_and_b32_e32 v161, 0xffff0000, v106
	v_and_b32_e32 v160, 0xffff0000, v102
	v_mov_b32_e32 v4, v77
	v_lshl_add_u64 v[24:25], v[24:25], 0, v[110:111]
	v_pk_mul_f32 v[76:77], v[4:5], v[160:161]
	v_add_co_u32_e32 v24, vcc, s25, v24
	v_add_f32_e32 v76, v80, v76
	s_nop 0
	v_addc_co_u32_e32 v25, vcc, 0, v25, vcc
	v_lshlrev_b32_e32 v122, 16, v27
	v_add_f32_e32 v102, v76, v77
	v_mov_b32_e32 v76, v82
	v_mov_b32_e32 v77, v2
	global_load_dwordx4 v[32:35], v[24:25], off nt
	v_mov_b32_e32 v24, s0
	v_mov_b32_e32 v25, s1
	v_pk_mul_f32 v[80:81], v[76:77], v[122:123]
	v_lshlrev_b32_e32 v162, 16, v103
	v_readfirstlane_b32 s16, v24
	v_readfirstlane_b32 s17, v25
	v_add_f32_e32 v2, v10, v80
	s_load_dwordx2 s[16:17], s[16:17], 0xc0
	v_add_f32_e32 v2, v2, v81
	v_lshlrev_b32_e32 v163, 16, v107
	v_mov_b32_e32 v80, v78
	v_mov_b32_e32 v81, v6
	v_pk_mul_f32 v[100:101], v[80:81], v[162:163]
	v_and_b32_e32 v130, 0xffff0000, v27
	v_add_f32_e32 v2, v2, v100
	v_add_f32_e32 v122, v2, v101
	v_mov_b32_e32 v2, v83
	v_pk_mul_f32 v[82:83], v[2:3], v[130:131]
	v_or_b32_e32 v135, 15, v149
	s_waitcnt lgkmcnt(0)
	v_mov_b64_e32 v[24:25], s[16:17]
	v_add_f32_e32 v6, v11, v82
	v_mad_i64_i32 v[24:25], s[16:17], v135, s24, v[24:25]
	v_add_f32_e32 v82, v6, v83
	v_and_b32_e32 v107, 0xffff0000, v107
	v_and_b32_e32 v106, 0xffff0000, v103
	v_mov_b32_e32 v6, v79
	v_lshl_add_u64 v[24:25], v[24:25], 0, v[110:111]
	v_pk_mul_f32 v[78:79], v[6:7], v[106:107]
	v_add_co_u32_e32 v24, vcc, s25, v24
	v_add_f32_e32 v78, v82, v78
	s_nop 0
	v_addc_co_u32_e32 v25, vcc, 0, v25, vcc
	v_add_f32_e32 v78, v78, v79
	global_load_dwordx4 v[24:27], v[24:25], off nt
	v_cvt_pk_bf16_f32 v100, v116, v124
	v_cvt_pk_bf16_f32 v101, v120, v118
	v_cvt_pk_bf16_f32 v102, v128, v102
	v_cvt_pk_bf16_f32 v103, v122, v78
	v_mov_b32_e32 v78, s0
	v_mov_b32_e32 v79, s1
	v_mov_b32_e32 v133, s0
	v_readfirstlane_b32 s16, v78
	v_readfirstlane_b32 s17, v79
	s_load_dwordx2 s[16:17], s[16:17], 0xc0
	v_mov_b32_e32 v134, s1
	v_add_u32_e32 v109, s3, v109
	v_add_u32_e32 v108, s20, v108
	v_and_b32_e32 v242, s99, v254
	v_lshl_or_b32 v109, v242, 12, v109
	s_waitcnt lgkmcnt(0)
	v_mov_b64_e32 v[78:79], s[16:17]
	v_mad_i64_i32 v[78:79], s[16:17], v149, s24, v[78:79]
	v_lshl_add_u64 v[78:79], v[78:79], 0, v[110:111]
	v_add_co_u32_e32 v78, vcc, s26, v78
	s_nop 1
	v_addc_co_u32_e32 v79, vcc, 0, v79, vcc
	global_store_dwordx4 v[78:79], v[100:103], off sc1
	v_mov_b32_e32 v78, v117
	v_mov_b32_e32 v79, v152
	v_pk_mul_f32 v[78:79], v[112:113], v[78:79]
	s_nop 0
	v_add_f32_e32 v78, v20, v78
	v_add_f32_e32 v102, v78, v79
	v_mov_b32_e32 v78, v125
	v_mov_b32_e32 v79, v154
	v_pk_mul_f32 v[78:79], v[12:13], v[78:79]
	s_nop 0
	v_add_f32_e32 v78, v21, v78
	v_add_f32_e32 v118, v78, v79
	v_mov_b32_e32 v78, v121
	v_mov_b32_e32 v79, v156
	v_pk_mul_f32 v[78:79], v[92:93], v[78:79]
	s_nop 0
	v_add_f32_e32 v78, v22, v78
	v_add_f32_e32 v124, v78, v79
	v_mov_b32_e32 v78, v119
	v_mov_b32_e32 v79, v104
	v_pk_mul_f32 v[78:79], v[14:15], v[78:79]
	s_nop 0
	v_add_f32_e32 v78, v23, v78
	v_add_f32_e32 v125, v78, v79
	v_mov_b32_e32 v78, v129
	v_mov_b32_e32 v79, v158
	v_pk_mul_f32 v[78:79], v[94:95], v[78:79]
	s_nop 0
	v_add_f32_e32 v78, v8, v78
	v_add_f32_e32 v126, v78, v79
	v_mov_b32_e32 v78, v127
	v_mov_b32_e32 v79, v160
	v_pk_mul_f32 v[78:79], v[0:1], v[78:79]
	s_nop 0
	v_add_f32_e32 v78, v9, v78
	v_add_f32_e32 v130, v78, v79
	v_mov_b32_e32 v78, v123
	v_mov_b32_e32 v79, v162
	v_pk_mul_f32 v[78:79], v[76:77], v[78:79]
	s_nop 0
	v_add_f32_e32 v78, v10, v78
	v_add_f32_e32 v149, v78, v79
	v_mov_b32_e32 v78, v131
	v_mov_b32_e32 v79, v106
	v_pk_mul_f32 v[78:79], v[2:3], v[78:79]
	s_nop 0
	v_add_f32_e32 v78, v11, v78
	v_add_f32_e32 v151, v78, v79
	v_pk_mul_f32 v[78:79], v[112:113], v[152:153]
	s_nop 0
	v_add_f32_e32 v78, v20, v78
	v_add_f32_e32 v103, v78, v79
	s_waitcnt vmcnt(15)
	v_lshlrev_b32_e32 v78, 16, v84
	s_waitcnt vmcnt(14)
	v_lshlrev_b32_e32 v79, 16, v88
	v_pk_mov_b32 v[100:101], v[152:153], v[78:79] op_sel:[1,0]
	s_nop 0
	v_pk_mul_f32 v[82:83], v[114:115], v[100:101]
	s_nop 0
	v_add_f32_e32 v82, v102, v82
	v_add_f32_e32 v119, v82, v83
	v_pk_mul_f32 v[82:83], v[114:115], v[78:79]
	v_and_b32_e32 v102, 0xffff0000, v84
	v_add_f32_e32 v82, v103, v82
	v_add_f32_e32 v164, v82, v83
	v_pk_mul_f32 v[82:83], v[12:13], v[154:155]
	v_and_b32_e32 v103, 0xffff0000, v88
	v_add_f32_e32 v82, v21, v82
	v_pk_mov_b32 v[116:117], v[154:155], v[102:103] op_sel:[1,0]
	v_add_f32_e32 v120, v82, v83
	v_pk_mul_f32 v[82:83], v[16:17], v[116:117]
	v_and_b32_e32 v88, 0xffff0000, v85
	v_add_f32_e32 v82, v118, v82
	v_add_f32_e32 v82, v82, v83
	v_cvt_pk_bf16_f32 v82, v119, v82
	v_pk_mul_f32 v[118:119], v[16:17], v[102:103]
	s_nop 0
	v_add_f32_e32 v83, v120, v118
	v_add_f32_e32 v165, v83, v119
	v_pk_mul_f32 v[118:119], v[92:93], v[156:157]
	s_nop 0
	v_add_f32_e32 v83, v22, v118
	v_add_f32_e32 v83, v83, v119
	v_lshlrev_b32_e32 v118, 16, v85
	v_lshlrev_b32_e32 v119, 16, v89
	v_pk_mov_b32 v[120:121], v[156:157], v[118:119] op_sel:[1,0]
	v_and_b32_e32 v89, 0xffff0000, v89
	v_pk_mul_f32 v[122:123], v[96:97], v[120:121]
	s_nop 0
	v_add_f32_e32 v84, v124, v122
	v_add_f32_e32 v124, v84, v123
	v_pk_mul_f32 v[122:123], v[96:97], v[118:119]
	s_nop 0
	v_add_f32_e32 v83, v83, v122
	v_add_f32_e32 v166, v83, v123
	v_pk_mul_f32 v[122:123], v[14:15], v[104:105]
	v_pk_mov_b32 v[104:105], v[104:105], v[88:89] op_sel:[1,0]
	v_add_f32_e32 v83, v23, v122
	v_pk_mul_f32 v[84:85], v[18:19], v[104:105]
	v_add_f32_e32 v122, v83, v123
	v_add_f32_e32 v83, v125, v84
	v_add_f32_e32 v83, v83, v85
	v_pk_mul_f32 v[84:85], v[18:19], v[88:89]
	v_lshlrev_b32_e32 v123, 16, v90
	v_add_f32_e32 v84, v122, v84
	v_add_f32_e32 v167, v84, v85
	v_pk_mul_f32 v[84:85], v[94:95], v[158:159]
	v_lshlrev_b32_e32 v122, 16, v86
	v_cvt_pk_bf16_f32 v83, v124, v83
	v_add_f32_e32 v84, v8, v84
	v_pk_mov_b32 v[124:125], v[158:159], v[122:123] op_sel:[1,0]
	v_add_f32_e32 v127, v84, v85
	v_pk_mul_f32 v[84:85], v[98:99], v[124:125]
	s_nop 0
	v_add_f32_e32 v84, v126, v84
	v_add_f32_e32 v131, v84, v85
	v_pk_mul_f32 v[84:85], v[98:99], v[122:123]
	v_and_b32_e32 v126, 0xffff0000, v86
	v_add_f32_e32 v84, v127, v84
	v_add_f32_e32 v158, v84, v85
	v_pk_mul_f32 v[84:85], v[0:1], v[160:161]
	v_and_b32_e32 v127, 0xffff0000, v90
	v_add_f32_e32 v84, v9, v84
	v_pk_mov_b32 v[128:129], v[160:161], v[126:127] op_sel:[1,0]
	v_add_f32_e32 v152, v84, v85
	v_pk_mul_f32 v[84:85], v[4:5], v[128:129]
	v_and_b32_e32 v90, 0xffff0000, v87
	v_add_f32_e32 v84, v130, v84
	v_add_f32_e32 v84, v84, v85
	v_cvt_pk_bf16_f32 v84, v131, v84
	v_pk_mul_f32 v[130:131], v[4:5], v[126:127]
	s_nop 0
	v_add_f32_e32 v85, v152, v130
	v_add_f32_e32 v159, v85, v131
	v_pk_mul_f32 v[130:131], v[76:77], v[162:163]
	s_nop 0
	v_add_f32_e32 v85, v10, v130
	v_add_f32_e32 v85, v85, v131
	v_lshlrev_b32_e32 v130, 16, v87
	v_lshlrev_b32_e32 v131, 16, v91
	v_pk_mov_b32 v[152:153], v[162:163], v[130:131] op_sel:[1,0]
	v_and_b32_e32 v91, 0xffff0000, v91
	v_pk_mul_f32 v[154:155], v[80:81], v[152:153]
	s_nop 0
	v_add_f32_e32 v86, v149, v154
	v_add_f32_e32 v149, v86, v155
	v_pk_mov_b32 v[86:87], v[106:107], v[90:91] op_sel:[1,0]
	v_pk_mul_f32 v[154:155], v[80:81], v[130:131]
	v_pk_mul_f32 v[156:157], v[6:7], v[86:87]
	v_add_f32_e32 v154, v85, v154
	v_add_f32_e32 v85, v151, v156
	v_add_f32_e32 v85, v85, v157
	v_cvt_pk_bf16_f32 v85, v149, v85
	v_mov_b32_e32 v149, s0
	v_mov_b32_e32 v151, s1
	v_pk_mul_f32 v[106:107], v[2:3], v[106:107]
	v_readfirstlane_b32 s16, v149
	v_readfirstlane_b32 s17, v151
	s_load_dwordx2 s[16:17], s[16:17], 0xc0
	v_add_f32_e32 v106, v11, v106
	v_add_f32_e32 v151, v106, v107
	v_add_f32_e32 v149, v154, v155
	s_waitcnt lgkmcnt(0)
	v_mov_b64_e32 v[106:107], s[16:17]
	v_mad_i64_i32 v[106:107], s[16:17], v150, s24, v[106:107]
	v_lshl_add_u64 v[106:107], v[106:107], 0, v[110:111]
	v_add_co_u32_e32 v106, vcc, s26, v106
	s_nop 1
	v_addc_co_u32_e32 v107, vcc, 0, v107, vcc
	global_store_dwordx4 v[106:107], v[82:85], off sc1
	v_mov_b32_e32 v106, s0
	v_mov_b32_e32 v107, s1
	v_pk_mul_f32 v[82:83], v[6:7], v[90:91]
	s_nop 0
	v_add_f32_e32 v82, v151, v82
	v_add_f32_e32 v85, v82, v83
	v_cvt_pk_bf16_f32 v82, v164, v165
	v_cvt_pk_bf16_f32 v83, v166, v167
	v_cvt_pk_bf16_f32 v84, v158, v159
	v_cvt_pk_bf16_f32 v85, v149, v85
	s_nop 0
	v_readfirstlane_b32 s16, v106
	v_readfirstlane_b32 s17, v107
	s_load_dwordx2 s[16:17], s[16:17], 0xc0
	s_waitcnt lgkmcnt(0)
	v_mov_b64_e32 v[106:107], s[16:17]
	v_mad_i64_i32 v[106:107], s[16:17], v148, s24, v[106:107]
	v_lshl_add_u64 v[106:107], v[106:107], 0, v[110:111]
	v_add_co_u32_e32 v106, vcc, s26, v106
	s_nop 1
	v_addc_co_u32_e32 v107, vcc, 0, v107, vcc
	global_store_dwordx4 v[106:107], v[82:85], off sc1
	s_nop 1
	v_pk_mul_f32 v[82:83], v[112:113], v[100:101]
	s_nop 0
	v_add_f32_e32 v82, v20, v82
	v_add_f32_e32 v100, v82, v83
	v_pk_mul_f32 v[82:83], v[12:13], v[116:117]
	s_nop 0
	v_add_f32_e32 v82, v21, v82
	v_add_f32_e32 v106, v82, v83
	v_pk_mul_f32 v[82:83], v[92:93], v[120:121]
	s_nop 0
	v_add_f32_e32 v82, v22, v82
	v_add_f32_e32 v107, v82, v83
	v_pk_mul_f32 v[82:83], v[14:15], v[104:105]
	s_nop 0
	v_add_f32_e32 v82, v23, v82
	v_add_f32_e32 v116, v82, v83
	v_pk_mul_f32 v[82:83], v[94:95], v[124:125]
	s_nop 0
	v_add_f32_e32 v82, v8, v82
	v_add_f32_e32 v120, v82, v83
	v_pk_mul_f32 v[82:83], v[0:1], v[128:129]
	s_nop 0
	v_add_f32_e32 v82, v9, v82
	v_add_f32_e32 v124, v82, v83
	v_pk_mul_f32 v[82:83], v[76:77], v[152:153]
	s_nop 0
	v_add_f32_e32 v82, v10, v82
	v_add_f32_e32 v128, v82, v83
	v_pk_mul_f32 v[82:83], v[2:3], v[86:87]
	s_nop 0
	v_add_f32_e32 v82, v11, v82
	v_add_f32_e32 v148, v82, v83
	v_pk_mul_f32 v[82:83], v[112:113], v[78:79]
	s_nop 0
	v_add_f32_e32 v82, v20, v82
	v_add_f32_e32 v86, v82, v83
	s_waitcnt vmcnt(15)
	v_lshlrev_b32_e32 v82, 16, v68
	s_waitcnt vmcnt(14)
	v_lshlrev_b32_e32 v83, 16, v72
	v_pk_mov_b32 v[78:79], v[78:79], v[82:83] op_sel:[1,0]
	s_nop 0
	v_pk_mul_f32 v[84:85], v[114:115], v[78:79]
	s_nop 0
	v_add_f32_e32 v84, v100, v84
	v_add_f32_e32 v104, v84, v85
	v_pk_mul_f32 v[84:85], v[114:115], v[82:83]
	s_nop 0
	v_add_f32_e32 v84, v86, v84
	v_add_f32_e32 v149, v84, v85
	v_pk_mul_f32 v[84:85], v[12:13], v[102:103]
	s_nop 0
	v_add_f32_e32 v84, v21, v84
	v_add_f32_e32 v105, v84, v85
	v_and_b32_e32 v85, 0xffff0000, v72
	v_and_b32_e32 v84, 0xffff0000, v68
	v_pk_mov_b32 v[86:87], v[102:103], v[84:85] op_sel:[1,0]
	s_nop 0
	v_pk_mul_f32 v[100:101], v[16:17], v[86:87]
	s_nop 0
	v_add_f32_e32 v68, v106, v100
	v_add_f32_e32 v68, v68, v101
	v_pk_mul_f32 v[100:101], v[16:17], v[84:85]
	v_cvt_pk_bf16_f32 v68, v104, v68
	s_nop 0
	v_add_f32_e32 v72, v105, v100
	v_add_f32_e32 v150, v72, v101
	v_pk_mul_f32 v[100:101], v[92:93], v[118:119]
	s_nop 0
	v_add_f32_e32 v72, v22, v100
	v_add_f32_e32 v72, v72, v101
	v_lshlrev_b32_e32 v100, 16, v69
	v_lshlrev_b32_e32 v101, 16, v73
	v_pk_mov_b32 v[102:103], v[118:119], v[100:101] op_sel:[1,0]
	v_and_b32_e32 v73, 0xffff0000, v73
	v_pk_mul_f32 v[104:105], v[96:97], v[102:103]
	s_nop 0
	v_add_f32_e32 v104, v107, v104
	v_add_f32_e32 v106, v104, v105
	v_pk_mul_f32 v[104:105], v[96:97], v[100:101]
	s_nop 0
	v_add_f32_e32 v72, v72, v104
	v_add_f32_e32 v151, v72, v105
	v_pk_mul_f32 v[104:105], v[14:15], v[88:89]
	s_nop 0
	v_add_f32_e32 v72, v23, v104
	v_add_f32_e32 v107, v72, v105
	v_and_b32_e32 v72, 0xffff0000, v69
	v_pk_mov_b32 v[88:89], v[88:89], v[72:73] op_sel:[1,0]
	s_nop 0
	v_pk_mul_f32 v[104:105], v[18:19], v[88:89]
	s_nop 0
	v_add_f32_e32 v69, v116, v104
	v_add_f32_e32 v69, v69, v105
	v_pk_mul_f32 v[104:105], v[18:19], v[72:73]
	v_cvt_pk_bf16_f32 v69, v106, v69
	s_nop 0
	v_add_f32_e32 v104, v107, v104
	v_add_f32_e32 v152, v104, v105
	v_pk_mul_f32 v[104:105], v[94:95], v[122:123]
	s_nop 0
	v_add_f32_e32 v104, v8, v104
	v_add_f32_e32 v118, v104, v105
	v_lshlrev_b32_e32 v104, 16, v70
	v_lshlrev_b32_e32 v105, 16, v74
	v_pk_mov_b32 v[106:107], v[122:123], v[104:105] op_sel:[1,0]
	s_nop 0
	v_pk_mul_f32 v[116:117], v[98:99], v[106:107]
	s_nop 0
	v_add_f32_e32 v116, v120, v116
	v_add_f32_e32 v122, v116, v117
	v_pk_mul_f32 v[116:117], v[98:99], v[104:105]
	s_nop 0
	v_add_f32_e32 v116, v118, v116
	v_add_f32_e32 v153, v116, v117
	v_pk_mul_f32 v[116:117], v[0:1], v[126:127]
	s_nop 0
	v_add_f32_e32 v116, v9, v116
	v_add_f32_e32 v123, v116, v117
	v_and_b32_e32 v117, 0xffff0000, v74
	v_and_b32_e32 v116, 0xffff0000, v70
	v_pk_mov_b32 v[118:119], v[126:127], v[116:117] op_sel:[1,0]
	s_nop 0
	v_pk_mul_f32 v[120:121], v[4:5], v[118:119]
	s_nop 0
	v_add_f32_e32 v70, v124, v120
	v_add_f32_e32 v70, v70, v121
	v_pk_mul_f32 v[120:121], v[4:5], v[116:117]
	v_cvt_pk_bf16_f32 v70, v122, v70
	s_nop 0
	v_add_f32_e32 v74, v123, v120
	v_add_f32_e32 v154, v74, v121
	v_pk_mul_f32 v[120:121], v[76:77], v[130:131]
	s_nop 0
	v_add_f32_e32 v74, v10, v120
	v_add_f32_e32 v74, v74, v121
	v_lshlrev_b32_e32 v120, 16, v71
	v_lshlrev_b32_e32 v121, 16, v75
	v_pk_mov_b32 v[122:123], v[130:131], v[120:121] op_sel:[1,0]
	v_and_b32_e32 v75, 0xffff0000, v75
	v_pk_mul_f32 v[124:125], v[80:81], v[122:123]
	s_nop 0
	v_add_f32_e32 v124, v128, v124
	v_add_f32_e32 v130, v124, v125
	v_pk_mul_f32 v[124:125], v[80:81], v[120:121]
	s_nop 0
	v_add_f32_e32 v124, v74, v124
	v_and_b32_e32 v74, 0xffff0000, v71
	v_pk_mov_b32 v[126:127], v[90:91], v[74:75] op_sel:[1,0]
	v_pk_mul_f32 v[90:91], v[2:3], v[90:91]
	v_pk_mul_f32 v[128:129], v[6:7], v[126:127]
	v_add_f32_e32 v90, v11, v90
	v_add_f32_e32 v71, v148, v128
	v_add_f32_e32 v71, v71, v129
	v_mov_b32_e32 v128, s0
	v_mov_b32_e32 v129, s1
	v_cvt_pk_bf16_f32 v71, v130, v71
	v_add_f32_e32 v124, v124, v125
	v_readfirstlane_b32 s16, v128
	v_readfirstlane_b32 s17, v129
	s_load_dwordx2 s[16:17], s[16:17], 0xc0
	v_add_f32_e32 v125, v90, v91
	s_waitcnt lgkmcnt(0)
	v_mov_b64_e32 v[90:91], s[16:17]
	v_mad_i64_i32 v[90:91], s[16:17], v147, s24, v[90:91]
	v_lshl_add_u64 v[90:91], v[90:91], 0, v[110:111]
	v_add_co_u32_e32 v90, vcc, s26, v90
	s_nop 1
	v_addc_co_u32_e32 v91, vcc, 0, v91, vcc
	global_store_dwordx4 v[90:91], v[68:71], off sc1
	v_mov_b32_e32 v90, s0
	v_mov_b32_e32 v91, s1
	v_pk_mul_f32 v[68:69], v[6:7], v[74:75]
	s_nop 0
	v_add_f32_e32 v68, v125, v68
	v_add_f32_e32 v71, v68, v69
	v_cvt_pk_bf16_f32 v68, v149, v150
	v_cvt_pk_bf16_f32 v69, v151, v152
	v_cvt_pk_bf16_f32 v70, v153, v154
	v_cvt_pk_bf16_f32 v71, v124, v71
	s_nop 0
	v_readfirstlane_b32 s16, v90
	v_readfirstlane_b32 s17, v91
	s_load_dwordx2 s[16:17], s[16:17], 0xc0
	s_waitcnt lgkmcnt(0)
	v_mov_b64_e32 v[90:91], s[16:17]
	v_mad_i64_i32 v[90:91], s[16:17], v146, s24, v[90:91]
	v_lshl_add_u64 v[90:91], v[90:91], 0, v[110:111]
	v_add_co_u32_e32 v90, vcc, s26, v90
	s_nop 1
	v_addc_co_u32_e32 v91, vcc, 0, v91, vcc
	global_store_dwordx4 v[90:91], v[68:71], off sc1
	s_nop 1
	v_pk_mul_f32 v[68:69], v[112:113], v[78:79]
	s_nop 0
	v_add_f32_e32 v68, v20, v68
	v_add_f32_e32 v90, v68, v69
	v_pk_mul_f32 v[68:69], v[12:13], v[86:87]
	s_nop 0
	v_add_f32_e32 v68, v21, v68
	v_add_f32_e32 v86, v68, v69
	v_pk_mul_f32 v[68:69], v[92:93], v[102:103]
	s_nop 0
	v_add_f32_e32 v68, v22, v68
	v_add_f32_e32 v91, v68, v69
	v_pk_mul_f32 v[68:69], v[14:15], v[88:89]
	s_nop 0
	v_add_f32_e32 v68, v23, v68
	v_add_f32_e32 v102, v68, v69
	v_pk_mul_f32 v[68:69], v[94:95], v[106:107]
	s_nop 0
	v_add_f32_e32 v68, v8, v68
	v_add_f32_e32 v103, v68, v69
	v_pk_mul_f32 v[68:69], v[0:1], v[118:119]
	s_nop 0
	v_add_f32_e32 v68, v9, v68
	v_add_f32_e32 v106, v68, v69
	v_pk_mul_f32 v[68:69], v[76:77], v[122:123]
	s_nop 0
	v_add_f32_e32 v68, v10, v68
	v_add_f32_e32 v118, v68, v69
	v_pk_mul_f32 v[68:69], v[2:3], v[126:127]
	s_nop 0
	v_add_f32_e32 v68, v11, v68
	v_add_f32_e32 v122, v68, v69
	v_pk_mul_f32 v[68:69], v[112:113], v[82:83]
	s_nop 0
	v_add_f32_e32 v68, v20, v68
	v_add_f32_e32 v87, v68, v69
	s_waitcnt vmcnt(15)
	v_lshlrev_b32_e32 v68, 16, v60
	s_waitcnt vmcnt(14)
	v_lshlrev_b32_e32 v69, 16, v64
	v_pk_mov_b32 v[70:71], v[82:83], v[68:69] op_sel:[1,0]
	s_nop 0
	v_pk_mul_f32 v[78:79], v[114:115], v[70:71]
	s_nop 0
	v_add_f32_e32 v78, v90, v78
	v_add_f32_e32 v88, v78, v79
	v_pk_mul_f32 v[78:79], v[114:115], v[68:69]
	s_nop 0
	v_add_f32_e32 v78, v87, v78
	v_add_f32_e32 v123, v78, v79
	v_pk_mul_f32 v[78:79], v[12:13], v[84:85]
	s_nop 0
	v_add_f32_e32 v78, v21, v78
	v_add_f32_e32 v87, v78, v79
	v_and_b32_e32 v79, 0xffff0000, v64
	v_and_b32_e32 v78, 0xffff0000, v60
	v_pk_mov_b32 v[82:83], v[84:85], v[78:79] op_sel:[1,0]
	s_nop 0
	v_pk_mul_f32 v[84:85], v[16:17], v[82:83]
	s_nop 0
	v_add_f32_e32 v60, v86, v84
	v_add_f32_e32 v60, v60, v85
	v_pk_mul_f32 v[84:85], v[16:17], v[78:79]
	v_cvt_pk_bf16_f32 v60, v88, v60
	s_nop 0
	v_add_f32_e32 v64, v87, v84
	v_add_f32_e32 v124, v64, v85
	v_pk_mul_f32 v[84:85], v[92:93], v[100:101]
	s_nop 0
	v_add_f32_e32 v64, v22, v84
	v_add_f32_e32 v64, v64, v85
	v_lshlrev_b32_e32 v84, 16, v61
	v_lshlrev_b32_e32 v85, 16, v65
	v_pk_mov_b32 v[86:87], v[100:101], v[84:85] op_sel:[1,0]
	v_and_b32_e32 v65, 0xffff0000, v65
	v_pk_mul_f32 v[88:89], v[96:97], v[86:87]
	s_nop 0
	v_add_f32_e32 v88, v91, v88
	v_add_f32_e32 v90, v88, v89
	v_pk_mul_f32 v[88:89], v[96:97], v[84:85]
	s_nop 0
	v_add_f32_e32 v64, v64, v88
	v_add_f32_e32 v125, v64, v89
	v_pk_mul_f32 v[88:89], v[14:15], v[72:73]
	s_nop 0
	v_add_f32_e32 v64, v23, v88
	v_add_f32_e32 v91, v64, v89
	v_and_b32_e32 v64, 0xffff0000, v61
	v_pk_mov_b32 v[72:73], v[72:73], v[64:65] op_sel:[1,0]
	s_nop 0
	v_pk_mul_f32 v[88:89], v[18:19], v[72:73]
	s_nop 0
	v_add_f32_e32 v61, v102, v88
	v_add_f32_e32 v61, v61, v89
	v_pk_mul_f32 v[88:89], v[18:19], v[64:65]
	v_cvt_pk_bf16_f32 v61, v90, v61
	s_nop 0
	v_add_f32_e32 v88, v91, v88
	v_add_f32_e32 v126, v88, v89
	v_pk_mul_f32 v[88:89], v[94:95], v[104:105]
	s_nop 0
	v_add_f32_e32 v88, v8, v88
	v_add_f32_e32 v102, v88, v89
	v_lshlrev_b32_e32 v88, 16, v62
	v_lshlrev_b32_e32 v89, 16, v66
	v_pk_mov_b32 v[90:91], v[104:105], v[88:89] op_sel:[1,0]
	s_nop 0
	v_pk_mul_f32 v[100:101], v[98:99], v[90:91]
	s_nop 0
	v_add_f32_e32 v100, v103, v100
	v_add_f32_e32 v107, v100, v101
	v_pk_mul_f32 v[100:101], v[98:99], v[88:89]
	s_nop 0
	v_add_f32_e32 v100, v102, v100
	v_add_f32_e32 v127, v100, v101
	v_pk_mul_f32 v[100:101], v[0:1], v[116:117]
	s_nop 0
	v_add_f32_e32 v100, v9, v100
	v_add_f32_e32 v119, v100, v101
	v_and_b32_e32 v101, 0xffff0000, v66
	v_and_b32_e32 v100, 0xffff0000, v62
	v_pk_mov_b32 v[102:103], v[116:117], v[100:101] op_sel:[1,0]
	s_nop 0
	v_pk_mul_f32 v[104:105], v[4:5], v[102:103]
	s_nop 0
	v_add_f32_e32 v62, v106, v104
	v_add_f32_e32 v62, v62, v105
	v_pk_mul_f32 v[104:105], v[4:5], v[100:101]
	v_cvt_pk_bf16_f32 v62, v107, v62
	s_nop 0
	v_add_f32_e32 v66, v119, v104
	v_add_f32_e32 v128, v66, v105
	v_pk_mul_f32 v[104:105], v[76:77], v[120:121]
	s_nop 0
	v_add_f32_e32 v66, v10, v104
	v_add_f32_e32 v66, v66, v105
	v_lshlrev_b32_e32 v104, 16, v63
	v_lshlrev_b32_e32 v105, 16, v67
	v_pk_mov_b32 v[106:107], v[120:121], v[104:105] op_sel:[1,0]
	v_and_b32_e32 v67, 0xffff0000, v67
	v_pk_mul_f32 v[116:117], v[80:81], v[106:107]
	s_nop 0
	v_add_f32_e32 v116, v118, v116
	v_add_f32_e32 v129, v116, v117
	v_pk_mul_f32 v[116:117], v[80:81], v[104:105]
	s_nop 0
	v_add_f32_e32 v116, v66, v116
	v_and_b32_e32 v66, 0xffff0000, v63
	v_pk_mov_b32 v[118:119], v[74:75], v[66:67] op_sel:[1,0]
	v_pk_mul_f32 v[74:75], v[2:3], v[74:75]
	v_pk_mul_f32 v[120:121], v[6:7], v[118:119]
	v_add_f32_e32 v74, v11, v74
	v_add_f32_e32 v63, v122, v120
	v_add_f32_e32 v63, v63, v121
	v_mov_b32_e32 v120, s0
	v_mov_b32_e32 v121, s1
	v_cvt_pk_bf16_f32 v63, v129, v63
	v_add_f32_e32 v116, v116, v117
	v_readfirstlane_b32 s16, v120
	v_readfirstlane_b32 s17, v121
	s_load_dwordx2 s[16:17], s[16:17], 0xc0
	v_add_f32_e32 v117, v74, v75
	s_waitcnt lgkmcnt(0)
	v_mov_b64_e32 v[74:75], s[16:17]
	v_mad_i64_i32 v[74:75], s[16:17], v145, s24, v[74:75]
	v_lshl_add_u64 v[74:75], v[74:75], 0, v[110:111]
	v_add_co_u32_e32 v74, vcc, s26, v74
	s_nop 1
	v_addc_co_u32_e32 v75, vcc, 0, v75, vcc
	global_store_dwordx4 v[74:75], v[60:63], off sc1
	v_mov_b32_e32 v74, s0
	v_mov_b32_e32 v75, s1
	v_pk_mul_f32 v[60:61], v[6:7], v[66:67]
	s_nop 0
	v_add_f32_e32 v60, v117, v60
	v_add_f32_e32 v63, v60, v61
	v_cvt_pk_bf16_f32 v60, v123, v124
	v_cvt_pk_bf16_f32 v61, v125, v126
	v_cvt_pk_bf16_f32 v62, v127, v128
	v_cvt_pk_bf16_f32 v63, v116, v63
	s_nop 0
	v_readfirstlane_b32 s16, v74
	v_readfirstlane_b32 s17, v75
	s_load_dwordx2 s[16:17], s[16:17], 0xc0
	s_waitcnt lgkmcnt(0)
	v_mov_b64_e32 v[74:75], s[16:17]
	v_mad_i64_i32 v[74:75], s[16:17], v144, s24, v[74:75]
	v_lshl_add_u64 v[74:75], v[74:75], 0, v[110:111]
	v_add_co_u32_e32 v74, vcc, s26, v74
	s_nop 1
	v_addc_co_u32_e32 v75, vcc, 0, v75, vcc
	global_store_dwordx4 v[74:75], v[60:63], off sc1
	s_nop 1
	v_pk_mul_f32 v[60:61], v[112:113], v[70:71]
	s_nop 0
	v_add_f32_e32 v60, v20, v60
	v_add_f32_e32 v70, v60, v61
	v_pk_mul_f32 v[60:61], v[12:13], v[82:83]
	s_nop 0
	v_add_f32_e32 v60, v21, v60
	v_add_f32_e32 v74, v60, v61
	v_pk_mul_f32 v[60:61], v[92:93], v[86:87]
	s_nop 0
	v_add_f32_e32 v60, v22, v60
	v_add_f32_e32 v82, v60, v61
	v_pk_mul_f32 v[60:61], v[14:15], v[72:73]
	s_nop 0
	v_add_f32_e32 v60, v23, v60
	v_add_f32_e32 v83, v60, v61
	v_pk_mul_f32 v[60:61], v[94:95], v[90:91]
	s_nop 0
	v_add_f32_e32 v60, v8, v60
	v_add_f32_e32 v86, v60, v61
	v_pk_mul_f32 v[60:61], v[0:1], v[102:103]
	s_nop 0
	v_add_f32_e32 v60, v9, v60
	v_add_f32_e32 v90, v60, v61
	v_pk_mul_f32 v[60:61], v[76:77], v[106:107]
	s_nop 0
	v_add_f32_e32 v60, v10, v60
	v_add_f32_e32 v102, v60, v61
	v_pk_mul_f32 v[60:61], v[2:3], v[118:119]
	s_nop 0
	v_add_f32_e32 v60, v11, v60
	v_add_f32_e32 v106, v60, v61
	v_pk_mul_f32 v[60:61], v[112:113], v[68:69]
	s_nop 0
	v_add_f32_e32 v60, v20, v60
	v_add_f32_e32 v71, v60, v61
	s_waitcnt vmcnt(15)
	v_lshlrev_b32_e32 v60, 16, v52
	s_waitcnt vmcnt(14)
	v_lshlrev_b32_e32 v61, 16, v56
	v_pk_mov_b32 v[62:63], v[68:69], v[60:61] op_sel:[1,0]
	s_nop 0
	v_pk_mul_f32 v[68:69], v[114:115], v[62:63]
	s_nop 0
	v_add_f32_e32 v68, v70, v68
	v_add_f32_e32 v75, v68, v69
	v_pk_mul_f32 v[68:69], v[114:115], v[60:61]
	s_nop 0
	v_add_f32_e32 v68, v71, v68
	v_add_f32_e32 v107, v68, v69
	v_pk_mul_f32 v[68:69], v[12:13], v[78:79]
	s_nop 0
	v_add_f32_e32 v68, v21, v68
	v_add_f32_e32 v87, v68, v69
	v_and_b32_e32 v69, 0xffff0000, v56
	v_and_b32_e32 v68, 0xffff0000, v52
	v_pk_mov_b32 v[70:71], v[78:79], v[68:69] op_sel:[1,0]
	s_nop 0
	v_pk_mul_f32 v[72:73], v[16:17], v[70:71]
	s_nop 0
	v_add_f32_e32 v52, v74, v72
	v_add_f32_e32 v52, v52, v73
	v_pk_mul_f32 v[72:73], v[16:17], v[68:69]
	v_cvt_pk_bf16_f32 v52, v75, v52
	s_nop 0
	v_add_f32_e32 v56, v87, v72
	v_add_f32_e32 v116, v56, v73
	v_pk_mul_f32 v[72:73], v[92:93], v[84:85]
	s_nop 0
	v_add_f32_e32 v56, v22, v72
	v_add_f32_e32 v56, v56, v73
	v_lshlrev_b32_e32 v72, 16, v53
	v_lshlrev_b32_e32 v73, 16, v57
	v_pk_mov_b32 v[74:75], v[84:85], v[72:73] op_sel:[1,0]
	v_and_b32_e32 v57, 0xffff0000, v57
	v_pk_mul_f32 v[78:79], v[96:97], v[74:75]
	s_nop 0
	v_add_f32_e32 v78, v82, v78
	v_add_f32_e32 v82, v78, v79
	v_pk_mul_f32 v[78:79], v[96:97], v[72:73]
	s_nop 0
	v_add_f32_e32 v56, v56, v78
	v_add_f32_e32 v117, v56, v79
	v_pk_mul_f32 v[78:79], v[14:15], v[64:65]
	s_nop 0
	v_add_f32_e32 v56, v23, v78
	v_add_f32_e32 v84, v56, v79
	v_and_b32_e32 v56, 0xffff0000, v53
	v_pk_mov_b32 v[64:65], v[64:65], v[56:57] op_sel:[1,0]
	s_nop 0
	v_pk_mul_f32 v[78:79], v[18:19], v[64:65]
	s_nop 0
	v_add_f32_e32 v53, v83, v78
	v_add_f32_e32 v53, v53, v79
	v_pk_mul_f32 v[78:79], v[18:19], v[56:57]
	v_cvt_pk_bf16_f32 v53, v82, v53
	s_nop 0
	v_add_f32_e32 v78, v84, v78
	v_add_f32_e32 v118, v78, v79
	v_pk_mul_f32 v[78:79], v[94:95], v[88:89]
	s_nop 0
	v_add_f32_e32 v78, v8, v78
	v_add_f32_e32 v87, v78, v79
	v_lshlrev_b32_e32 v78, 16, v54
	v_lshlrev_b32_e32 v79, 16, v58
	v_pk_mov_b32 v[82:83], v[88:89], v[78:79] op_sel:[1,0]
	s_nop 0
	v_pk_mul_f32 v[84:85], v[98:99], v[82:83]
	s_nop 0
	v_add_f32_e32 v84, v86, v84
	v_add_f32_e32 v91, v84, v85
	v_pk_mul_f32 v[84:85], v[98:99], v[78:79]
	s_nop 0
	v_add_f32_e32 v84, v87, v84
	v_add_f32_e32 v119, v84, v85
	v_pk_mul_f32 v[84:85], v[0:1], v[100:101]
	s_nop 0
	v_add_f32_e32 v84, v9, v84
	v_add_f32_e32 v103, v84, v85
	v_and_b32_e32 v85, 0xffff0000, v58
	v_and_b32_e32 v84, 0xffff0000, v54
	v_pk_mov_b32 v[86:87], v[100:101], v[84:85] op_sel:[1,0]
	s_nop 0
	v_pk_mul_f32 v[88:89], v[4:5], v[86:87]
	s_nop 0
	v_add_f32_e32 v54, v90, v88
	v_add_f32_e32 v54, v54, v89
	v_pk_mul_f32 v[88:89], v[4:5], v[84:85]
	v_cvt_pk_bf16_f32 v54, v91, v54
	s_nop 0
	v_add_f32_e32 v58, v103, v88
	v_add_f32_e32 v120, v58, v89
	v_pk_mul_f32 v[88:89], v[76:77], v[104:105]
	s_nop 0
	v_add_f32_e32 v58, v10, v88
	v_add_f32_e32 v58, v58, v89
	v_lshlrev_b32_e32 v88, 16, v55
	v_lshlrev_b32_e32 v89, 16, v59
	v_pk_mov_b32 v[90:91], v[104:105], v[88:89] op_sel:[1,0]
	v_and_b32_e32 v59, 0xffff0000, v59
	v_pk_mul_f32 v[100:101], v[80:81], v[90:91]
	s_nop 0
	v_add_f32_e32 v100, v102, v100
	v_add_f32_e32 v121, v100, v101
	v_pk_mul_f32 v[100:101], v[80:81], v[88:89]
	s_nop 0
	v_add_f32_e32 v100, v58, v100
	v_and_b32_e32 v58, 0xffff0000, v55
	v_pk_mov_b32 v[102:103], v[66:67], v[58:59] op_sel:[1,0]
	v_pk_mul_f32 v[66:67], v[2:3], v[66:67]
	v_pk_mul_f32 v[104:105], v[6:7], v[102:103]
	v_add_f32_e32 v66, v11, v66
	v_add_f32_e32 v55, v106, v104
	v_add_f32_e32 v55, v55, v105
	v_mov_b32_e32 v104, s0
	v_mov_b32_e32 v105, s1
	v_cvt_pk_bf16_f32 v55, v121, v55
	v_add_f32_e32 v100, v100, v101
	v_readfirstlane_b32 s16, v104
	v_readfirstlane_b32 s17, v105
	s_load_dwordx2 s[16:17], s[16:17], 0xc0
	v_add_f32_e32 v101, v66, v67
	s_waitcnt lgkmcnt(0)
	v_mov_b64_e32 v[66:67], s[16:17]
	v_mad_i64_i32 v[66:67], s[16:17], v143, s24, v[66:67]
	v_lshl_add_u64 v[66:67], v[66:67], 0, v[110:111]
	v_add_co_u32_e32 v66, vcc, s26, v66
	s_nop 1
	v_addc_co_u32_e32 v67, vcc, 0, v67, vcc
	global_store_dwordx4 v[66:67], v[52:55], off sc1
	v_mov_b32_e32 v66, s0
	v_mov_b32_e32 v67, s1
	v_pk_mul_f32 v[52:53], v[6:7], v[58:59]
	s_nop 0
	v_add_f32_e32 v52, v101, v52
	v_add_f32_e32 v55, v52, v53
	v_cvt_pk_bf16_f32 v52, v107, v116
	v_cvt_pk_bf16_f32 v53, v117, v118
	v_cvt_pk_bf16_f32 v54, v119, v120
	v_cvt_pk_bf16_f32 v55, v100, v55
	s_nop 0
	v_readfirstlane_b32 s16, v66
	v_readfirstlane_b32 s17, v67
	s_load_dwordx2 s[16:17], s[16:17], 0xc0
	s_waitcnt lgkmcnt(0)
	v_mov_b64_e32 v[66:67], s[16:17]
	v_mad_i64_i32 v[66:67], s[16:17], v142, s24, v[66:67]
	v_lshl_add_u64 v[66:67], v[66:67], 0, v[110:111]
	v_add_co_u32_e32 v66, vcc, s26, v66
	s_nop 1
	v_addc_co_u32_e32 v67, vcc, 0, v67, vcc
	global_store_dwordx4 v[66:67], v[52:55], off sc1
	s_nop 1
	v_pk_mul_f32 v[52:53], v[112:113], v[62:63]
	s_nop 0
	v_add_f32_e32 v52, v20, v52
	v_add_f32_e32 v62, v52, v53
	v_pk_mul_f32 v[52:53], v[12:13], v[70:71]
	s_nop 0
	v_add_f32_e32 v52, v21, v52
	v_add_f32_e32 v66, v52, v53
	v_pk_mul_f32 v[52:53], v[92:93], v[74:75]
	s_nop 0
	v_add_f32_e32 v52, v22, v52
	v_add_f32_e32 v70, v52, v53
	v_pk_mul_f32 v[52:53], v[14:15], v[64:65]
	s_nop 0
	v_add_f32_e32 v52, v23, v52
	v_add_f32_e32 v71, v52, v53
	v_pk_mul_f32 v[52:53], v[94:95], v[82:83]
	s_nop 0
	v_add_f32_e32 v52, v8, v52
	v_add_f32_e32 v74, v52, v53
	v_pk_mul_f32 v[52:53], v[0:1], v[86:87]
	s_nop 0
	v_add_f32_e32 v52, v9, v52
	v_add_f32_e32 v82, v52, v53
	v_pk_mul_f32 v[52:53], v[76:77], v[90:91]
	s_nop 0
	v_add_f32_e32 v52, v10, v52
	v_add_f32_e32 v86, v52, v53
	v_pk_mul_f32 v[52:53], v[2:3], v[102:103]
	s_nop 0
	v_add_f32_e32 v52, v11, v52
	v_add_f32_e32 v90, v52, v53
	v_pk_mul_f32 v[52:53], v[112:113], v[60:61]
	s_nop 0
	v_add_f32_e32 v52, v20, v52
	v_add_f32_e32 v63, v52, v53
	s_waitcnt vmcnt(15)
	v_lshlrev_b32_e32 v52, 16, v44
	s_waitcnt vmcnt(14)
	v_lshlrev_b32_e32 v53, 16, v48
	v_pk_mov_b32 v[54:55], v[60:61], v[52:53] op_sel:[1,0]
	s_nop 0
	v_pk_mul_f32 v[60:61], v[114:115], v[54:55]
	s_nop 0
	v_add_f32_e32 v60, v62, v60
	v_add_f32_e32 v67, v60, v61
	v_pk_mul_f32 v[60:61], v[114:115], v[52:53]
	s_nop 0
	v_add_f32_e32 v60, v63, v60
	v_add_f32_e32 v91, v60, v61
	v_pk_mul_f32 v[60:61], v[12:13], v[68:69]
	s_nop 0
	v_add_f32_e32 v60, v21, v60
	v_add_f32_e32 v75, v60, v61
	v_and_b32_e32 v61, 0xffff0000, v48
	v_and_b32_e32 v60, 0xffff0000, v44
	v_pk_mov_b32 v[62:63], v[68:69], v[60:61] op_sel:[1,0]
	s_nop 0
	v_pk_mul_f32 v[64:65], v[16:17], v[62:63]
	s_nop 0
	v_add_f32_e32 v44, v66, v64
	v_add_f32_e32 v44, v44, v65
	v_pk_mul_f32 v[64:65], v[16:17], v[60:61]
	v_cvt_pk_bf16_f32 v44, v67, v44
	s_nop 0
	v_add_f32_e32 v48, v75, v64
	v_add_f32_e32 v100, v48, v65
	v_pk_mul_f32 v[64:65], v[92:93], v[72:73]
	s_nop 0
	v_add_f32_e32 v48, v22, v64
	v_add_f32_e32 v48, v48, v65
	v_lshlrev_b32_e32 v64, 16, v45
	v_lshlrev_b32_e32 v65, 16, v49
	v_pk_mov_b32 v[66:67], v[72:73], v[64:65] op_sel:[1,0]
	v_and_b32_e32 v49, 0xffff0000, v49
	v_pk_mul_f32 v[68:69], v[96:97], v[66:67]
	s_nop 0
	v_add_f32_e32 v68, v70, v68
	v_add_f32_e32 v70, v68, v69
	v_pk_mul_f32 v[68:69], v[96:97], v[64:65]
	s_nop 0
	v_add_f32_e32 v48, v48, v68
	v_add_f32_e32 v101, v48, v69
	v_pk_mul_f32 v[68:69], v[14:15], v[56:57]
	s_nop 0
	v_add_f32_e32 v48, v23, v68
	v_add_f32_e32 v72, v48, v69
	v_and_b32_e32 v48, 0xffff0000, v45
	v_pk_mov_b32 v[56:57], v[56:57], v[48:49] op_sel:[1,0]
	s_nop 0
	v_pk_mul_f32 v[68:69], v[18:19], v[56:57]
	s_nop 0
	v_add_f32_e32 v45, v71, v68
	v_add_f32_e32 v45, v45, v69
	v_pk_mul_f32 v[68:69], v[18:19], v[48:49]
	v_cvt_pk_bf16_f32 v45, v70, v45
	s_nop 0
	v_add_f32_e32 v68, v72, v68
	v_add_f32_e32 v102, v68, v69
	v_pk_mul_f32 v[68:69], v[94:95], v[78:79]
	s_nop 0
	v_add_f32_e32 v68, v8, v68
	v_add_f32_e32 v75, v68, v69
	v_lshlrev_b32_e32 v68, 16, v46
	v_lshlrev_b32_e32 v69, 16, v50
	v_pk_mov_b32 v[70:71], v[78:79], v[68:69] op_sel:[1,0]
	s_nop 0
	v_pk_mul_f32 v[72:73], v[98:99], v[70:71]
	s_nop 0
	v_add_f32_e32 v72, v74, v72
	v_add_f32_e32 v83, v72, v73
	v_pk_mul_f32 v[72:73], v[98:99], v[68:69]
	s_nop 0
	v_add_f32_e32 v72, v75, v72
	v_add_f32_e32 v103, v72, v73
	v_pk_mul_f32 v[72:73], v[0:1], v[84:85]
	s_nop 0
	v_add_f32_e32 v72, v9, v72
	v_add_f32_e32 v87, v72, v73
	v_and_b32_e32 v73, 0xffff0000, v50
	v_and_b32_e32 v72, 0xffff0000, v46
	v_pk_mov_b32 v[74:75], v[84:85], v[72:73] op_sel:[1,0]
	s_nop 0
	v_pk_mul_f32 v[78:79], v[4:5], v[74:75]
	s_nop 0
	v_add_f32_e32 v46, v82, v78
	v_add_f32_e32 v46, v46, v79
	v_pk_mul_f32 v[78:79], v[4:5], v[72:73]
	v_cvt_pk_bf16_f32 v46, v83, v46
	s_nop 0
	v_add_f32_e32 v50, v87, v78
	v_add_f32_e32 v104, v50, v79
	v_pk_mul_f32 v[78:79], v[76:77], v[88:89]
	s_nop 0
	v_add_f32_e32 v50, v10, v78
	v_add_f32_e32 v50, v50, v79
	v_lshlrev_b32_e32 v78, 16, v47
	v_lshlrev_b32_e32 v79, 16, v51
	v_pk_mov_b32 v[82:83], v[88:89], v[78:79] op_sel:[1,0]
	v_and_b32_e32 v51, 0xffff0000, v51
	v_pk_mul_f32 v[84:85], v[80:81], v[82:83]
	s_nop 0
	v_add_f32_e32 v84, v86, v84
	v_add_f32_e32 v105, v84, v85
	v_pk_mul_f32 v[84:85], v[80:81], v[78:79]
	s_nop 0
	v_add_f32_e32 v84, v50, v84
	v_and_b32_e32 v50, 0xffff0000, v47
	v_pk_mov_b32 v[86:87], v[58:59], v[50:51] op_sel:[1,0]
	v_pk_mul_f32 v[58:59], v[2:3], v[58:59]
	v_pk_mul_f32 v[88:89], v[6:7], v[86:87]
	v_add_f32_e32 v58, v11, v58
	v_add_f32_e32 v47, v90, v88
	v_add_f32_e32 v47, v47, v89
	v_mov_b32_e32 v88, s0
	v_mov_b32_e32 v89, s1
	v_cvt_pk_bf16_f32 v47, v105, v47
	v_add_f32_e32 v84, v84, v85
	v_readfirstlane_b32 s16, v88
	v_readfirstlane_b32 s17, v89
	s_load_dwordx2 s[16:17], s[16:17], 0xc0
	v_add_f32_e32 v85, v58, v59
	s_waitcnt lgkmcnt(0)
	v_mov_b64_e32 v[58:59], s[16:17]
	v_mad_i64_i32 v[58:59], s[16:17], v141, s24, v[58:59]
	v_lshl_add_u64 v[58:59], v[58:59], 0, v[110:111]
	v_add_co_u32_e32 v58, vcc, s26, v58
	s_nop 1
	v_addc_co_u32_e32 v59, vcc, 0, v59, vcc
	global_store_dwordx4 v[58:59], v[44:47], off sc1
	v_mov_b32_e32 v58, s0
	v_mov_b32_e32 v59, s1
	v_pk_mul_f32 v[44:45], v[6:7], v[50:51]
	s_nop 0
	v_add_f32_e32 v44, v85, v44
	v_add_f32_e32 v47, v44, v45
	v_cvt_pk_bf16_f32 v44, v91, v100
	v_cvt_pk_bf16_f32 v45, v101, v102
	v_cvt_pk_bf16_f32 v46, v103, v104
	v_cvt_pk_bf16_f32 v47, v84, v47
	s_nop 0
	v_readfirstlane_b32 s16, v58
	v_readfirstlane_b32 s17, v59
	s_load_dwordx2 s[16:17], s[16:17], 0xc0
	s_waitcnt lgkmcnt(0)
	v_mov_b64_e32 v[58:59], s[16:17]
	v_mad_i64_i32 v[58:59], s[16:17], v140, s24, v[58:59]
	v_lshl_add_u64 v[58:59], v[58:59], 0, v[110:111]
	v_add_co_u32_e32 v58, vcc, s26, v58
	s_nop 1
	v_addc_co_u32_e32 v59, vcc, 0, v59, vcc
	global_store_dwordx4 v[58:59], v[44:47], off sc1
	s_nop 1
	v_pk_mul_f32 v[44:45], v[112:113], v[54:55]
	s_nop 0
	v_add_f32_e32 v44, v20, v44
	v_add_f32_e32 v54, v44, v45
	v_pk_mul_f32 v[44:45], v[12:13], v[62:63]
	s_nop 0
	v_add_f32_e32 v44, v21, v44
	v_add_f32_e32 v58, v44, v45
	v_pk_mul_f32 v[44:45], v[92:93], v[66:67]
	s_nop 0
	v_add_f32_e32 v44, v22, v44
	v_add_f32_e32 v62, v44, v45
	v_pk_mul_f32 v[44:45], v[14:15], v[56:57]
	s_nop 0
	v_add_f32_e32 v44, v23, v44
	v_add_f32_e32 v63, v44, v45
	v_pk_mul_f32 v[44:45], v[94:95], v[70:71]
	s_nop 0
	v_add_f32_e32 v44, v8, v44
	v_add_f32_e32 v66, v44, v45
	v_pk_mul_f32 v[44:45], v[0:1], v[74:75]
	s_nop 0
	v_add_f32_e32 v44, v9, v44
	v_add_f32_e32 v70, v44, v45
	v_pk_mul_f32 v[44:45], v[76:77], v[82:83]
	s_nop 0
	v_add_f32_e32 v44, v10, v44
	v_add_f32_e32 v74, v44, v45
	v_pk_mul_f32 v[44:45], v[2:3], v[86:87]
	s_nop 0
	v_add_f32_e32 v44, v11, v44
	v_add_f32_e32 v82, v44, v45
	v_pk_mul_f32 v[44:45], v[112:113], v[52:53]
	s_nop 0
	v_add_f32_e32 v44, v20, v44
	v_add_f32_e32 v55, v44, v45
	s_waitcnt vmcnt(15)
	v_lshlrev_b32_e32 v44, 16, v36
	s_waitcnt vmcnt(14)
	v_lshlrev_b32_e32 v45, 16, v40
	v_pk_mov_b32 v[46:47], v[52:53], v[44:45] op_sel:[1,0]
	s_nop 0
	v_pk_mul_f32 v[52:53], v[114:115], v[46:47]
	s_nop 0
	v_add_f32_e32 v52, v54, v52
	v_add_f32_e32 v59, v52, v53
	v_pk_mul_f32 v[52:53], v[114:115], v[44:45]
	s_nop 0
	v_add_f32_e32 v52, v55, v52
	v_add_f32_e32 v83, v52, v53
	v_pk_mul_f32 v[52:53], v[12:13], v[60:61]
	s_nop 0
	v_add_f32_e32 v52, v21, v52
	v_add_f32_e32 v67, v52, v53
	v_and_b32_e32 v53, 0xffff0000, v40
	v_and_b32_e32 v52, 0xffff0000, v36
	v_pk_mov_b32 v[54:55], v[60:61], v[52:53] op_sel:[1,0]
	s_nop 0
	v_pk_mul_f32 v[56:57], v[16:17], v[54:55]
	s_nop 0
	v_add_f32_e32 v36, v58, v56
	v_add_f32_e32 v36, v36, v57
	v_pk_mul_f32 v[56:57], v[16:17], v[52:53]
	v_cvt_pk_bf16_f32 v36, v59, v36
	s_nop 0
	v_add_f32_e32 v40, v67, v56
	v_add_f32_e32 v84, v40, v57
	v_pk_mul_f32 v[56:57], v[92:93], v[64:65]
	s_nop 0
	v_add_f32_e32 v40, v22, v56
	v_add_f32_e32 v40, v40, v57
	v_lshlrev_b32_e32 v56, 16, v37
	v_lshlrev_b32_e32 v57, 16, v41
	v_pk_mov_b32 v[58:59], v[64:65], v[56:57] op_sel:[1,0]
	v_and_b32_e32 v41, 0xffff0000, v41
	v_pk_mul_f32 v[60:61], v[96:97], v[58:59]
	s_nop 0
	v_add_f32_e32 v60, v62, v60
	v_add_f32_e32 v62, v60, v61
	v_pk_mul_f32 v[60:61], v[96:97], v[56:57]
	s_nop 0
	v_add_f32_e32 v40, v40, v60
	v_add_f32_e32 v85, v40, v61
	v_pk_mul_f32 v[60:61], v[14:15], v[48:49]
	s_nop 0
	v_add_f32_e32 v40, v23, v60
	v_add_f32_e32 v64, v40, v61
	v_and_b32_e32 v40, 0xffff0000, v37
	v_pk_mov_b32 v[48:49], v[48:49], v[40:41] op_sel:[1,0]
	s_nop 0
	v_pk_mul_f32 v[60:61], v[18:19], v[48:49]
	s_nop 0
	v_add_f32_e32 v37, v63, v60
	v_add_f32_e32 v37, v37, v61
	v_pk_mul_f32 v[60:61], v[18:19], v[40:41]
	v_cvt_pk_bf16_f32 v37, v62, v37
	s_nop 0
	v_add_f32_e32 v60, v64, v60
	v_add_f32_e32 v86, v60, v61
	v_pk_mul_f32 v[60:61], v[94:95], v[68:69]
	s_nop 0
	v_add_f32_e32 v60, v8, v60
	v_add_f32_e32 v67, v60, v61
	v_lshlrev_b32_e32 v60, 16, v38
	v_lshlrev_b32_e32 v61, 16, v42
	v_pk_mov_b32 v[62:63], v[68:69], v[60:61] op_sel:[1,0]
	s_nop 0
	v_pk_mul_f32 v[64:65], v[98:99], v[62:63]
	s_nop 0
	v_add_f32_e32 v64, v66, v64
	v_add_f32_e32 v71, v64, v65
	v_pk_mul_f32 v[64:65], v[98:99], v[60:61]
	s_nop 0
	v_add_f32_e32 v64, v67, v64
	v_add_f32_e32 v87, v64, v65
	v_pk_mul_f32 v[64:65], v[0:1], v[72:73]
	s_nop 0
	v_add_f32_e32 v64, v9, v64
	v_add_f32_e32 v75, v64, v65
	v_and_b32_e32 v65, 0xffff0000, v42
	v_and_b32_e32 v64, 0xffff0000, v38
	v_pk_mov_b32 v[66:67], v[72:73], v[64:65] op_sel:[1,0]
	s_nop 0
	v_pk_mul_f32 v[68:69], v[4:5], v[66:67]
	s_nop 0
	v_add_f32_e32 v38, v70, v68
	v_add_f32_e32 v38, v38, v69
	v_pk_mul_f32 v[68:69], v[4:5], v[64:65]
	v_cvt_pk_bf16_f32 v38, v71, v38
	s_nop 0
	v_add_f32_e32 v42, v75, v68
	v_add_f32_e32 v88, v42, v69
	v_pk_mul_f32 v[68:69], v[76:77], v[78:79]
	s_nop 0
	v_add_f32_e32 v42, v10, v68
	v_add_f32_e32 v42, v42, v69
	v_lshlrev_b32_e32 v68, 16, v39
	v_lshlrev_b32_e32 v69, 16, v43
	v_pk_mov_b32 v[70:71], v[78:79], v[68:69] op_sel:[1,0]
	v_and_b32_e32 v43, 0xffff0000, v43
	v_pk_mul_f32 v[72:73], v[80:81], v[70:71]
	s_nop 0
	v_add_f32_e32 v72, v74, v72
	v_add_f32_e32 v89, v72, v73
	v_pk_mul_f32 v[72:73], v[80:81], v[68:69]
	s_nop 0
	v_add_f32_e32 v72, v42, v72
	v_and_b32_e32 v42, 0xffff0000, v39
	v_pk_mov_b32 v[74:75], v[50:51], v[42:43] op_sel:[1,0]
	v_pk_mul_f32 v[50:51], v[2:3], v[50:51]
	v_pk_mul_f32 v[78:79], v[6:7], v[74:75]
	v_add_f32_e32 v50, v11, v50
	v_add_f32_e32 v39, v82, v78
	v_add_f32_e32 v39, v39, v79
	v_mov_b32_e32 v78, s0
	v_mov_b32_e32 v79, s1
	v_cvt_pk_bf16_f32 v39, v89, v39
	v_add_f32_e32 v72, v72, v73
	v_readfirstlane_b32 s16, v78
	v_readfirstlane_b32 s17, v79
	s_load_dwordx2 s[16:17], s[16:17], 0xc0
	v_add_f32_e32 v73, v50, v51
	s_waitcnt lgkmcnt(0)
	v_mov_b64_e32 v[50:51], s[16:17]
	v_mad_i64_i32 v[50:51], s[16:17], v139, s24, v[50:51]
	v_lshl_add_u64 v[50:51], v[50:51], 0, v[110:111]
	v_add_co_u32_e32 v50, vcc, s26, v50
	s_nop 1
	v_addc_co_u32_e32 v51, vcc, 0, v51, vcc
	global_store_dwordx4 v[50:51], v[36:39], off sc1
	v_mov_b32_e32 v50, s0
	v_mov_b32_e32 v51, s1
	v_pk_mul_f32 v[36:37], v[6:7], v[42:43]
	s_nop 0
	v_add_f32_e32 v36, v73, v36
	v_add_f32_e32 v39, v36, v37
	v_cvt_pk_bf16_f32 v36, v83, v84
	v_cvt_pk_bf16_f32 v37, v85, v86
	v_cvt_pk_bf16_f32 v38, v87, v88
	v_cvt_pk_bf16_f32 v39, v72, v39
	s_nop 0
	v_readfirstlane_b32 s16, v50
	v_readfirstlane_b32 s17, v51
	s_load_dwordx2 s[16:17], s[16:17], 0xc0
	s_waitcnt lgkmcnt(0)
	v_mov_b64_e32 v[50:51], s[16:17]
	v_mad_i64_i32 v[50:51], s[16:17], v138, s24, v[50:51]
	v_lshl_add_u64 v[50:51], v[50:51], 0, v[110:111]
	v_add_co_u32_e32 v50, vcc, s26, v50
	s_nop 1
	v_addc_co_u32_e32 v51, vcc, 0, v51, vcc
	global_store_dwordx4 v[50:51], v[36:39], off sc1
	s_nop 1
	v_pk_mul_f32 v[36:37], v[112:113], v[46:47]
	s_nop 0
	v_add_f32_e32 v36, v20, v36
	v_add_f32_e32 v46, v36, v37
	v_pk_mul_f32 v[36:37], v[12:13], v[54:55]
	s_nop 0
	v_add_f32_e32 v36, v21, v36
	v_add_f32_e32 v50, v36, v37
	v_pk_mul_f32 v[36:37], v[92:93], v[58:59]
	s_nop 0
	v_add_f32_e32 v36, v22, v36
	v_add_f32_e32 v54, v36, v37
	v_pk_mul_f32 v[36:37], v[14:15], v[48:49]
	s_nop 0
	v_add_f32_e32 v36, v23, v36
	v_add_f32_e32 v55, v36, v37
	v_pk_mul_f32 v[36:37], v[94:95], v[62:63]
	s_nop 0
	v_add_f32_e32 v36, v8, v36
	v_add_f32_e32 v58, v36, v37
	v_pk_mul_f32 v[36:37], v[0:1], v[66:67]
	s_nop 0
	v_add_f32_e32 v36, v9, v36
	v_add_f32_e32 v62, v36, v37
	v_pk_mul_f32 v[36:37], v[76:77], v[70:71]
	s_nop 0
	v_add_f32_e32 v36, v10, v36
	v_add_f32_e32 v66, v36, v37
	v_pk_mul_f32 v[36:37], v[2:3], v[74:75]
	s_nop 0
	v_add_f32_e32 v36, v11, v36
	v_add_f32_e32 v70, v36, v37
	v_pk_mul_f32 v[36:37], v[112:113], v[44:45]
	s_nop 0
	v_add_f32_e32 v36, v20, v36
	v_add_f32_e32 v47, v36, v37
	s_waitcnt vmcnt(15)
	v_lshlrev_b32_e32 v36, 16, v28
	s_waitcnt vmcnt(14)
	v_lshlrev_b32_e32 v37, 16, v32
	v_pk_mov_b32 v[38:39], v[44:45], v[36:37] op_sel:[1,0]
	s_nop 0
	v_pk_mul_f32 v[44:45], v[114:115], v[38:39]
	v_pk_mul_f32 v[38:39], v[112:113], v[38:39]
	v_add_f32_e32 v44, v46, v44
	v_add_f32_e32 v51, v44, v45
	v_pk_mul_f32 v[44:45], v[114:115], v[36:37]
	v_add_f32_e32 v20, v20, v38
	v_add_f32_e32 v36, v47, v44
	v_add_f32_e32 v36, v36, v45
	v_pk_mul_f32 v[44:45], v[12:13], v[52:53]
	v_add_f32_e32 v20, v20, v39
	v_add_f32_e32 v44, v21, v44
	v_add_f32_e32 v59, v44, v45
	v_and_b32_e32 v45, 0xffff0000, v32
	v_and_b32_e32 v44, 0xffff0000, v28
	v_pk_mov_b32 v[46:47], v[52:53], v[44:45] op_sel:[1,0]
	s_nop 0
	v_pk_mul_f32 v[48:49], v[16:17], v[46:47]
	v_pk_mul_f32 v[12:13], v[12:13], v[46:47]
	v_add_f32_e32 v28, v50, v48
	v_add_f32_e32 v28, v28, v49
	v_pk_mul_f32 v[48:49], v[16:17], v[44:45]
	v_cvt_pk_bf16_f32 v28, v51, v28
	v_add_f32_e32 v12, v21, v12
	v_add_f32_e32 v32, v59, v48
	v_add_f32_e32 v44, v32, v49
	v_pk_mul_f32 v[48:49], v[92:93], v[56:57]
	v_add_f32_e32 v21, v12, v13
	v_add_f32_e32 v32, v22, v48
	v_add_f32_e32 v32, v32, v49
	v_lshlrev_b32_e32 v48, 16, v29
	v_lshlrev_b32_e32 v49, 16, v33
	v_pk_mov_b32 v[50:51], v[56:57], v[48:49] op_sel:[1,0]
	v_and_b32_e32 v33, 0xffff0000, v33
	v_pk_mul_f32 v[52:53], v[96:97], v[50:51]
	s_nop 0
	v_add_f32_e32 v52, v54, v52
	v_add_f32_e32 v54, v52, v53
	v_pk_mul_f32 v[52:53], v[96:97], v[48:49]
	s_nop 0
	v_add_f32_e32 v32, v32, v52
	v_add_f32_e32 v48, v32, v53
	v_pk_mul_f32 v[52:53], v[14:15], v[40:41]
	s_nop 0
	v_add_f32_e32 v32, v23, v52
	v_add_f32_e32 v56, v32, v53
	v_and_b32_e32 v32, 0xffff0000, v29
	v_pk_mov_b32 v[40:41], v[40:41], v[32:33] op_sel:[1,0]
	s_nop 0
	v_pk_mul_f32 v[52:53], v[18:19], v[40:41]
	s_nop 0
	v_add_f32_e32 v29, v55, v52
	v_add_f32_e32 v29, v29, v53
	v_pk_mul_f32 v[52:53], v[18:19], v[32:33]
	v_cvt_pk_bf16_f32 v29, v54, v29
	s_nop 0
	v_add_f32_e32 v32, v56, v52
	v_add_f32_e32 v32, v32, v53
	v_pk_mul_f32 v[52:53], v[94:95], v[60:61]
	s_nop 0
	v_add_f32_e32 v52, v8, v52
	v_add_f32_e32 v59, v52, v53
	v_lshlrev_b32_e32 v52, 16, v30
	v_lshlrev_b32_e32 v53, 16, v34
	v_pk_mov_b32 v[54:55], v[60:61], v[52:53] op_sel:[1,0]
	s_nop 0
	v_pk_mul_f32 v[56:57], v[98:99], v[54:55]
	s_nop 0
	v_add_f32_e32 v56, v58, v56
	v_add_f32_e32 v63, v56, v57
	v_pk_mul_f32 v[56:57], v[98:99], v[52:53]
	s_nop 0
	v_add_f32_e32 v52, v59, v56
	v_add_f32_e32 v52, v52, v57
	v_pk_mul_f32 v[56:57], v[0:1], v[64:65]
	s_nop 0
	v_add_f32_e32 v56, v9, v56
	v_add_f32_e32 v67, v56, v57
	v_and_b32_e32 v57, 0xffff0000, v34
	v_and_b32_e32 v56, 0xffff0000, v30
	v_pk_mov_b32 v[58:59], v[64:65], v[56:57] op_sel:[1,0]
	s_nop 0
	v_pk_mul_f32 v[60:61], v[4:5], v[58:59]
	v_pk_mul_f32 v[0:1], v[0:1], v[58:59]
	v_add_f32_e32 v30, v62, v60
	v_add_f32_e32 v30, v30, v61
	v_pk_mul_f32 v[60:61], v[4:5], v[56:57]
	v_cvt_pk_bf16_f32 v30, v63, v30
	v_add_f32_e32 v0, v9, v0
	v_add_f32_e32 v34, v67, v60
	v_add_f32_e32 v56, v34, v61
	v_pk_mul_f32 v[60:61], v[76:77], v[68:69]
	v_add_f32_e32 v9, v0, v1
	v_add_f32_e32 v34, v10, v60
	v_add_f32_e32 v34, v34, v61
	v_lshlrev_b32_e32 v60, 16, v31
	v_lshlrev_b32_e32 v61, 16, v35
	v_pk_mov_b32 v[62:63], v[68:69], v[60:61] op_sel:[1,0]
	v_and_b32_e32 v35, 0xffff0000, v35
	v_pk_mul_f32 v[64:65], v[80:81], v[62:63]
	s_nop 0
	v_add_f32_e32 v64, v66, v64
	v_add_f32_e32 v71, v64, v65
	v_pk_mul_f32 v[64:65], v[80:81], v[60:61]
	s_nop 0
	v_add_f32_e32 v60, v34, v64
	v_and_b32_e32 v34, 0xffff0000, v31
	v_pk_mov_b32 v[66:67], v[42:43], v[34:35] op_sel:[1,0]
	v_mov_b32_e32 v64, s0
	v_pk_mul_f32 v[68:69], v[6:7], v[66:67]
	v_pk_mul_f32 v[42:43], v[2:3], v[42:43]
	v_add_f32_e32 v31, v70, v68
	v_add_f32_e32 v31, v31, v69
	v_mov_b32_e32 v68, s1
	v_cvt_pk_bf16_f32 v31, v71, v31
	v_add_f32_e32 v42, v11, v42
	v_readfirstlane_b32 s16, v64
	v_readfirstlane_b32 s17, v68
	s_load_dwordx2 s[16:17], s[16:17], 0xc0
	v_add_f32_e32 v64, v42, v43
	v_add_f32_e32 v60, v60, v65
	s_waitcnt vmcnt(13)
	v_and_b32_e32 v69, 0xffff0000, v26
	v_mov_b32_e32 v68, v57
	s_waitcnt lgkmcnt(0)
	v_mov_b64_e32 v[42:43], s[16:17]
	v_mad_i64_i32 v[42:43], s[16:17], v137, s24, v[42:43]
	v_lshl_add_u64 v[42:43], v[42:43], 0, v[110:111]
	v_add_co_u32_e32 v42, vcc, s26, v42
	v_pk_mul_f32 v[0:1], v[4:5], v[68:69]
	s_nop 0
	v_addc_co_u32_e32 v43, vcc, 0, v43, vcc
	global_store_dwordx4 v[42:43], v[28:31], off sc1
	v_add_f32_e32 v0, v9, v0
	v_add_f32_e32 v4, v0, v1
	v_pk_mul_f32 v[28:29], v[6:7], v[34:35]
	v_mov_b32_e32 v34, s1
	v_add_f32_e32 v28, v64, v28
	v_add_f32_e32 v31, v28, v29
	v_cvt_pk_bf16_f32 v28, v36, v44
	v_cvt_pk_bf16_f32 v29, v48, v32
	v_mov_b32_e32 v32, s0
	v_cvt_pk_bf16_f32 v30, v52, v56
	v_cvt_pk_bf16_f32 v31, v60, v31
	v_pk_mul_f32 v[0:1], v[76:77], v[62:63]
	v_readfirstlane_b32 s16, v32
	v_readfirstlane_b32 s17, v34
	s_load_dwordx2 s[16:17], s[16:17], 0xc0
	v_lshlrev_b32_e32 v71, 16, v27
	v_add_f32_e32 v0, v10, v0
	v_mov_b32_e32 v70, v61
	v_add_f32_e32 v5, v0, v1
	s_waitcnt lgkmcnt(0)
	v_mov_b64_e32 v[42:43], s[16:17]
	v_mad_i64_i32 v[42:43], s[16:17], v136, s24, v[42:43]
	v_lshl_add_u64 v[42:43], v[42:43], 0, v[110:111]
	v_add_co_u32_e32 v42, vcc, s26, v42
	v_pk_mul_f32 v[0:1], v[80:81], v[70:71]
	s_nop 0
	v_addc_co_u32_e32 v43, vcc, 0, v43, vcc
	global_store_dwordx4 v[42:43], v[28:31], off sc1
	v_lshlrev_b32_e32 v43, 16, v25
	v_mov_b32_e32 v42, v49
	v_and_b32_e32 v31, 0xffff0000, v24
	v_mov_b32_e32 v30, v45
	v_pk_mul_f32 v[12:13], v[16:17], v[30:31]
	v_lshlrev_b32_e32 v29, 16, v24
	v_add_f32_e32 v12, v21, v12
	v_add_f32_e32 v16, v12, v13
	v_pk_mul_f32 v[12:13], v[92:93], v[50:51]
	v_and_b32_e32 v25, 0xffff0000, v25
	v_add_f32_e32 v12, v22, v12
	v_add_f32_e32 v17, v12, v13
	v_pk_mul_f32 v[12:13], v[96:97], v[42:43]
	v_mov_b32_e32 v24, v33
	v_add_f32_e32 v12, v17, v12
	v_add_f32_e32 v17, v12, v13
	v_pk_mul_f32 v[12:13], v[14:15], v[40:41]
	v_add_f32_e32 v0, v5, v0
	v_add_f32_e32 v12, v23, v12
	v_add_f32_e32 v14, v12, v13
	v_pk_mul_f32 v[12:13], v[18:19], v[24:25]
	v_add_f32_e32 v5, v0, v1
	v_add_f32_e32 v12, v14, v12
	v_pk_mul_f32 v[0:1], v[2:3], v[66:67]
	v_lshlrev_b32_e32 v65, 16, v26
	v_and_b32_e32 v27, 0xffff0000, v27
	v_add_f32_e32 v14, v12, v13
	v_pk_mul_f32 v[12:13], v[94:95], v[54:55]
	v_add_f32_e32 v0, v11, v0
	v_mov_b32_e32 v26, v35
	v_mov_b32_e32 v28, v37
	v_add_f32_e32 v8, v8, v12
	v_mov_b32_e32 v64, v53
	v_add_f32_e32 v2, v0, v1
	v_pk_mul_f32 v[0:1], v[6:7], v[26:27]
	v_pk_mul_f32 v[28:29], v[114:115], v[28:29]
	v_add_f32_e32 v8, v8, v13
	v_pk_mul_f32 v[12:13], v[98:99], v[64:65]
	v_add_f32_e32 v0, v2, v0
	v_add_f32_e32 v20, v20, v28
	v_add_f32_e32 v8, v8, v12
	v_add_f32_e32 v3, v0, v1
	v_add_f32_e32 v20, v20, v29
	v_add_f32_e32 v8, v8, v13
	v_cvt_pk_bf16_f32 v0, v20, v16
	v_cvt_pk_bf16_f32 v1, v17, v14
	v_cvt_pk_bf16_f32 v2, v8, v4
	v_cvt_pk_bf16_f32 v3, v5, v3
	s_nop 0
	v_readfirstlane_b32 s16, v133
	v_readfirstlane_b32 s17, v134
	s_load_dwordx2 s[16:17], s[16:17], 0xc0
	s_waitcnt lgkmcnt(0)
	v_mov_b64_e32 v[4:5], s[16:17]
	v_mad_i64_i32 v[4:5], s[16:17], v135, s24, v[4:5]
	v_lshl_add_u64 v[4:5], v[4:5], 0, v[110:111]
	v_add_co_u32_e32 v4, vcc, 0x14000000, v4
	s_nop 1
	v_addc_co_u32_e32 v5, vcc, 0, v5, vcc
	v_cmp_lt_i32_e32 vcc, s27, v109
	s_or_b64 s[10:11], vcc, s[10:11]
	global_store_dwordx4 v[4:5], v[0:3], off sc1
	s_andn2_b64 exec, exec, s[10:11]
	s_cbranch_execz .LBB0_487
.LBB0_481:
	v_mul_hi_i32 v0, v109, s21
	v_lshrrev_b32_e32 v1, 31, v0
	v_ashrrev_i32_e32 v0, 4, v0
	v_add_u32_e32 v26, v0, v1
	v_mad_u64_u32 v[32:33], s[16:17], v26, s22, v[108:109]
	v_ashrrev_i32_e32 v33, 31, v32
	v_lshlrev_b64 v[8:9], 2, v[32:33]
	v_lshl_add_u64 v[4:5], s[6:7], 0, v[8:9]
	v_add_co_u32_e32 v10, vcc, s23, v4
	global_load_dwordx4 v[80:83], v[4:5], off offset:16 nt
	global_load_dwordx4 v[96:99], v[4:5], off nt
	global_load_dwordx4 v[0:3], v[4:5], off offset:3088 nt
	global_load_dwordx4 v[12:15], v[4:5], off offset:3072 nt
	v_addc_co_u32_e32 v11, vcc, 0, v5, vcc
	v_add_co_u32_e32 v20, vcc, 0x2000, v4
	v_lshl_add_u64 v[6:7], v[4:5], 0, s[12:13]
	global_load_dwordx4 v[92:95], v[10:11], off offset:2048 nt
	global_load_dwordx4 v[76:79], v[6:7], off offset:16 nt
	v_lshl_add_u64 v[10:11], v[4:5], 0, s[14:15]
	v_addc_co_u32_e32 v21, vcc, 0, v5, vcc
	v_lshl_add_u64 v[24:25], s[8:9], 0, v[8:9]
	global_load_dwordx4 v[16:19], v[20:21], off offset:1024 nt
	global_load_dwordx4 v[4:7], v[10:11], off offset:16 nt
	s_nop 0
	global_load_dwordx4 v[8:11], v[24:25], off offset:16 nt
	global_load_dwordx4 v[20:23], v[24:25], off nt
	v_lshlrev_b32_e32 v149, 4, v26
	v_cmp_ne_u32_sdwa s[16:17], v26, v132 src0_sel:BYTE_0 src1_sel:DWORD
	v_mov_b32_e32 v24, 0
	v_mov_b32_e32 v25, 0
	v_mov_b32_e32 v26, 0
	v_mov_b32_e32 v27, 0
	s_and_saveexec_b64 s[18:19], s[16:17]
	s_cbranch_execz .LBB0_483
	v_mov_b32_e32 v24, s0
	v_mov_b32_e32 v25, s1
	v_add_u32_e32 v26, -3, v149
	v_readfirstlane_b32 s28, v24
	v_readfirstlane_b32 s29, v25
	s_load_dwordx2 s[28:29], s[28:29], 0xc0
	s_waitcnt lgkmcnt(0)
	v_mov_b64_e32 v[24:25], s[28:29]
	v_mad_i64_i32 v[24:25], s[28:29], v26, s24, v[24:25]
	v_lshl_add_u64 v[24:25], v[32:33], 1, v[24:25]
	v_add_co_u32_e32 v24, vcc, 0xe000000, v24
	s_nop 1
	v_addc_co_u32_e32 v25, vcc, 0, v25, vcc
	global_load_dwordx4 v[24:27], v[24:25], off nt
.LBB0_483:
	s_or_b64 exec, exec, s[18:19]
	v_mov_b32_e32 v28, 0
	v_mov_b32_e32 v29, 0
	v_mov_b32_e32 v30, 0
	v_mov_b32_e32 v31, 0
	s_and_saveexec_b64 s[18:19], s[16:17]
	s_cbranch_execz .LBB0_485
	v_mov_b32_e32 v28, s0
	v_mov_b32_e32 v29, s1
	v_add_u32_e32 v30, -2, v149
	v_readfirstlane_b32 s28, v28
	v_readfirstlane_b32 s29, v29
	s_load_dwordx2 s[28:29], s[28:29], 0xc0
	s_waitcnt lgkmcnt(0)
	v_mov_b64_e32 v[28:29], s[28:29]
	v_mad_i64_i32 v[28:29], s[28:29], v30, s24, v[28:29]
	v_lshl_add_u64 v[28:29], v[32:33], 1, v[28:29]
	v_add_co_u32_e32 v28, vcc, 0xe000000, v28
	s_nop 1
	v_addc_co_u32_e32 v29, vcc, 0, v29, vcc
	global_load_dwordx4 v[28:31], v[28:29], off nt
.LBB0_485:
	s_or_b64 exec, exec, s[18:19]
	v_mov_b32_e32 v100, 0
	v_mov_b32_e32 v101, 0
	v_mov_b32_e32 v102, 0
	v_mov_b32_e32 v103, 0
	s_and_saveexec_b64 s[18:19], s[16:17]
	s_cbranch_execz .LBB0_480
	v_mov_b32_e32 v34, s0
	v_mov_b32_e32 v35, s1
	v_add_u32_e32 v36, -1, v149
	v_readfirstlane_b32 s16, v34
	v_readfirstlane_b32 s17, v35
	s_load_dwordx2 s[16:17], s[16:17], 0xc0
	s_waitcnt lgkmcnt(0)
	v_mov_b64_e32 v[34:35], s[16:17]
	v_mad_i64_i32 v[34:35], s[16:17], v36, s24, v[34:35]
	v_lshl_add_u64 v[34:35], v[32:33], 1, v[34:35]
	v_add_co_u32_e32 v34, vcc, 0xe000000, v34
	s_nop 1
	v_addc_co_u32_e32 v35, vcc, 0, v35, vcc
	global_load_dwordx4 v[100:103], v[34:35], off nt
	s_branch .LBB0_480
.LBB0_487:
	s_or_b64 exec, exec, s[4:5]
	s_waitcnt lgkmcnt(0)
	s_cmpk_lt_i32 s33, 0xc1
	s_cbranch_scc0 .LBB0_495
	v_mov_b32_e32 v2, s0
	v_mov_b32_e32 v3, s1
	v_mov_b32_e32 v0, s0
	v_readfirstlane_b32 s4, v2
	v_readfirstlane_b32 s5, v3
	v_mov_b32_e32 v2, s0
	v_mov_b32_e32 v3, s1
	v_mov_b32_e32 v1, s1
	v_readfirstlane_b32 s8, v2
	v_readfirstlane_b32 s9, v3
	v_mov_b32_e32 v2, s0
	v_mov_b32_e32 v3, s1
	s_cmpk_gt_i32 s2, 0x1ff
	s_nop 0
	v_readfirstlane_b32 s10, v2
	v_readfirstlane_b32 s11, v3
	v_readfirstlane_b32 s12, v0
	v_readfirstlane_b32 s13, v1
	s_cbranch_scc1 .LBB0_495
	s_load_dwordx2 s[4:5], s[4:5], 0xc0
	v_lshrrev_b32_e32 v2, 1, v254
	v_and_b32_e32 v154, 0x1e0, v2
	v_mov_b32_e32 v141, 0
	v_and_b32_e32 v7, 31, v254
	s_waitcnt lgkmcnt(0)
	s_add_u32 s3, s4, 0x1a000000
	s_addc_u32 s20, s5, 0
	s_ashr_i32 s4, s2, 6
	s_lshl_b32 s6, s2, 8
	s_ashr_i32 s5, s4, 31
	s_and_b32 s14, s6, 0xf00
	s_lshl_b64 s[6:7], s[4:5], 21
	s_lshl_b32 s21, s2, 2
	s_add_u32 s6, s3, s6
	s_addc_u32 s7, s20, s7
	v_add_lshl_u32 v140, s14, v154, 9
	s_lshl_b32 s4, s2, 3
	s_mov_b32 s5, 0
	v_lshl_add_u64 v[0:1], s[6:7], 0, v[140:141]
	s_and_b32 s4, s4, 0x180
	v_lshl_add_u64 v[0:1], v[0:1], 0, s[4:5]
	v_lshlrev_b32_e32 v140, 9, v7
	v_lshl_add_u64 v[0:1], v[0:1], 0, v[140:141]
	v_and_b32_e32 v140, 16, v2
	v_lshl_add_u64 v[4:5], v[0:1], 0, v[140:141]
	global_load_dwordx4 v[0:3], v[4:5], off nt
	global_load_dwordx4 v[136:139], v[4:5], off offset:32 nt
	global_load_dwordx4 v[132:135], v[4:5], off offset:64 nt
	global_load_dwordx4 v[128:131], v[4:5], off offset:96 nt
	v_mbcnt_lo_u32_b32 v12, -1, 0
	v_mbcnt_hi_u32_b32 v12, -1, v12
	v_and_b32_e32 v21, 64, v12
	v_xor_b32_e32 v13, 32, v12
	v_add_u32_e32 v21, 64, v21
	v_cmp_lt_i32_e32 vcc, v13, v21
	v_lshlrev_b32_e32 v6, 4, v254
	s_movk_i32 s4, 0x90
	v_cndmask_b32_e32 v12, v12, v13, vcc
	v_lshrrev_b32_e32 v140, 3, v254
	s_load_dwordx2 s[14:15], s[8:9], 0xc0
	s_load_dwordx2 s[16:17], s[10:11], 0xc0
	s_load_dwordx2 s[6:7], s[12:13], 0xc0
	v_and_b32_e32 v9, 0x70, v6
	v_lshlrev_b32_e32 v155, 2, v12
	v_mul_lo_u32 v12, v140, s4
	v_add3_u32 v157, v12, v9, 0
	v_lshlrev_b64 v[12:13], 9, v[140:141]
	v_and_b32_e32 v5, 63, v254
	v_or_b32_e32 v12, v12, v9
	v_or_b32_e32 v8, 32, v5
	v_or_b32_e32 v6, 0x60, v5
	s_waitcnt lgkmcnt(0)
	v_lshl_add_u64 v[12:13], s[14:15], 0, v[12:13]
	s_mov_b64 s[8:9], 0x3320c00
	v_lshrrev_b32_e32 v140, 5, v254
	v_lshlrev_b32_e32 v4, 8, v7
	v_bfe_u32 v10, v254, 5, 1
	v_mul_u32_u24_e32 v14, 0x90, v7
	v_mul_u32_u24_e32 v15, 0x90, v8
	v_mul_u32_u24_e32 v16, 0x90, v6
	v_or_b32_e32 v6, 0xa0, v5
	s_movk_i32 s10, 0x208
	v_mul_u32_u24_e32 v19, 0x208, v7
	v_mul_u32_u24_e32 v20, 0x208, v8
	v_lshlrev_b32_e32 v8, 10, v7
	v_lshlrev_b32_e32 v7, 4, v7
	v_lshl_add_u64 v[142:143], v[12:13], 0, s[8:9]
	v_lshlrev_b64 v[12:13], 9, v[140:141]
	v_lshl_add_u32 v11, v10, 4, 0
	v_mul_u32_u24_e32 v17, 0x90, v6
	v_or_b32_e32 v5, 0xe0, v5
	v_lshlrev_b32_e32 v6, 3, v10
	v_mul_lo_u32 v9, v140, s10
	v_or_b32_e32 v12, v12, v7
	v_mul_u32_u24_e32 v5, 0x90, v5
	v_sub_u32_e32 v18, v11, v6
	v_lshlrev_b32_e32 v10, 2, v10
	v_add3_u32 v9, v9, v7, 0
	v_lshl_add_u64 v[12:13], s[16:17], 0, v[12:13]
	s_mov_b64 s[8:9], 0x3520c00
	v_add_u32_e32 v156, 0xfffffe00, v254
	s_lshl_b32 s22, s33, 2
	v_add_u32_e32 v158, 0x9000, v9
	v_lshl_add_u64 v[144:145], v[12:13], 0, s[8:9]
	s_mov_b64 s[8:9], 0x8000
	s_movk_i32 s23, 0x5ff
	s_mov_b64 s[10:11], 0x2000
	v_add_u32_e32 v159, v11, v14
	v_add_u32_e32 v160, v11, v15
	v_add_u32_e32 v161, v11, v16
	v_add_u32_e32 v162, v11, v17
	v_add_u32_e32 v163, v11, v5
	s_mov_b32 s24, 0xff800000
	v_add_u32_e32 v164, v18, v19
	v_add_u32_e32 v165, v18, v20
	v_lshlrev_b32_e32 v146, 1, v4
	v_lshlrev_b32_e32 v148, 1, v6
	v_lshlrev_b32_e32 v150, 1, v8
	v_lshlrev_b32_e32 v152, 1, v10
	s_mov_b64 s[12:13], 0x1b000600
	s_mov_b32 s25, 0x1b000000
	s_mov_b32 s26, s2

.LBB0_491:
	global_load_dwordx4 v[8:11], v[4:5], off nt
	v_add_u32_e32 v7, 0x200, v7
	v_cmp_lt_u32_e32 vcc, s23, v7
	v_lshl_add_u64 v[4:5], v[4:5], 0, s[8:9]
	s_or_b64 s[18:19], vcc, s[18:19]
	s_waitcnt vmcnt(0)
	ds_write_b128 v6, v[8:11]
	v_add_u32_e32 v6, 0x2400, v6
	s_andn2_b64 exec, exec, s[18:19]
	s_cbranch_execnz .LBB0_491
	s_or_b64 exec, exec, s[18:19]
	s_lshl_b32 s4, s4, 15
	s_add_u32 s14, s14, s4
	s_addc_u32 s15, s15, 0
	v_lshl_add_u64 v[4:5], v[144:145], 0, s[14:15]
	s_mov_b64 s[14:15], 0
	v_mov_b32_e32 v6, v158
	v_mov_b32_e32 v7, v156
.LBB0_493:
	global_load_dwordx4 v[8:11], v[4:5], off nt
	v_add_u32_e32 v7, 0x200, v7
	v_cmp_lt_u32_e32 vcc, s23, v7
	v_lshl_add_u64 v[4:5], v[4:5], 0, s[10:11]
	s_or_b64 s[14:15], vcc, s[14:15]
	s_waitcnt vmcnt(0)
	ds_write2_b64 v6, v[8:9], v[10:11] offset1:1
	v_add_u32_e32 v6, 0x2080, v6
	s_andn2_b64 exec, exec, s[14:15]
	s_cbranch_execnz .LBB0_493
	s_or_b64 exec, exec, s[14:15]
	s_waitcnt lgkmcnt(0)
	s_barrier
	ds_read_b128 v[4:7], v159
	ds_read_b128 v[8:11], v159 offset:32
	s_waitcnt lgkmcnt(1)
	v_mfma_f32_32x32x16_bf16 v[112:127], v[4:7], v[0:3], 0
	s_lshl_b32 s4, s26, 8
	s_and_b32 s19, s4, 0xf00
	s_add_i32 s18, s26, s33
	s_cmpk_lt_i32 s18, 0x200
	s_cselect_b64 s[14:15], -1, 0
	s_and_b64 s[28:29], s[14:15], exec
	s_cselect_b32 s4, s18, s26
	s_waitcnt lgkmcnt(0)
	v_mfma_f32_32x32x16_bf16 v[112:127], v[8:11], v[136:139], v[112:127]
	ds_read_b128 v[4:7], v159 offset:64
	ds_read_b128 v[8:11], v159 offset:96
	s_ashr_i32 s28, s4, 6
	s_ashr_i32 s29, s28, 31
	s_lshl_b32 s27, s4, 8
	s_and_b32 s27, s27, 0xf00
	s_lshl_b64 s[28:29], s[28:29], 21
	s_add_u32 s28, s3, s28
	s_waitcnt lgkmcnt(1)
	v_mfma_f32_32x32x16_bf16 v[112:127], v[4:7], v[132:135], v[112:127]
	s_addc_u32 s29, s20, s29
	v_add_lshl_u32 v140, s27, v154, 9
	v_lshl_add_u64 v[190:191], s[28:29], 0, v[140:141]
	s_lshl_b32 s4, s4, 3
	s_and_b32 s4, s4, 0x180
	s_lshl_b64 s[16:17], s[16:17], 23
	s_add_u32 s16, s6, s16
	s_waitcnt lgkmcnt(0)
	v_mfma_f32_32x32x16_bf16 v[112:127], v[8:11], v[128:131], v[112:127]
	ds_read_b128 v[4:7], v160
	ds_read_b128 v[8:11], v160 offset:32
	s_addc_u32 s17, s7, s17
	s_add_i32 s21, s21, s22
	s_waitcnt lgkmcnt(1)
	v_mfma_f32_32x32x16_bf16 v[96:111], v[4:7], v[0:3], 0
	s_waitcnt lgkmcnt(0)
	v_mfma_f32_32x32x16_bf16 v[96:111], v[8:11], v[136:139], v[96:111]
	ds_read_b128 v[4:7], v160 offset:64
	ds_read_b128 v[8:11], v160 offset:96
	s_waitcnt lgkmcnt(1)
	v_mfma_f32_32x32x16_bf16 v[96:111], v[4:7], v[132:135], v[96:111]
	s_waitcnt lgkmcnt(0)
	v_mfma_f32_32x32x16_bf16 v[96:111], v[8:11], v[128:131], v[96:111]
	ds_read_b128 v[4:7], v159 offset:9216
	ds_read_b128 v[8:11], v159 offset:9248
	s_waitcnt lgkmcnt(1)
	v_mfma_f32_32x32x16_bf16 v[80:95], v[4:7], v[0:3], 0
	s_waitcnt lgkmcnt(0)
	v_mfma_f32_32x32x16_bf16 v[80:95], v[8:11], v[136:139], v[80:95]
	ds_read_b128 v[4:7], v159 offset:9280
	ds_read_b128 v[8:11], v159 offset:9312
	s_waitcnt lgkmcnt(1)
	v_mfma_f32_32x32x16_bf16 v[80:95], v[4:7], v[132:135], v[80:95]
	s_waitcnt lgkmcnt(0)
	v_mfma_f32_32x32x16_bf16 v[80:95], v[8:11], v[128:131], v[80:95]
	ds_read_b128 v[4:7], v161
	ds_read_b128 v[8:11], v161 offset:32
	s_waitcnt lgkmcnt(1)
	v_mfma_f32_32x32x16_bf16 v[64:79], v[4:7], v[0:3], 0
	s_waitcnt lgkmcnt(0)
	v_mfma_f32_32x32x16_bf16 v[64:79], v[8:11], v[136:139], v[64:79]
	ds_read_b128 v[4:7], v161 offset:64
	ds_read_b128 v[8:11], v161 offset:96
	s_waitcnt lgkmcnt(1)
	v_mfma_f32_32x32x16_bf16 v[64:79], v[4:7], v[132:135], v[64:79]
	s_waitcnt lgkmcnt(0)
	v_mfma_f32_32x32x16_bf16 v[64:79], v[8:11], v[128:131], v[64:79]
	ds_read_b128 v[4:7], v159 offset:18432
	ds_read_b128 v[8:11], v159 offset:18464
	s_waitcnt lgkmcnt(1)
	v_mfma_f32_32x32x16_bf16 v[48:63], v[4:7], v[0:3], 0
	s_waitcnt lgkmcnt(0)
	v_mfma_f32_32x32x16_bf16 v[48:63], v[8:11], v[136:139], v[48:63]
	ds_read_b128 v[4:7], v159 offset:18496
	ds_read_b128 v[8:11], v159 offset:18528
	s_waitcnt lgkmcnt(1)
	v_mfma_f32_32x32x16_bf16 v[48:63], v[4:7], v[132:135], v[48:63]
	ds_read_b128 v[4:7], v162
	s_waitcnt lgkmcnt(1)
	v_mfma_f32_32x32x16_bf16 v[48:63], v[8:11], v[128:131], v[48:63]
	ds_read_b128 v[8:11], v162 offset:32
	s_waitcnt lgkmcnt(1)
	v_mfma_f32_32x32x16_bf16 v[32:47], v[4:7], v[0:3], 0
	ds_read_b128 v[4:7], v162 offset:64
	s_waitcnt lgkmcnt(1)
	v_mfma_f32_32x32x16_bf16 v[32:47], v[8:11], v[136:139], v[32:47]
	ds_read_b128 v[8:11], v162 offset:96
	s_waitcnt lgkmcnt(1)
	v_mfma_f32_32x32x16_bf16 v[32:47], v[4:7], v[132:135], v[32:47]
	ds_read_b128 v[4:7], v159 offset:27648
	ds_read_b128 v[12:15], v159 offset:27680
	ds_read_b128 v[166:169], v159 offset:27712
	ds_read_b128 v[170:173], v159 offset:27744
	ds_read_b128 v[174:177], v163
	ds_read_b128 v[178:181], v163 offset:32
	ds_read_b128 v[182:185], v163 offset:64
	ds_read_b128 v[186:189], v163 offset:96
	s_waitcnt lgkmcnt(8)
	v_mfma_f32_32x32x16_bf16 v[32:47], v[8:11], v[128:131], v[32:47]
	v_max3_f32 v8, v112, s24, v113
	v_max3_f32 v8, v8, v114, v115
	v_max3_f32 v8, v8, v116, v117
	v_max3_f32 v8, v8, v118, v119
	v_max3_f32 v8, v8, v120, v121
	v_max3_f32 v8, v8, v122, v123
	v_max3_f32 v8, v8, v124, v125
	s_waitcnt lgkmcnt(7)
	v_mfma_f32_32x32x16_bf16 v[16:31], v[4:7], v[0:3], 0
	v_max3_f32 v4, v8, v126, v127
	v_max3_f32 v4, v4, v96, v97
	v_max3_f32 v4, v4, v98, v99
	v_max3_f32 v4, v4, v100, v101
	v_max3_f32 v4, v4, v102, v103
	v_max3_f32 v4, v4, v104, v105
	v_max3_f32 v4, v4, v106, v107
	v_max3_f32 v4, v4, v108, v109
	v_max3_f32 v4, v4, v110, v111
	v_max3_f32 v4, v4, v80, v81
	v_max3_f32 v4, v4, v82, v83
	v_max3_f32 v4, v4, v84, v85
	v_max3_f32 v4, v4, v86, v87
	v_max3_f32 v4, v4, v88, v89
	v_max3_f32 v4, v4, v90, v91
	v_max3_f32 v4, v4, v92, v93
	v_max3_f32 v4, v4, v94, v95
	v_max3_f32 v4, v4, v64, v65
	v_max3_f32 v4, v4, v66, v67
	v_max3_f32 v4, v4, v68, v69
	v_max3_f32 v4, v4, v70, v71
	v_max3_f32 v4, v4, v72, v73
	v_max3_f32 v4, v4, v74, v75
	v_max3_f32 v4, v4, v76, v77
	v_max3_f32 v4, v4, v78, v79
	v_max3_f32 v4, v4, v48, v49
	v_max3_f32 v4, v4, v50, v51
	s_waitcnt lgkmcnt(6)
	v_mfma_f32_32x32x16_bf16 v[16:31], v[12:15], v[136:139], v[16:31]
	v_max3_f32 v140, v4, v52, v53
	v_max3_f32 v140, v140, v54, v55
	v_max3_f32 v140, v140, v56, v57
	v_max3_f32 v140, v140, v58, v59
	v_max3_f32 v140, v140, v60, v61
	v_max3_f32 v140, v140, v62, v63
	v_max3_f32 v140, v140, v32, v33
	s_waitcnt lgkmcnt(3)
	v_mfma_f32_32x32x16_bf16 v[0:15], v[174:177], v[0:3], 0
	v_max3_f32 v140, v140, v34, v35
	v_mfma_f32_32x32x16_bf16 v[16:31], v[166:169], v[132:135], v[16:31]
	s_waitcnt lgkmcnt(2)
	v_mfma_f32_32x32x16_bf16 v[0:15], v[178:181], v[136:139], v[0:15]
	v_max3_f32 v136, v140, v36, v37
	v_max3_f32 v136, v136, v38, v39
	v_max3_f32 v136, v136, v40, v41
	v_max3_f32 v136, v136, v42, v43
	v_max3_f32 v136, v136, v44, v45
	v_max3_f32 v136, v136, v46, v47
	v_add_lshl_u32 v140, s19, v154, 11
	v_mfma_f32_32x32x16_bf16 v[16:31], v[170:173], v[128:131], v[16:31]
	s_waitcnt lgkmcnt(1)
	v_mfma_f32_32x32x16_bf16 v[0:15], v[182:185], v[132:135], v[0:15]
	s_nop 9
	v_max3_f32 v136, v136, v16, v17
	v_max3_f32 v132, v136, v18, v19
	v_max3_f32 v132, v132, v20, v21
	v_max3_f32 v132, v132, v22, v23
	v_max3_f32 v132, v132, v24, v25
	v_max3_f32 v132, v132, v26, v27
	v_max3_f32 v132, v132, v28, v29
	s_waitcnt lgkmcnt(0)
	v_mfma_f32_32x32x16_bf16 v[0:15], v[186:189], v[128:131], v[0:15]
	v_max3_f32 v132, v132, v30, v31
	s_nop 10
	v_max3_f32 v128, v132, v0, v1
	v_max3_f32 v128, v128, v2, v3
	v_max3_f32 v128, v128, v4, v5
	v_max3_f32 v128, v128, v6, v7
	v_max3_f32 v128, v128, v8, v9
	v_max3_f32 v128, v128, v10, v11
	v_max3_f32 v128, v128, v12, v13
	v_max3_f32 v130, v128, v14, v15
	ds_bpermute_b32 v131, v155, v130
	v_lshl_add_u64 v[128:129], v[190:191], 0, s[4:5]
	s_lshl_b32 s4, s26, 3
	s_and_b32 s4, s4, 0x180
	s_mov_b32 s26, s18
	s_waitcnt lgkmcnt(0)
	v_max_f32_e32 v131, v131, v131
	v_max_f32_e32 v130, v130, v131
	v_sub_f32_e32 v112, v112, v130
	v_exp_f32_e32 v112, v112
	v_sub_f32_e32 v113, v113, v130
	v_exp_f32_e32 v113, v113
	v_sub_f32_e32 v114, v114, v130
	v_exp_f32_e32 v114, v114
	v_sub_f32_e32 v115, v115, v130
	v_exp_f32_e32 v115, v115
	v_sub_f32_e32 v116, v116, v130
	v_add_f32_e32 v131, 0, v112
	v_exp_f32_e32 v116, v116
	v_sub_f32_e32 v117, v117, v130
	v_add_f32_e32 v131, v113, v131
	v_exp_f32_e32 v117, v117
	v_sub_f32_e32 v118, v118, v130
	v_add_f32_e32 v131, v114, v131
	v_exp_f32_e32 v118, v118
	v_sub_f32_e32 v119, v119, v130
	v_add_f32_e32 v131, v115, v131
	v_exp_f32_e32 v119, v119
	v_sub_f32_e32 v120, v120, v130
	v_add_f32_e32 v131, v116, v131
	v_exp_f32_e32 v120, v120
	v_sub_f32_e32 v121, v121, v130
	v_add_f32_e32 v131, v117, v131
	v_exp_f32_e32 v121, v121
	v_sub_f32_e32 v122, v122, v130
	v_add_f32_e32 v131, v118, v131
	v_exp_f32_e32 v122, v122
	v_sub_f32_e32 v123, v123, v130
	v_add_f32_e32 v131, v119, v131
	v_exp_f32_e32 v123, v123
	v_sub_f32_e32 v124, v124, v130
	v_add_f32_e32 v131, v120, v131
	v_exp_f32_e32 v124, v124
	v_sub_f32_e32 v125, v125, v130
	v_add_f32_e32 v131, v121, v131
	v_exp_f32_e32 v125, v125
	v_sub_f32_e32 v126, v126, v130
	v_add_f32_e32 v131, v122, v131
	v_exp_f32_e32 v126, v126
	v_sub_f32_e32 v127, v127, v130
	v_add_f32_e32 v131, v123, v131
	v_exp_f32_e32 v127, v127
	v_sub_f32_e32 v96, v96, v130
	v_add_f32_e32 v131, v124, v131
	v_exp_f32_e32 v96, v96
	v_sub_f32_e32 v97, v97, v130
	v_add_f32_e32 v131, v125, v131
	v_exp_f32_e32 v97, v97
	v_sub_f32_e32 v98, v98, v130
	v_add_f32_e32 v131, v126, v131
	v_exp_f32_e32 v98, v98
	v_sub_f32_e32 v99, v99, v130
	v_add_f32_e32 v131, v127, v131
	v_exp_f32_e32 v99, v99
	v_sub_f32_e32 v100, v100, v130
	v_add_f32_e32 v131, v96, v131
	v_exp_f32_e32 v100, v100
	v_sub_f32_e32 v101, v101, v130
	v_add_f32_e32 v131, v97, v131
	v_exp_f32_e32 v101, v101
	v_sub_f32_e32 v102, v102, v130
	v_add_f32_e32 v131, v98, v131
	v_exp_f32_e32 v102, v102
	v_sub_f32_e32 v103, v103, v130
	v_add_f32_e32 v131, v99, v131
	v_exp_f32_e32 v103, v103
	v_sub_f32_e32 v104, v104, v130
	v_add_f32_e32 v131, v100, v131
	v_exp_f32_e32 v104, v104
	v_sub_f32_e32 v105, v105, v130
	v_add_f32_e32 v131, v101, v131
	v_exp_f32_e32 v105, v105
	v_sub_f32_e32 v106, v106, v130
	v_add_f32_e32 v131, v102, v131
	v_exp_f32_e32 v106, v106
	v_sub_f32_e32 v107, v107, v130
	v_add_f32_e32 v131, v103, v131
	v_exp_f32_e32 v107, v107
	v_sub_f32_e32 v108, v108, v130
	v_add_f32_e32 v131, v104, v131
	v_exp_f32_e32 v108, v108
	v_sub_f32_e32 v109, v109, v130
	v_add_f32_e32 v131, v105, v131
	v_exp_f32_e32 v109, v109
	v_sub_f32_e32 v110, v110, v130
	v_add_f32_e32 v131, v106, v131
	v_exp_f32_e32 v110, v110
	v_sub_f32_e32 v111, v111, v130
	v_add_f32_e32 v131, v107, v131
	v_exp_f32_e32 v111, v111
	v_sub_f32_e32 v80, v80, v130
	v_add_f32_e32 v131, v108, v131
	v_exp_f32_e32 v132, v80
	v_sub_f32_e32 v80, v81, v130
	v_add_f32_e32 v131, v109, v131
	v_exp_f32_e32 v133, v80
	v_sub_f32_e32 v80, v82, v130
	v_add_f32_e32 v131, v110, v131
	v_exp_f32_e32 v134, v80
	v_sub_f32_e32 v81, v83, v130
	v_add_f32_e32 v80, v111, v131
	v_exp_f32_e32 v131, v81
	v_sub_f32_e32 v81, v84, v130
	v_add_f32_e32 v80, v132, v80
	v_exp_f32_e32 v135, v81
	v_sub_f32_e32 v81, v85, v130
	v_add_f32_e32 v80, v133, v80
	v_exp_f32_e32 v136, v81
	v_sub_f32_e32 v81, v86, v130
	v_add_f32_e32 v80, v134, v80
	v_exp_f32_e32 v137, v81
	v_sub_f32_e32 v81, v87, v130
	v_add_f32_e32 v80, v131, v80
	v_exp_f32_e32 v138, v81
	v_sub_f32_e32 v81, v88, v130
	v_add_f32_e32 v80, v135, v80
	v_exp_f32_e32 v88, v81
	v_sub_f32_e32 v81, v89, v130
	v_add_f32_e32 v80, v136, v80
	v_exp_f32_e32 v89, v81
	v_sub_f32_e32 v81, v90, v130
	v_add_f32_e32 v80, v137, v80
	v_exp_f32_e32 v90, v81
	v_sub_f32_e32 v81, v91, v130
	v_add_f32_e32 v80, v138, v80
	v_exp_f32_e32 v91, v81
	v_sub_f32_e32 v81, v92, v130
	v_add_f32_e32 v80, v88, v80
	v_exp_f32_e32 v92, v81
	v_sub_f32_e32 v81, v93, v130
	v_add_f32_e32 v80, v89, v80
	v_exp_f32_e32 v93, v81
	v_sub_f32_e32 v81, v94, v130
	v_add_f32_e32 v80, v90, v80
	v_exp_f32_e32 v94, v81
	v_sub_f32_e32 v81, v95, v130
	v_add_f32_e32 v80, v91, v80
	v_exp_f32_e32 v95, v81
	v_sub_f32_e32 v64, v64, v130
	v_add_f32_e32 v80, v92, v80
	v_exp_f32_e32 v139, v64
	v_sub_f32_e32 v64, v65, v130
	v_add_f32_e32 v80, v93, v80
	v_exp_f32_e32 v147, v64
	v_sub_f32_e32 v64, v66, v130
	v_add_f32_e32 v80, v94, v80
	v_exp_f32_e32 v149, v64
	v_sub_f32_e32 v65, v67, v130
	v_add_f32_e32 v64, v95, v80
	v_exp_f32_e32 v151, v65
	v_sub_f32_e32 v65, v68, v130
	v_add_f32_e32 v64, v139, v64
	v_exp_f32_e32 v153, v65
	v_sub_f32_e32 v65, v69, v130
	v_add_f32_e32 v64, v147, v64
	v_exp_f32_e32 v166, v65
	v_sub_f32_e32 v65, v70, v130
	v_add_f32_e32 v64, v149, v64
	v_exp_f32_e32 v167, v65
	v_sub_f32_e32 v65, v71, v130
	v_add_f32_e32 v64, v151, v64
	v_exp_f32_e32 v168, v65
	v_sub_f32_e32 v65, v72, v130
	v_add_f32_e32 v64, v153, v64
	v_exp_f32_e32 v169, v65
	v_sub_f32_e32 v65, v73, v130
	v_add_f32_e32 v64, v166, v64
	v_exp_f32_e32 v170, v65
	v_sub_f32_e32 v65, v74, v130
	v_add_f32_e32 v64, v167, v64
	v_exp_f32_e32 v171, v65
	v_sub_f32_e32 v65, v75, v130
	v_add_f32_e32 v64, v168, v64
	v_exp_f32_e32 v172, v65
	v_sub_f32_e32 v65, v76, v130
	v_add_f32_e32 v64, v169, v64
	v_exp_f32_e32 v173, v65
	v_sub_f32_e32 v65, v77, v130
	v_add_f32_e32 v64, v170, v64
	v_exp_f32_e32 v174, v65
	v_sub_f32_e32 v65, v78, v130
	v_add_f32_e32 v64, v171, v64
	v_exp_f32_e32 v175, v65
	v_sub_f32_e32 v65, v79, v130
	v_add_f32_e32 v64, v172, v64
	v_exp_f32_e32 v176, v65
	v_sub_f32_e32 v48, v48, v130
	v_add_f32_e32 v64, v173, v64
	v_exp_f32_e32 v177, v48
	v_sub_f32_e32 v48, v49, v130
	v_add_f32_e32 v64, v174, v64
	v_exp_f32_e32 v178, v48
	v_sub_f32_e32 v48, v50, v130
	v_add_f32_e32 v64, v175, v64
	v_exp_f32_e32 v179, v48
	v_sub_f32_e32 v49, v51, v130
	v_add_f32_e32 v48, v176, v64
	v_exp_f32_e32 v180, v49
	v_sub_f32_e32 v49, v52, v130
	v_add_f32_e32 v48, v177, v48
	v_exp_f32_e32 v181, v49
	v_sub_f32_e32 v49, v53, v130
	v_add_f32_e32 v48, v178, v48
	v_exp_f32_e32 v182, v49
	v_sub_f32_e32 v49, v54, v130
	v_add_f32_e32 v48, v179, v48
	v_exp_f32_e32 v183, v49
	v_sub_f32_e32 v49, v55, v130
	v_add_f32_e32 v48, v180, v48
	v_exp_f32_e32 v184, v49
	v_sub_f32_e32 v49, v56, v130
	v_add_f32_e32 v48, v181, v48
	v_exp_f32_e32 v185, v49
	v_sub_f32_e32 v49, v57, v130
	v_add_f32_e32 v48, v182, v48
	v_exp_f32_e32 v186, v49
	v_sub_f32_e32 v49, v58, v130
	v_add_f32_e32 v48, v183, v48
	v_exp_f32_e32 v187, v49
	v_sub_f32_e32 v49, v59, v130
	v_add_f32_e32 v48, v184, v48
	v_exp_f32_e32 v188, v49
	v_sub_f32_e32 v49, v60, v130
	v_add_f32_e32 v48, v185, v48
	v_exp_f32_e32 v189, v49
	v_sub_f32_e32 v49, v61, v130
	v_add_f32_e32 v48, v186, v48
	v_exp_f32_e32 v190, v49
	v_sub_f32_e32 v49, v62, v130
	v_add_f32_e32 v48, v187, v48
	v_exp_f32_e32 v191, v49
	v_sub_f32_e32 v49, v63, v130
	v_add_f32_e32 v48, v188, v48
	v_exp_f32_e32 v192, v49
	v_sub_f32_e32 v32, v32, v130
	v_add_f32_e32 v48, v189, v48
	v_exp_f32_e32 v193, v32
	v_sub_f32_e32 v32, v33, v130
	v_add_f32_e32 v48, v190, v48
	v_exp_f32_e32 v194, v32
	v_sub_f32_e32 v32, v34, v130
	v_add_f32_e32 v48, v191, v48
	v_exp_f32_e32 v195, v32
	v_sub_f32_e32 v33, v35, v130
	v_add_f32_e32 v32, v192, v48
	v_exp_f32_e32 v196, v33
	v_sub_f32_e32 v33, v36, v130
	v_add_f32_e32 v32, v193, v32
	v_exp_f32_e32 v197, v33
	v_sub_f32_e32 v33, v37, v130
	v_add_f32_e32 v32, v194, v32
	v_exp_f32_e32 v198, v33
	v_sub_f32_e32 v33, v38, v130
	v_add_f32_e32 v32, v195, v32
	v_exp_f32_e32 v199, v33
	v_add_f32_e32 v32, v196, v32
	v_add_f32_e32 v32, v197, v32
	v_add_f32_e32 v32, v198, v32
	v_add_f32_e32 v38, v199, v32
	v_sub_f32_e32 v32, v39, v130
	v_cvt_pk_bf16_f32 v34, v112, v113
	v_add_u32_e32 v33, 0x9000, v164
	v_exp_f32_e32 v112, v32
	v_add_u32_e32 v32, 0x9000, v165
	v_cvt_pk_bf16_f32 v35, v114, v115
	v_cvt_pk_bf16_f32 v36, v116, v117
	v_cvt_pk_bf16_f32 v37, v118, v119
	ds_read2_b64 v[48:51], v33 offset1:2
	ds_read2_b64 v[52:55], v32 offset1:2
	v_sub_f32_e32 v39, v40, v130
	v_exp_f32_e32 v113, v39
	s_waitcnt lgkmcnt(1)
	v_mfma_f32_32x32x16_bf16 v[64:79], v[48:51], v[34:37], 0
	v_cvt_pk_bf16_f32 v80, v120, v121
	v_cvt_pk_bf16_f32 v81, v122, v123
	v_cvt_pk_bf16_f32 v82, v124, v125
	v_cvt_pk_bf16_f32 v83, v126, v127
	ds_read2_b64 v[84:87], v33 offset0:4 offset1:6
	v_sub_f32_e32 v16, v16, v130
	v_sub_f32_e32 v17, v17, v130
	s_waitcnt lgkmcnt(1)
	v_mfma_f32_32x32x16_bf16 v[48:63], v[52:55], v[34:37], 0
	v_add_f32_e32 v34, v112, v38
	v_add_f32_e32 v38, v113, v34
	v_sub_f32_e32 v34, v41, v130
	v_exp_f32_e32 v114, v34
	v_sub_f32_e32 v34, v42, v130
	v_exp_f32_e32 v115, v34
	ds_read2_b64 v[34:37], v32 offset0:4 offset1:6
	v_add_f32_e32 v38, v114, v38
	s_waitcnt lgkmcnt(0)
	v_mfma_f32_32x32x16_bf16 v[48:63], v[34:37], v[80:83], v[48:63]
	v_sub_f32_e32 v34, v43, v130
	v_add_f32_e32 v116, v115, v38
	v_cvt_pk_bf16_f32 v38, v96, v97
	v_exp_f32_e32 v96, v34
	v_sub_f32_e32 v34, v44, v130
	v_exp_f32_e32 v97, v34
	v_sub_f32_e32 v34, v45, v130
	v_cvt_pk_bf16_f32 v39, v98, v99
	v_cvt_pk_bf16_f32 v40, v100, v101
	v_cvt_pk_bf16_f32 v41, v102, v103
	v_exp_f32_e32 v98, v34
	ds_read2_b64 v[34:37], v32 offset0:8 offset1:10
	v_mfma_f32_32x32x16_bf16 v[64:79], v[84:87], v[80:83], v[64:79]
	ds_read2_b64 v[84:87], v33 offset0:8 offset1:10
	v_sub_f32_e32 v42, v46, v130
	v_exp_f32_e32 v46, v42
	v_cvt_pk_bf16_f32 v42, v104, v105
	v_cvt_pk_bf16_f32 v43, v106, v107
	v_cvt_pk_bf16_f32 v44, v108, v109
	v_cvt_pk_bf16_f32 v45, v110, v111
	s_waitcnt lgkmcnt(1)
	v_mfma_f32_32x32x16_bf16 v[48:63], v[34:37], v[38:41], v[48:63]
	v_add_f32_e32 v34, v96, v116
	v_add_f32_e32 v34, v97, v34
	ds_read2_b64 v[80:83], v33 offset0:12 offset1:14
	v_add_f32_e32 v34, v98, v34
	v_sub_f32_e32 v0, v0, v130
	v_sub_f32_e32 v1, v1, v130
	s_waitcnt lgkmcnt(1)
	v_mfma_f32_32x32x16_bf16 v[64:79], v[84:87], v[38:41], v[64:79]
	v_add_f32_e32 v84, v46, v34
	v_sub_f32_e32 v34, v47, v130
	v_exp_f32_e32 v47, v34
	ds_read2_b64 v[34:37], v32 offset0:12 offset1:14
	v_cvt_pk_bf16_f32 v38, v132, v133
	v_cvt_pk_bf16_f32 v39, v134, v131
	v_cvt_pk_bf16_f32 v40, v135, v136
	s_waitcnt lgkmcnt(1)
	v_mfma_f32_32x32x16_bf16 v[64:79], v[80:83], v[42:45], v[64:79]
	v_cvt_pk_bf16_f32 v41, v137, v138
	ds_read2_b64 v[80:83], v33 offset0:16 offset1:18
	v_exp_f32_e32 v85, v16
	v_add_f32_e32 v16, v47, v84
	v_exp_f32_e32 v84, v17
	v_sub_f32_e32 v17, v18, v130
	v_exp_f32_e32 v86, v17
	s_waitcnt lgkmcnt(1)
	v_mfma_f32_32x32x16_bf16 v[48:63], v[34:37], v[42:45], v[48:63]
	ds_read2_b64 v[34:37], v32 offset0:16 offset1:18
	v_add_f32_e32 v16, v85, v16
	v_add_f32_e32 v16, v84, v16
	v_add_f32_e32 v87, v86, v16
	v_sub_f32_e32 v16, v19, v130
	v_cvt_pk_bf16_f32 v42, v88, v89
	v_exp_f32_e32 v88, v16
	v_sub_f32_e32 v16, v20, v130
	s_waitcnt lgkmcnt(1)
	v_mfma_f32_32x32x16_bf16 v[64:79], v[80:83], v[38:41], v[64:79]
	v_cvt_pk_bf16_f32 v43, v90, v91
	v_cvt_pk_bf16_f32 v44, v92, v93
	v_cvt_pk_bf16_f32 v45, v94, v95
	ds_read2_b64 v[80:83], v33 offset0:20 offset1:22
	v_exp_f32_e32 v89, v16
	v_sub_f32_e32 v16, v21, v130
	v_exp_f32_e32 v90, v16
	ds_read2_b64 v[16:19], v32 offset0:20 offset1:22
	s_waitcnt lgkmcnt(2)
	v_mfma_f32_32x32x16_bf16 v[48:63], v[34:37], v[38:41], v[48:63]
	v_sub_f32_e32 v20, v22, v130
	v_cvt_pk_bf16_f32 v34, v139, v147
	v_cvt_pk_bf16_f32 v35, v149, v151
	v_cvt_pk_bf16_f32 v36, v153, v166
	v_cvt_pk_bf16_f32 v37, v167, v168
	ds_read2_b64 v[38:41], v33 offset0:24 offset1:26
	v_mov_b32_e32 v147, v141
	s_waitcnt lgkmcnt(2)
	v_mfma_f32_32x32x16_bf16 v[64:79], v[80:83], v[42:45], v[64:79]
	v_exp_f32_e32 v80, v20
	v_sub_f32_e32 v20, v24, v130
	v_mov_b32_e32 v149, v141
	v_mov_b32_e32 v151, v141
	v_mov_b32_e32 v153, v141
	s_waitcnt lgkmcnt(1)
	v_mfma_f32_32x32x16_bf16 v[48:63], v[16:19], v[42:45], v[48:63]
	v_add_f32_e32 v16, v88, v87
	v_add_f32_e32 v16, v89, v16
	v_add_f32_e32 v16, v90, v16
	v_add_f32_e32 v42, v80, v16
	v_sub_f32_e32 v16, v23, v130
	v_exp_f32_e32 v43, v16
	ds_read2_b64 v[16:19], v32 offset0:24 offset1:26
	v_exp_f32_e32 v44, v20
	s_waitcnt lgkmcnt(0)
	v_mfma_f32_32x32x16_bf16 v[48:63], v[16:19], v[34:37], v[48:63]
	v_add_f32_e32 v16, v43, v42
	v_add_f32_e32 v24, v44, v16
	v_sub_f32_e32 v16, v25, v130
	v_exp_f32_e32 v42, v16
	v_sub_f32_e32 v16, v26, v130
	v_cvt_pk_bf16_f32 v20, v169, v170
	v_cvt_pk_bf16_f32 v21, v171, v172
	v_cvt_pk_bf16_f32 v22, v173, v174
	v_cvt_pk_bf16_f32 v23, v175, v176
	v_exp_f32_e32 v45, v16
	ds_read2_b64 v[16:19], v32 offset0:28 offset1:30
	v_mfma_f32_32x32x16_bf16 v[64:79], v[38:41], v[34:37], v[64:79]
	ds_read2_b64 v[38:41], v33 offset0:28 offset1:30
	v_cvt_pk_bf16_f32 v34, v177, v178
	v_cvt_pk_bf16_f32 v35, v179, v180
	v_cvt_pk_bf16_f32 v36, v181, v182
	v_cvt_pk_bf16_f32 v37, v183, v184
	v_add_f32_e32 v24, v42, v24
	v_add_f32_e32 v81, v45, v24
	s_waitcnt lgkmcnt(1)
	v_mfma_f32_32x32x16_bf16 v[48:63], v[16:19], v[20:23], v[48:63]
	v_sub_f32_e32 v16, v27, v130
	v_exp_f32_e32 v82, v16
	v_sub_f32_e32 v16, v28, v130
	v_exp_f32_e32 v83, v16
	v_sub_f32_e32 v16, v29, v130
	v_exp_f32_e32 v87, v16
	ds_read2_b64 v[16:19], v32 offset0:32 offset1:34
	s_waitcnt lgkmcnt(1)
	v_mfma_f32_32x32x16_bf16 v[64:79], v[38:41], v[20:23], v[64:79]
	ds_read2_b64 v[38:41], v33 offset0:32 offset1:34
	v_sub_f32_e32 v20, v30, v130
	s_waitcnt lgkmcnt(0)
	v_mfma_f32_32x32x16_bf16 v[64:79], v[38:41], v[34:37], v[64:79]
	v_exp_f32_e32 v38, v20
	v_cvt_pk_bf16_f32 v20, v185, v186
	v_cvt_pk_bf16_f32 v21, v187, v188
	v_cvt_pk_bf16_f32 v22, v189, v190
	v_cvt_pk_bf16_f32 v23, v191, v192
	ds_read2_b64 v[24:27], v33 offset0:36 offset1:38
	v_mfma_f32_32x32x16_bf16 v[48:63], v[16:19], v[34:37], v[48:63]
	v_add_f32_e32 v16, v82, v81
	v_add_f32_e32 v16, v83, v16
	v_add_f32_e32 v16, v87, v16
	v_add_f32_e32 v34, v38, v16
	v_sub_f32_e32 v16, v31, v130
	v_exp_f32_e32 v35, v16
	ds_read2_b64 v[16:19], v32 offset0:36 offset1:38
	s_waitcnt lgkmcnt(1)
	v_mfma_f32_32x32x16_bf16 v[64:79], v[24:27], v[20:23], v[64:79]
	v_cvt_pk_bf16_f32 v24, v193, v194
	v_cvt_pk_bf16_f32 v25, v195, v196
	v_cvt_pk_bf16_f32 v26, v197, v198
	v_cvt_pk_bf16_f32 v27, v199, v112
	ds_read2_b64 v[28:31], v33 offset0:40 offset1:42
	v_exp_f32_e32 v36, v0
	v_add_f32_e32 v0, v35, v34
	s_waitcnt lgkmcnt(1)
	v_mfma_f32_32x32x16_bf16 v[48:63], v[16:19], v[20:23], v[48:63]
	v_exp_f32_e32 v34, v1
	v_sub_f32_e32 v1, v2, v130
	ds_read2_b64 v[16:19], v32 offset0:40 offset1:42
	v_exp_f32_e32 v37, v1
	v_add_f32_e32 v0, v36, v0
	v_add_f32_e32 v0, v34, v0
	v_cvt_pk_bf16_f32 v20, v113, v114
	v_add_f32_e32 v39, v37, v0
	v_sub_f32_e32 v0, v3, v130
	v_exp_f32_e32 v40, v0
	v_sub_f32_e32 v0, v4, v130
	s_waitcnt lgkmcnt(1)
	v_mfma_f32_32x32x16_bf16 v[64:79], v[28:31], v[24:27], v[64:79]
	v_cvt_pk_bf16_f32 v21, v115, v96
	v_cvt_pk_bf16_f32 v22, v97, v98
	v_cvt_pk_bf16_f32 v23, v46, v47
	ds_read2_b64 v[28:31], v33 offset0:44 offset1:46
	v_exp_f32_e32 v41, v0
	v_sub_f32_e32 v0, v5, v130
	v_exp_f32_e32 v46, v0
	ds_read2_b64 v[0:3], v32 offset0:44 offset1:46
	s_waitcnt lgkmcnt(2)
	v_mfma_f32_32x32x16_bf16 v[48:63], v[16:19], v[24:27], v[48:63]
	v_sub_f32_e32 v4, v6, v130
	v_cvt_pk_bf16_f32 v16, v85, v84
	v_cvt_pk_bf16_f32 v17, v86, v88
	v_cvt_pk_bf16_f32 v18, v89, v90
	v_cvt_pk_bf16_f32 v19, v80, v43
	ds_read2_b64 v[24:27], v33 offset0:48 offset1:50
	s_waitcnt lgkmcnt(2)
	v_mfma_f32_32x32x16_bf16 v[64:79], v[28:31], v[20:23], v[64:79]
	v_exp_f32_e32 v28, v4
	v_sub_f32_e32 v4, v8, v130
	v_sub_f32_e32 v8, v11, v130
	s_waitcnt lgkmcnt(1)
	v_mfma_f32_32x32x16_bf16 v[48:63], v[0:3], v[20:23], v[48:63]
	v_add_f32_e32 v0, v40, v39
	v_add_f32_e32 v0, v41, v0
	v_add_f32_e32 v0, v46, v0
	v_add_f32_e32 v29, v28, v0
	v_sub_f32_e32 v0, v7, v130
	v_exp_f32_e32 v30, v0
	ds_read2_b64 v[0:3], v32 offset0:48 offset1:50
	s_waitcnt lgkmcnt(1)
	v_mfma_f32_32x32x16_bf16 v[64:79], v[24:27], v[16:19], v[64:79]
	v_exp_f32_e32 v24, v4
	v_cvt_pk_bf16_f32 v4, v44, v42
	v_cvt_pk_bf16_f32 v5, v45, v82
	v_cvt_pk_bf16_f32 v6, v83, v87
	v_cvt_pk_bf16_f32 v7, v38, v35
	ds_read2_b64 v[20:23], v33 offset0:52 offset1:54
	s_waitcnt lgkmcnt(1)
	v_mfma_f32_32x32x16_bf16 v[48:63], v[0:3], v[16:19], v[48:63]
	v_add_f32_e32 v0, v30, v29
	v_add_f32_e32 v25, v24, v0
	v_sub_f32_e32 v0, v9, v130
	v_exp_f32_e32 v26, v0
	v_sub_f32_e32 v0, v10, v130
	v_exp_f32_e32 v27, v0
	ds_read2_b64 v[0:3], v32 offset0:52 offset1:54
	s_waitcnt lgkmcnt(0)
	v_mfma_f32_32x32x16_bf16 v[48:63], v[0:3], v[4:7], v[48:63]
	v_sub_f32_e32 v0, v12, v130
	v_mfma_f32_32x32x16_bf16 v[64:79], v[20:23], v[4:7], v[64:79]
	v_exp_f32_e32 v21, v0
	v_sub_f32_e32 v0, v13, v130
	v_exp_f32_e32 v22, v0
	v_sub_f32_e32 v0, v14, v130
	v_exp_f32_e32 v20, v8
	v_cvt_pk_bf16_f32 v8, v36, v34
	v_cvt_pk_bf16_f32 v9, v37, v40
	v_cvt_pk_bf16_f32 v10, v41, v46
	v_cvt_pk_bf16_f32 v11, v28, v30
	v_exp_f32_e32 v23, v0
	ds_read2_b64 v[0:3], v32 offset0:56 offset1:58
	ds_read2_b64 v[16:19], v33 offset0:56 offset1:58
	s_waitcnt lgkmcnt(1)
	v_mfma_f32_32x32x16_bf16 v[48:63], v[0:3], v[8:11], v[48:63]
	v_add_f32_e32 v0, v26, v25
	v_add_f32_e32 v0, v27, v0
	v_add_f32_e32 v0, v20, v0
	v_add_f32_e32 v0, v21, v0
	v_sub_f32_e32 v4, v15, v130
	v_add_f32_e32 v0, v22, v0
	s_waitcnt lgkmcnt(0)
	v_mfma_f32_32x32x16_bf16 v[64:79], v[16:19], v[8:11], v[64:79]
	v_exp_f32_e32 v16, v4
	v_cvt_pk_bf16_f32 v4, v24, v26
	v_cvt_pk_bf16_f32 v5, v27, v20
	v_cvt_pk_bf16_f32 v6, v21, v22
	v_cvt_pk_bf16_f32 v7, v23, v16
	v_add_f32_e32 v8, v23, v0
	ds_read2_b64 v[0:3], v32 offset0:60 offset1:62
	ds_read2_b64 v[12:15], v33 offset0:60 offset1:62
	s_waitcnt lgkmcnt(1)
	v_mfma_f32_32x32x16_bf16 v[48:63], v[0:3], v[4:7], v[48:63]
	v_lshl_add_u64 v[0:1], v[128:129], 0, v[146:147]
	v_add_f32_e32 v10, v16, v8
	ds_bpermute_b32 v11, v155, v10
	v_lshl_add_u64 v[8:9], s[16:17], 0, v[140:141]
	v_lshl_add_u64 v[8:9], v[8:9], 0, s[4:5]
	s_waitcnt lgkmcnt(0)
	v_add_f32_e32 v10, v10, v11
	v_mfma_f32_32x32x16_bf16 v[64:79], v[12:15], v[4:7], v[64:79]
	v_lshl_add_u64 v[4:5], v[0:1], 0, v[148:149]
	global_load_dwordx4 v[0:3], v[4:5], off nt
	global_load_dwordx4 v[136:139], v[4:5], off offset:32 nt
	global_load_dwordx4 v[132:135], v[4:5], off offset:64 nt
	global_load_dwordx4 v[128:131], v[4:5], off offset:96 nt
	v_div_scale_f32 v6, s[16:17], v10, v10, 1.0
	v_rcp_f32_e32 v7, v6
	s_nop 0
	v_fma_f32 v4, -v6, v7, 1.0
	v_fmac_f32_e32 v7, v4, v7
	v_div_scale_f32 v4, vcc, 1.0, v10, 1.0
	v_mul_f32_e32 v5, v4, v7
	v_fma_f32 v11, -v6, v5, v4
	v_fmac_f32_e32 v5, v11, v7
	v_fma_f32 v4, -v6, v5, v4
	v_div_fmas_f32 v4, v4, v7, v5
	v_div_fixup_f32 v10, v4, v10, 1.0
	v_lshl_add_u64 v[4:5], v[8:9], 0, v[150:151]
	v_lshl_add_u64 v[4:5], v[4:5], 0, v[152:153]
	v_lshl_add_u64 v[6:7], v[4:5], 0, s[12:13]
	v_mul_f32_e32 v8, v64, v10
	v_mul_f32_e32 v9, v65, v10
	v_add_co_u32_e32 v4, vcc, s25, v4
	v_cvt_pk_bf16_f32 v8, v8, v9
	v_mul_f32_e32 v9, v66, v10
	s_nop 0
	v_addc_co_u32_e32 v5, vcc, 0, v5, vcc
	v_mul_f32_e32 v11, v67, v10
	v_cvt_pk_bf16_f32 v9, v9, v11
	global_store_dwordx2 v[4:5], v[8:9], off offset:1536 sc1
	v_mul_f32_e32 v4, v68, v10
	v_mul_f32_e32 v5, v69, v10
	v_cvt_pk_bf16_f32 v4, v4, v5
	v_mul_f32_e32 v5, v70, v10
	v_mul_f32_e32 v8, v71, v10
	v_cvt_pk_bf16_f32 v5, v5, v8
	global_store_dwordx2 v[6:7], v[4:5], off offset:16 sc1
	v_mul_f32_e32 v4, v72, v10
	v_mul_f32_e32 v5, v73, v10
	v_cvt_pk_bf16_f32 v4, v4, v5
	v_mul_f32_e32 v5, v74, v10
	v_mul_f32_e32 v8, v75, v10
	v_cvt_pk_bf16_f32 v5, v5, v8
	global_store_dwordx2 v[6:7], v[4:5], off offset:32 sc1
	v_mul_f32_e32 v4, v76, v10
	v_mul_f32_e32 v5, v77, v10
	v_cvt_pk_bf16_f32 v4, v4, v5
	v_mul_f32_e32 v5, v78, v10
	v_mul_f32_e32 v8, v79, v10
	v_cvt_pk_bf16_f32 v5, v5, v8
	global_store_dwordx2 v[6:7], v[4:5], off offset:48 sc1
	v_mul_f32_e32 v4, v48, v10
	v_mul_f32_e32 v5, v49, v10
	v_cvt_pk_bf16_f32 v4, v4, v5
	v_mul_f32_e32 v5, v50, v10
	v_mul_f32_e32 v8, v51, v10
	v_cvt_pk_bf16_f32 v5, v5, v8
	global_store_dwordx2 v[6:7], v[4:5], off offset:64 sc1
	v_mul_f32_e32 v4, v52, v10
	v_mul_f32_e32 v5, v53, v10
	v_cvt_pk_bf16_f32 v4, v4, v5
	v_mul_f32_e32 v5, v54, v10
	v_mul_f32_e32 v8, v55, v10
	v_cvt_pk_bf16_f32 v5, v5, v8
	global_store_dwordx2 v[6:7], v[4:5], off offset:80 sc1
	v_mul_f32_e32 v4, v56, v10
	v_mul_f32_e32 v5, v57, v10
	v_cvt_pk_bf16_f32 v4, v4, v5
	v_mul_f32_e32 v5, v58, v10
	v_mul_f32_e32 v8, v59, v10
	v_cvt_pk_bf16_f32 v5, v5, v8
	global_store_dwordx2 v[6:7], v[4:5], off offset:96 sc1
	v_mul_f32_e32 v4, v60, v10
	v_mul_f32_e32 v5, v61, v10
	v_cvt_pk_bf16_f32 v4, v4, v5
	v_mul_f32_e32 v5, v62, v10
	s_and_b64 vcc, s[14:15], exec
	v_mul_f32_e32 v8, v63, v10
	v_cvt_pk_bf16_f32 v5, v5, v8
	global_store_dwordx2 v[6:7], v[4:5], off offset:112 sc1
	s_barrier
	s_cbranch_vccnz .LBB0_490
